# branch gates stored as bf16 logits by the input projection; sigmoid evaluated inside the up-projection epilogue (hidden under its load-issue time) instead of the VALU-bound input-projection epilogue
# speedup vs baseline: 1.0118x; 1.0118x over previous
;     DI void operator()(Acc& acc, const Unit& u, int wr, int wc, int fr, int fq) const {
;     ...
;             for (int m = 0; m < 4; ++m) { const int row = u.pm * 256 + ai * 128 + wr * 64 + m * 16 + fr;
;                 bf16_t* prow = proj + (size_t)row * NPJ + pn * 256 + wc * 32 + fq * 8;
; #pragma unroll
;                 for (int bj = 0; bj < 2; ++bj) { f32x4 v0 = acc[ai][bj][m][0], v1 = acc[ai][bj][m][1];
;                     if (pn == 2) {
;                         const int kvh = wc >> 1, d = (wc & 1) * 32 + fq * 8;
;                         float* o = nullptr;
;                         if (row >= MP) { const int bs = (row - MP) >> 3, t = (row - MP) & 7; o = out + (bj ? O_VWS : O_KWS) + ((size_t)(bs * 128 + 120 + t) * 2 + kvh) * 64 + d; }
;                         else { const int t = row & 4095; if (t >= 3968) o = out + (bj ? O_VWP : O_KWP) + ((size_t)((row >> 12) * 128 + t - 3968) * 2 + kvh) * 64 + d; }
;                         if (o) { *(f32x4*)o = v0; *(f32x4*)(o + 4) = v1; }
;                         if (row < MP) { const int tt = row & 4095, bk = ((row >> 12) * 2 + kvh);
;                             if (bj == 0) *(u32x4*)(ksw + ((((((size_t)bk * 128 + (tt >> 5)) * 4 + (d >> 4)) * 2 + ((d >> 3) & 1)) * 32 + (tt & 31)) * 8)) = pack8(v0, v1);
;                             else { const int w16 = tt & 15; bf16_t* t = vtsw + (((((size_t)bk * 256 + (tt >> 4)) * 2 + ((w16 >> 2) & 1)) * 64 + d) * 8) + (w16 & 3) + 4 * (w16 >> 3);
; #pragma unroll
;                                 for (int j = 0; j < 4; ++j) { t[j * 8] = f2bf(v0[j]); t[(4 + j) * 8] = f2bf(v1[j]); } } }
;                         continue;
;                     }
;                     if (pn < 2) { v0 *= 0.125f * LOG2E; v1 *= 0.125f * LOG2E; }
;                     else if (pn < 5 || (pn >= 9 && pn < 11)) {
; #pragma unroll
;                         for (int j = 0; j < 4; ++j) { v0[j] = fsilu(v0[j]); v1[j] = fsilu(v1[j]); } }
;                     else if (pn < 7) { const f32x4 l0 = lbv[bj][0], l1 = lbv[bj][1];
; #pragma unroll
;                         for (int j = 0; j < 4; ++j) { v0[j] = flog(l0[j] + (1.0f - l0[j]) * fsigmoid(v0[j])); v1[j] = flog(l1[j] + (1.0f - l1[j]) * fsigmoid(v1[j])); } }
;                     else if (pn < 9) {}
;                     else if (pn < 13) { v0 *= 0.08838834764831845f * LOG2E; v1 *= 0.08838834764831845f * LOG2E; }
;                     else {
.LBB0_122:
	s_mov_b64 s[4:5], -1
	s_cmpk_gt_i32 s96, 0x83
	v_lshlrev_b32_e32 v193, 5, v154
	v_and_b32_e32 v194, 31, v192
	s_cbranch_scc1 .LBB0_639
	s_lshl_b32 s4, s96, 8
	s_lshl_b32 s54, s94, 8
	s_add_i32 s4, s4, s23
	s_ashr_i32 s55, s54, 31
	s_cmp_lg_u32 s94, 2
	v_add_u32_e32 v200, s4, v192
	s_cselect_b64 s[4:5], -1, 0
	s_cmp_gt_i32 s94, 1
	s_cselect_b64 s[40:41], -1, 0
	s_cmp_gt_u32 s94, 6
	s_cselect_b64 s[52:53], -1, 0
	s_cmp_gt_u32 s94, 8
	v_mov_b64_e32 v[162:163], s[48:49]
	s_cselect_b64 s[18:19], -1, 0
	s_cmp_gt_u32 s94, 12
	v_mad_i64_i32 v[162:163], s[6:7], v200, s50, v[162:163]
	s_cselect_b64 s[16:17], -1, 0
	s_andn2_b64 s[18:19], s[18:19], s[16:17]
	v_lshl_add_u64 v[162:163], s[54:55], 1, v[162:163]
	s_lshl_b32 s28, s33, 1
	v_ashrrev_i32_e32 v161, 31, v160
	v_lshl_add_u64 v[162:163], v[162:163], 0, s[28:29]
	v_and_b32_e32 v154, 0xfff, v200
	v_lshl_add_u64 v[164:165], v[160:161], 1, v[162:163]
	v_cmp_gt_i32_e64 s[8:9], s14, v200
	v_cmp_lt_u32_e64 s[10:11], s51, v154
	s_mov_b64 s[6:7], -1
	s_and_b64 vcc, exec, s[4:5]
	s_cbranch_vccz .LBB0_136
	s_and_b64 vcc, exec, s[40:41]
	s_cbranch_vccz .LBB0_133
	s_cmp_lt_i32 s94, 9
	s_cbranch_scc1 .LBB0_127
	s_cmp_gt_i32 s94, 10
	s_cselect_b64 s[78:79], -1, 0
	s_cbranch_execz .LBB0_128
	s_branch .LBB0_129

; DI float bflo(unsigned w) { return __uint_as_float(w << 16); }
; DI float bfhi(unsigned w) { return __uint_as_float(w & 0xffff0000u); }
; DI float fexp(float x) { return __builtin_amdgcn_exp2f(x * LOG2E); }
; DI float frcp(float x) { return __builtin_amdgcn_rcpf(x); }
; DI float fsigmoid(float x) { return frcp(1.0f + fexp(-x)); }
;     DI void operator()(Acc& acc, const Unit& u, int wr, int wc, int fr, int fq) const {
;     ...
;                     for (int bj = 0; bj < 2; ++bj) g[ai][m][bj] = *(const u32x4*)(base + (size_t)(ai * 128 + m * 16) * NPJ + u.k * 1024 + bj * 128);
; #pragma unroll
;             for (int ai = 0; ai < 2; ++ai)
; #pragma unroll
;                 for (int m = 0; m < 4; ++m)
; #pragma unroll
;                     for (int bj = 0; bj < 2; ++bj) { const u32x4 q = g[ai][m][bj]; f32x4& v0 = acc[ai][bj][m][0]; f32x4& v1 = acc[ai][bj][m][1];
;                         v0[0] *= bflo(q.x); v0[1] *= bfhi(q.x); v0[2] *= bflo(q.y); v0[3] *= bfhi(q.y); v1[0] *= bflo(q.z); v1[1] *= bfhi(q.z); v1[2] *= bflo(q.w); v1[3] *= bfhi(q.w); }
.LBB0_948:
	v_mov_b32_e32 v130, v1
	v_mov_b32_e32 v132, v172
	s_lshl_b32 s8, s30, 1
	v_add_u32_e32 v133, s39, v130
	v_mov_b64_e32 v[130:131], s[48:49]
	v_mad_i64_i32 v[130:131], s[24:25], v133, s41, v[130:131]
	v_lshl_add_u64 v[130:131], v[130:131], 0, s[8:9]
	s_mov_b32 s17, s9
	v_lshlrev_b32_e32 v132, 3, v132
	v_lshl_add_u64 v[130:131], v[130:131], 0, s[16:17]
	v_ashrrev_i32_e32 v133, 31, v132
	v_lshl_add_u64 v[130:131], v[132:133], 1, v[130:131]
	v_lshl_add_u64 v[166:167], v[130:131], 0, s[18:19]
	s_lshl_b32 s8, s84, 10
	v_lshl_add_u64 v[130:131], s[8:9], 1, v[166:167]
	s_mov_b32 s101, 0
	s_mov_b32 s100, 0x32000
	v_lshl_add_u64 v[132:133], v[130:131], 0, s[100:101]
	s_mov_b32 s100, 0x64000
	v_lshl_add_u64 v[134:135], v[130:131], 0, s[100:101]
	s_mov_b32 s100, 0x96000
	v_lshl_add_u64 v[136:137], v[130:131], 0, s[100:101]
	s_mov_b32 s100, 0x190000
	v_lshl_add_u64 v[138:139], v[130:131], 0, s[100:101]
	s_mov_b32 s100, 0x1c2000
	v_lshl_add_u64 v[140:141], v[130:131], 0, s[100:101]
	s_mov_b32 s100, 0x1f4000
	v_lshl_add_u64 v[142:143], v[130:131], 0, s[100:101]
	s_mov_b32 s100, 0x226000
	v_lshl_add_u64 v[144:145], v[130:131], 0, s[100:101]
	s_mov_b32 s100, 0xbfb8aa3b
	s_cmp_eq_u32 s84, 2
	s_cbranch_scc1 .Lup3_final
	global_load_dwordx4 v[184:187], v[130:131], off
	global_load_dwordx4 v[188:191], v[130:131], off offset:256
	global_load_dwordx4 v[192:195], v[130:131], off offset:2048
	global_load_dwordx4 v[196:199], v[130:131], off offset:2304
	global_load_dwordx4 v[200:203], v[132:133], off
	global_load_dwordx4 v[204:207], v[132:133], off offset:256
	global_load_dwordx4 v[208:211], v[132:133], off offset:2048
	global_load_dwordx4 v[212:215], v[132:133], off offset:2304
	global_load_dwordx4 v[216:219], v[134:135], off
	global_load_dwordx4 v[220:223], v[134:135], off offset:256
	global_load_dwordx4 v[224:227], v[134:135], off offset:2048
	global_load_dwordx4 v[228:231], v[134:135], off offset:2304
	s_waitcnt vmcnt(8)
	v_lshlrev_b32_e32 v146, 16, v184
	v_and_b32_e32 v147, 0xffff0000, v184
	v_lshlrev_b32_e32 v148, 16, v192
	v_and_b32_e32 v149, 0xffff0000, v192
	v_lshlrev_b32_e32 v150, 16, v185
	v_and_b32_e32 v151, 0xffff0000, v185
	v_lshlrev_b32_e32 v152, 16, v193
	v_and_b32_e32 v153, 0xffff0000, v193
	v_pk_mul_f32 v[146:147], v[146:147], s[100:101] op_sel_hi:[1,0]
	v_pk_mul_f32 v[148:149], v[148:149], s[100:101] op_sel_hi:[1,0]
	v_pk_mul_f32 v[150:151], v[150:151], s[100:101] op_sel_hi:[1,0]
	v_pk_mul_f32 v[152:153], v[152:153], s[100:101] op_sel_hi:[1,0]
	v_min_f32_e32 v146, 0x42b80000, v146
	v_min_f32_e32 v147, 0x42b80000, v147
	v_min_f32_e32 v148, 0x42b80000, v148
	v_min_f32_e32 v149, 0x42b80000, v149
	v_min_f32_e32 v150, 0x42b80000, v150
	v_min_f32_e32 v151, 0x42b80000, v151
	v_min_f32_e32 v152, 0x42b80000, v152
	v_min_f32_e32 v153, 0x42b80000, v153
	v_exp_f32_e32 v146, v146
	v_exp_f32_e32 v147, v147
	v_exp_f32_e32 v148, v148
	v_exp_f32_e32 v149, v149
	v_exp_f32_e32 v150, v150
	v_exp_f32_e32 v151, v151
	v_exp_f32_e32 v152, v152
	v_exp_f32_e32 v153, v153
	s_nop 0
	v_add_f32_e32 v146, 1.0, v146
	v_add_f32_e32 v147, 1.0, v147
	v_add_f32_e32 v148, 1.0, v148
	v_add_f32_e32 v149, 1.0, v149
	v_add_f32_e32 v150, 1.0, v150
	v_add_f32_e32 v151, 1.0, v151
	v_add_f32_e32 v152, 1.0, v152
	v_add_f32_e32 v153, 1.0, v153
	v_rcp_f32_e32 v146, v146
	v_rcp_f32_e32 v147, v147
	v_rcp_f32_e32 v150, v150
	v_rcp_f32_e32 v151, v151
	s_nop 0
	v_pk_mul_f32 v[146:147], v[146:147], v[148:149]
	v_pk_mul_f32 v[150:151], v[150:151], v[152:153]
	v_pk_mul_f32 v[126:127], v[126:127], v[146:147]
	v_pk_mul_f32 v[128:129], v[128:129], v[150:151]
	v_lshlrev_b32_e32 v168, 16, v186
	v_and_b32_e32 v169, 0xffff0000, v186
	v_lshlrev_b32_e32 v178, 16, v194
	v_and_b32_e32 v179, 0xffff0000, v194
	v_lshlrev_b32_e32 v180, 16, v187
	v_and_b32_e32 v181, 0xffff0000, v187
	v_lshlrev_b32_e32 v244, 16, v195
	v_and_b32_e32 v245, 0xffff0000, v195
	v_pk_mul_f32 v[168:169], v[168:169], s[100:101] op_sel_hi:[1,0]
	v_pk_mul_f32 v[178:179], v[178:179], s[100:101] op_sel_hi:[1,0]
	v_pk_mul_f32 v[180:181], v[180:181], s[100:101] op_sel_hi:[1,0]
	v_pk_mul_f32 v[244:245], v[244:245], s[100:101] op_sel_hi:[1,0]
	v_min_f32_e32 v168, 0x42b80000, v168
	v_min_f32_e32 v169, 0x42b80000, v169
	v_min_f32_e32 v178, 0x42b80000, v178
	v_min_f32_e32 v179, 0x42b80000, v179
	v_min_f32_e32 v180, 0x42b80000, v180
	v_min_f32_e32 v181, 0x42b80000, v181
	v_min_f32_e32 v244, 0x42b80000, v244
	v_min_f32_e32 v245, 0x42b80000, v245
	v_exp_f32_e32 v168, v168
	v_exp_f32_e32 v169, v169
	v_exp_f32_e32 v178, v178
	v_exp_f32_e32 v179, v179
	v_exp_f32_e32 v180, v180
	v_exp_f32_e32 v181, v181
	v_exp_f32_e32 v244, v244
	v_exp_f32_e32 v245, v245
	s_nop 0
	v_add_f32_e32 v168, 1.0, v168
	v_add_f32_e32 v169, 1.0, v169
	v_add_f32_e32 v178, 1.0, v178
	v_add_f32_e32 v179, 1.0, v179
	v_add_f32_e32 v180, 1.0, v180
	v_add_f32_e32 v181, 1.0, v181
	v_add_f32_e32 v244, 1.0, v244
	v_add_f32_e32 v245, 1.0, v245
	v_rcp_f32_e32 v168, v168
	v_rcp_f32_e32 v169, v169
	v_rcp_f32_e32 v180, v180
	v_rcp_f32_e32 v181, v181
	s_nop 0
	v_pk_mul_f32 v[168:169], v[168:169], v[178:179]
	v_pk_mul_f32 v[180:181], v[180:181], v[244:245]
	v_pk_mul_f32 v[122:123], v[122:123], v[168:169]
	v_pk_mul_f32 v[124:125], v[124:125], v[180:181]
	v_lshlrev_b32_e32 v168, 16, v188
	v_and_b32_e32 v169, 0xffff0000, v188
	v_lshlrev_b32_e32 v178, 16, v196
	v_and_b32_e32 v179, 0xffff0000, v196
	v_lshlrev_b32_e32 v180, 16, v189
	v_and_b32_e32 v181, 0xffff0000, v189
	v_lshlrev_b32_e32 v244, 16, v197
	v_and_b32_e32 v245, 0xffff0000, v197
	v_pk_mul_f32 v[168:169], v[168:169], s[100:101] op_sel_hi:[1,0]
	v_pk_mul_f32 v[178:179], v[178:179], s[100:101] op_sel_hi:[1,0]
; DI float bflo(unsigned w) { return __uint_as_float(w << 16); }
; DI float bfhi(unsigned w) { return __uint_as_float(w & 0xffff0000u); }
; DI float fexp(float x) { return __builtin_amdgcn_exp2f(x * LOG2E); }
; DI float frcp(float x) { return __builtin_amdgcn_rcpf(x); }
; DI float fsigmoid(float x) { return frcp(1.0f + fexp(-x)); }
;     DI void operator()(Acc& acc, const Unit& u, int wr, int wc, int fr, int fq) const {
;     ...
;                     for (int bj = 0; bj < 2; ++bj) g[ai][m][bj] = *(const u32x4*)(base + (size_t)(ai * 128 + m * 16) * NPJ + u.k * 1024 + bj * 128);
; #pragma unroll
;             for (int ai = 0; ai < 2; ++ai)
; #pragma unroll
;                 for (int m = 0; m < 4; ++m)
; #pragma unroll
;                     for (int bj = 0; bj < 2; ++bj) { const u32x4 q = g[ai][m][bj]; f32x4& v0 = acc[ai][bj][m][0]; f32x4& v1 = acc[ai][bj][m][1];
;                         v0[0] *= bflo(q.x); v0[1] *= bfhi(q.x); v0[2] *= bflo(q.y); v0[3] *= bfhi(q.y); v1[0] *= bflo(q.z); v1[1] *= bfhi(q.z); v1[2] *= bflo(q.w); v1[3] *= bfhi(q.w); }
	v_pk_mul_f32 v[180:181], v[180:181], s[100:101] op_sel_hi:[1,0]
	v_pk_mul_f32 v[244:245], v[244:245], s[100:101] op_sel_hi:[1,0]
	v_min_f32_e32 v168, 0x42b80000, v168
	v_min_f32_e32 v169, 0x42b80000, v169
	v_min_f32_e32 v178, 0x42b80000, v178
	v_min_f32_e32 v179, 0x42b80000, v179
	v_min_f32_e32 v180, 0x42b80000, v180
	v_min_f32_e32 v181, 0x42b80000, v181
	v_min_f32_e32 v244, 0x42b80000, v244
	v_min_f32_e32 v245, 0x42b80000, v245
	v_exp_f32_e32 v168, v168
	v_exp_f32_e32 v169, v169
	v_exp_f32_e32 v178, v178
	v_exp_f32_e32 v179, v179
	v_exp_f32_e32 v180, v180
	v_exp_f32_e32 v181, v181
	v_exp_f32_e32 v244, v244
	v_exp_f32_e32 v245, v245
	s_nop 0
	v_add_f32_e32 v168, 1.0, v168
	v_add_f32_e32 v169, 1.0, v169
	v_add_f32_e32 v178, 1.0, v178
	v_add_f32_e32 v179, 1.0, v179
	v_add_f32_e32 v180, 1.0, v180
	v_add_f32_e32 v181, 1.0, v181
	v_add_f32_e32 v244, 1.0, v244
	v_add_f32_e32 v245, 1.0, v245
	v_rcp_f32_e32 v168, v168
	v_rcp_f32_e32 v169, v169
	v_rcp_f32_e32 v180, v180
	v_rcp_f32_e32 v181, v181
	s_nop 0
	v_pk_mul_f32 v[168:169], v[168:169], v[178:179]
	v_pk_mul_f32 v[180:181], v[180:181], v[244:245]
	v_pk_mul_f32 v[114:115], v[114:115], v[168:169]
	v_pk_mul_f32 v[116:117], v[116:117], v[180:181]
	v_lshlrev_b32_e32 v146, 16, v190
	v_and_b32_e32 v147, 0xffff0000, v190
	v_lshlrev_b32_e32 v148, 16, v198
	v_and_b32_e32 v149, 0xffff0000, v198
	v_lshlrev_b32_e32 v150, 16, v191
	v_and_b32_e32 v151, 0xffff0000, v191
	v_lshlrev_b32_e32 v152, 16, v199
	v_and_b32_e32 v153, 0xffff0000, v199
	v_pk_mul_f32 v[146:147], v[146:147], s[100:101] op_sel_hi:[1,0]
	v_pk_mul_f32 v[148:149], v[148:149], s[100:101] op_sel_hi:[1,0]
	v_pk_mul_f32 v[150:151], v[150:151], s[100:101] op_sel_hi:[1,0]
	v_pk_mul_f32 v[152:153], v[152:153], s[100:101] op_sel_hi:[1,0]
	v_min_f32_e32 v146, 0x42b80000, v146
	v_min_f32_e32 v147, 0x42b80000, v147
	v_min_f32_e32 v148, 0x42b80000, v148
	v_min_f32_e32 v149, 0x42b80000, v149
	v_min_f32_e32 v150, 0x42b80000, v150
	v_min_f32_e32 v151, 0x42b80000, v151
	v_min_f32_e32 v152, 0x42b80000, v152
	v_min_f32_e32 v153, 0x42b80000, v153
	v_exp_f32_e32 v146, v146
	v_exp_f32_e32 v147, v147
	v_exp_f32_e32 v148, v148
	v_exp_f32_e32 v149, v149
	v_exp_f32_e32 v150, v150
	v_exp_f32_e32 v151, v151
	v_exp_f32_e32 v152, v152
	v_exp_f32_e32 v153, v153
	s_nop 0
	v_add_f32_e32 v146, 1.0, v146
	v_add_f32_e32 v147, 1.0, v147
	v_add_f32_e32 v148, 1.0, v148
	v_add_f32_e32 v149, 1.0, v149
	v_add_f32_e32 v150, 1.0, v150
	v_add_f32_e32 v151, 1.0, v151
	v_add_f32_e32 v152, 1.0, v152
	v_add_f32_e32 v153, 1.0, v153
	v_rcp_f32_e32 v146, v146
	v_rcp_f32_e32 v147, v147
	v_rcp_f32_e32 v150, v150
	v_rcp_f32_e32 v151, v151
	s_nop 0
	v_pk_mul_f32 v[146:147], v[146:147], v[148:149]
	v_pk_mul_f32 v[150:151], v[150:151], v[152:153]
	v_pk_mul_f32 v[110:111], v[110:111], v[146:147]
	v_pk_mul_f32 v[112:113], v[112:113], v[150:151]
	global_load_dwordx4 v[184:187], v[136:137], off
	global_load_dwordx4 v[188:191], v[136:137], off offset:256
	global_load_dwordx4 v[192:195], v[136:137], off offset:2048
	global_load_dwordx4 v[196:199], v[136:137], off offset:2304
	s_waitcnt vmcnt(8)
	v_lshlrev_b32_e32 v146, 16, v200
	v_and_b32_e32 v147, 0xffff0000, v200
	v_lshlrev_b32_e32 v148, 16, v208
	v_and_b32_e32 v149, 0xffff0000, v208
	v_lshlrev_b32_e32 v150, 16, v201
	v_and_b32_e32 v151, 0xffff0000, v201
	v_lshlrev_b32_e32 v152, 16, v209
	v_and_b32_e32 v153, 0xffff0000, v209
	v_pk_mul_f32 v[146:147], v[146:147], s[100:101] op_sel_hi:[1,0]
	v_pk_mul_f32 v[148:149], v[148:149], s[100:101] op_sel_hi:[1,0]
	v_pk_mul_f32 v[150:151], v[150:151], s[100:101] op_sel_hi:[1,0]
	v_pk_mul_f32 v[152:153], v[152:153], s[100:101] op_sel_hi:[1,0]
	v_min_f32_e32 v146, 0x42b80000, v146
	v_min_f32_e32 v147, 0x42b80000, v147
	v_min_f32_e32 v148, 0x42b80000, v148
	v_min_f32_e32 v149, 0x42b80000, v149
	v_min_f32_e32 v150, 0x42b80000, v150
	v_min_f32_e32 v151, 0x42b80000, v151
	v_min_f32_e32 v152, 0x42b80000, v152
	v_min_f32_e32 v153, 0x42b80000, v153
	v_exp_f32_e32 v146, v146
	v_exp_f32_e32 v147, v147
	v_exp_f32_e32 v148, v148
	v_exp_f32_e32 v149, v149
	v_exp_f32_e32 v150, v150
	v_exp_f32_e32 v151, v151
	v_exp_f32_e32 v152, v152
	v_exp_f32_e32 v153, v153
	s_nop 0
	v_add_f32_e32 v146, 1.0, v146
	v_add_f32_e32 v147, 1.0, v147
	v_add_f32_e32 v148, 1.0, v148
	v_add_f32_e32 v149, 1.0, v149
	v_add_f32_e32 v150, 1.0, v150
	v_add_f32_e32 v151, 1.0, v151
	v_add_f32_e32 v152, 1.0, v152
	v_add_f32_e32 v153, 1.0, v153
	v_rcp_f32_e32 v146, v146
	v_rcp_f32_e32 v147, v147
	v_rcp_f32_e32 v150, v150
	v_rcp_f32_e32 v151, v151
	s_nop 0
	v_pk_mul_f32 v[146:147], v[146:147], v[148:149]
	v_pk_mul_f32 v[150:151], v[150:151], v[152:153]
	v_pk_mul_f32 v[118:119], v[118:119], v[146:147]
	v_pk_mul_f32 v[120:121], v[120:121], v[150:151]
	v_lshlrev_b32_e32 v168, 16, v202
	v_and_b32_e32 v169, 0xffff0000, v202
	v_lshlrev_b32_e32 v178, 16, v210
	v_and_b32_e32 v179, 0xffff0000, v210
	v_lshlrev_b32_e32 v180, 16, v203
	v_and_b32_e32 v181, 0xffff0000, v203
	v_lshlrev_b32_e32 v244, 16, v211
	v_and_b32_e32 v245, 0xffff0000, v211
	v_pk_mul_f32 v[168:169], v[168:169], s[100:101] op_sel_hi:[1,0]
	v_pk_mul_f32 v[178:179], v[178:179], s[100:101] op_sel_hi:[1,0]
	v_pk_mul_f32 v[180:181], v[180:181], s[100:101] op_sel_hi:[1,0]
	v_pk_mul_f32 v[244:245], v[244:245], s[100:101] op_sel_hi:[1,0]
	v_min_f32_e32 v168, 0x42b80000, v168
	v_min_f32_e32 v169, 0x42b80000, v169
	v_min_f32_e32 v178, 0x42b80000, v178
	v_min_f32_e32 v179, 0x42b80000, v179
	v_min_f32_e32 v180, 0x42b80000, v180
	v_min_f32_e32 v181, 0x42b80000, v181
	v_min_f32_e32 v244, 0x42b80000, v244
	v_min_f32_e32 v245, 0x42b80000, v245
	v_exp_f32_e32 v168, v168
	v_exp_f32_e32 v169, v169
	v_exp_f32_e32 v178, v178
; DI float bflo(unsigned w) { return __uint_as_float(w << 16); }
; DI float bfhi(unsigned w) { return __uint_as_float(w & 0xffff0000u); }
; DI float fexp(float x) { return __builtin_amdgcn_exp2f(x * LOG2E); }
; DI float frcp(float x) { return __builtin_amdgcn_rcpf(x); }
; DI float fsigmoid(float x) { return frcp(1.0f + fexp(-x)); }
;     DI void operator()(Acc& acc, const Unit& u, int wr, int wc, int fr, int fq) const {
;     ...
;                     for (int bj = 0; bj < 2; ++bj) g[ai][m][bj] = *(const u32x4*)(base + (size_t)(ai * 128 + m * 16) * NPJ + u.k * 1024 + bj * 128);
; #pragma unroll
;             for (int ai = 0; ai < 2; ++ai)
; #pragma unroll
;                 for (int m = 0; m < 4; ++m)
; #pragma unroll
;                     for (int bj = 0; bj < 2; ++bj) { const u32x4 q = g[ai][m][bj]; f32x4& v0 = acc[ai][bj][m][0]; f32x4& v1 = acc[ai][bj][m][1];
;                         v0[0] *= bflo(q.x); v0[1] *= bfhi(q.x); v0[2] *= bflo(q.y); v0[3] *= bfhi(q.y); v1[0] *= bflo(q.z); v1[1] *= bfhi(q.z); v1[2] *= bflo(q.w); v1[3] *= bfhi(q.w); }
	v_exp_f32_e32 v179, v179
	v_exp_f32_e32 v180, v180
	v_exp_f32_e32 v181, v181
	v_exp_f32_e32 v244, v244
	v_exp_f32_e32 v245, v245
	s_nop 0
	v_add_f32_e32 v168, 1.0, v168
	v_add_f32_e32 v169, 1.0, v169
	v_add_f32_e32 v178, 1.0, v178
	v_add_f32_e32 v179, 1.0, v179
	v_add_f32_e32 v180, 1.0, v180
	v_add_f32_e32 v181, 1.0, v181
	v_add_f32_e32 v244, 1.0, v244
	v_add_f32_e32 v245, 1.0, v245
	v_rcp_f32_e32 v168, v168
	v_rcp_f32_e32 v169, v169
	v_rcp_f32_e32 v180, v180
	v_rcp_f32_e32 v181, v181
	s_nop 0
	v_pk_mul_f32 v[168:169], v[168:169], v[178:179]
	v_pk_mul_f32 v[180:181], v[180:181], v[244:245]
	v_pk_mul_f32 v[106:107], v[106:107], v[168:169]
	v_pk_mul_f32 v[108:109], v[108:109], v[180:181]
	v_lshlrev_b32_e32 v168, 16, v204
	v_and_b32_e32 v169, 0xffff0000, v204
	v_lshlrev_b32_e32 v178, 16, v212
	v_and_b32_e32 v179, 0xffff0000, v212
	v_lshlrev_b32_e32 v180, 16, v205
	v_and_b32_e32 v181, 0xffff0000, v205
	v_lshlrev_b32_e32 v244, 16, v213
	v_and_b32_e32 v245, 0xffff0000, v213
	v_pk_mul_f32 v[168:169], v[168:169], s[100:101] op_sel_hi:[1,0]
	v_pk_mul_f32 v[178:179], v[178:179], s[100:101] op_sel_hi:[1,0]
	v_pk_mul_f32 v[180:181], v[180:181], s[100:101] op_sel_hi:[1,0]
	v_pk_mul_f32 v[244:245], v[244:245], s[100:101] op_sel_hi:[1,0]
	v_min_f32_e32 v168, 0x42b80000, v168
	v_min_f32_e32 v169, 0x42b80000, v169
	v_min_f32_e32 v178, 0x42b80000, v178
	v_min_f32_e32 v179, 0x42b80000, v179
	v_min_f32_e32 v180, 0x42b80000, v180
	v_min_f32_e32 v181, 0x42b80000, v181
	v_min_f32_e32 v244, 0x42b80000, v244
	v_min_f32_e32 v245, 0x42b80000, v245
	v_exp_f32_e32 v168, v168
	v_exp_f32_e32 v169, v169
	v_exp_f32_e32 v178, v178
	v_exp_f32_e32 v179, v179
	v_exp_f32_e32 v180, v180
	v_exp_f32_e32 v181, v181
	v_exp_f32_e32 v244, v244
	v_exp_f32_e32 v245, v245
	s_nop 0
	v_add_f32_e32 v168, 1.0, v168
	v_add_f32_e32 v169, 1.0, v169
	v_add_f32_e32 v178, 1.0, v178
	v_add_f32_e32 v179, 1.0, v179
	v_add_f32_e32 v180, 1.0, v180
	v_add_f32_e32 v181, 1.0, v181
	v_add_f32_e32 v244, 1.0, v244
	v_add_f32_e32 v245, 1.0, v245
	v_rcp_f32_e32 v168, v168
	v_rcp_f32_e32 v169, v169
	v_rcp_f32_e32 v180, v180
	v_rcp_f32_e32 v181, v181
	s_nop 0
	v_pk_mul_f32 v[168:169], v[168:169], v[178:179]
	v_pk_mul_f32 v[180:181], v[180:181], v[244:245]
	v_pk_mul_f32 v[98:99], v[98:99], v[168:169]
	v_pk_mul_f32 v[100:101], v[100:101], v[180:181]
	v_lshlrev_b32_e32 v146, 16, v206
	v_and_b32_e32 v147, 0xffff0000, v206
	v_lshlrev_b32_e32 v148, 16, v214
	v_and_b32_e32 v149, 0xffff0000, v214
	v_lshlrev_b32_e32 v150, 16, v207
	v_and_b32_e32 v151, 0xffff0000, v207
	v_lshlrev_b32_e32 v152, 16, v215
	v_and_b32_e32 v153, 0xffff0000, v215
	v_pk_mul_f32 v[146:147], v[146:147], s[100:101] op_sel_hi:[1,0]
	v_pk_mul_f32 v[148:149], v[148:149], s[100:101] op_sel_hi:[1,0]
	v_pk_mul_f32 v[150:151], v[150:151], s[100:101] op_sel_hi:[1,0]
	v_pk_mul_f32 v[152:153], v[152:153], s[100:101] op_sel_hi:[1,0]
	v_min_f32_e32 v146, 0x42b80000, v146
	v_min_f32_e32 v147, 0x42b80000, v147
	v_min_f32_e32 v148, 0x42b80000, v148
	v_min_f32_e32 v149, 0x42b80000, v149
	v_min_f32_e32 v150, 0x42b80000, v150
	v_min_f32_e32 v151, 0x42b80000, v151
	v_min_f32_e32 v152, 0x42b80000, v152
	v_min_f32_e32 v153, 0x42b80000, v153
	v_exp_f32_e32 v146, v146
	v_exp_f32_e32 v147, v147
	v_exp_f32_e32 v148, v148
	v_exp_f32_e32 v149, v149
	v_exp_f32_e32 v150, v150
	v_exp_f32_e32 v151, v151
	v_exp_f32_e32 v152, v152
	v_exp_f32_e32 v153, v153
	s_nop 0
	v_add_f32_e32 v146, 1.0, v146
	v_add_f32_e32 v147, 1.0, v147
	v_add_f32_e32 v148, 1.0, v148
	v_add_f32_e32 v149, 1.0, v149
	v_add_f32_e32 v150, 1.0, v150
	v_add_f32_e32 v151, 1.0, v151
	v_add_f32_e32 v152, 1.0, v152
	v_add_f32_e32 v153, 1.0, v153
	v_rcp_f32_e32 v146, v146
	v_rcp_f32_e32 v147, v147
	v_rcp_f32_e32 v150, v150
	v_rcp_f32_e32 v151, v151
	s_nop 0
	v_pk_mul_f32 v[146:147], v[146:147], v[148:149]
	v_pk_mul_f32 v[150:151], v[150:151], v[152:153]
	v_pk_mul_f32 v[90:91], v[90:91], v[146:147]
	v_pk_mul_f32 v[92:93], v[92:93], v[150:151]
	global_load_dwordx4 v[200:203], v[138:139], off
	global_load_dwordx4 v[204:207], v[138:139], off offset:256
	global_load_dwordx4 v[208:211], v[138:139], off offset:2048
	global_load_dwordx4 v[212:215], v[138:139], off offset:2304
	s_waitcnt vmcnt(8)
	v_lshlrev_b32_e32 v146, 16, v216
	v_and_b32_e32 v147, 0xffff0000, v216
	v_lshlrev_b32_e32 v148, 16, v224
	v_and_b32_e32 v149, 0xffff0000, v224
	v_lshlrev_b32_e32 v150, 16, v217
	v_and_b32_e32 v151, 0xffff0000, v217
	v_lshlrev_b32_e32 v152, 16, v225
	v_and_b32_e32 v153, 0xffff0000, v225
	v_pk_mul_f32 v[146:147], v[146:147], s[100:101] op_sel_hi:[1,0]
	v_pk_mul_f32 v[148:149], v[148:149], s[100:101] op_sel_hi:[1,0]
	v_pk_mul_f32 v[150:151], v[150:151], s[100:101] op_sel_hi:[1,0]
	v_pk_mul_f32 v[152:153], v[152:153], s[100:101] op_sel_hi:[1,0]
	v_min_f32_e32 v146, 0x42b80000, v146
	v_min_f32_e32 v147, 0x42b80000, v147
	v_min_f32_e32 v148, 0x42b80000, v148
	v_min_f32_e32 v149, 0x42b80000, v149
	v_min_f32_e32 v150, 0x42b80000, v150
	v_min_f32_e32 v151, 0x42b80000, v151
	v_min_f32_e32 v152, 0x42b80000, v152
	v_min_f32_e32 v153, 0x42b80000, v153
	v_exp_f32_e32 v146, v146
	v_exp_f32_e32 v147, v147
	v_exp_f32_e32 v148, v148
	v_exp_f32_e32 v149, v149
	v_exp_f32_e32 v150, v150
	v_exp_f32_e32 v151, v151
	v_exp_f32_e32 v152, v152
	v_exp_f32_e32 v153, v153
	s_nop 0
	v_add_f32_e32 v146, 1.0, v146
	v_add_f32_e32 v147, 1.0, v147
	v_add_f32_e32 v148, 1.0, v148
	v_add_f32_e32 v149, 1.0, v149
	v_add_f32_e32 v150, 1.0, v150
	v_add_f32_e32 v151, 1.0, v151
	v_add_f32_e32 v152, 1.0, v152
	v_add_f32_e32 v153, 1.0, v153
	v_rcp_f32_e32 v146, v146
	v_rcp_f32_e32 v147, v147
	v_rcp_f32_e32 v150, v150
	v_rcp_f32_e32 v151, v151
	s_nop 0
; DI float bflo(unsigned w) { return __uint_as_float(w << 16); }
; DI float bfhi(unsigned w) { return __uint_as_float(w & 0xffff0000u); }
; DI float fexp(float x) { return __builtin_amdgcn_exp2f(x * LOG2E); }
; DI float frcp(float x) { return __builtin_amdgcn_rcpf(x); }
; DI float fsigmoid(float x) { return frcp(1.0f + fexp(-x)); }
;     DI void operator()(Acc& acc, const Unit& u, int wr, int wc, int fr, int fq) const {
;     ...
;                     for (int bj = 0; bj < 2; ++bj) g[ai][m][bj] = *(const u32x4*)(base + (size_t)(ai * 128 + m * 16) * NPJ + u.k * 1024 + bj * 128);
; #pragma unroll
;             for (int ai = 0; ai < 2; ++ai)
; #pragma unroll
;                 for (int m = 0; m < 4; ++m)
; #pragma unroll
;                     for (int bj = 0; bj < 2; ++bj) { const u32x4 q = g[ai][m][bj]; f32x4& v0 = acc[ai][bj][m][0]; f32x4& v1 = acc[ai][bj][m][1];
;                         v0[0] *= bflo(q.x); v0[1] *= bfhi(q.x); v0[2] *= bflo(q.y); v0[3] *= bfhi(q.y); v1[0] *= bflo(q.z); v1[1] *= bfhi(q.z); v1[2] *= bflo(q.w); v1[3] *= bfhi(q.w); }
	v_pk_mul_f32 v[146:147], v[146:147], v[148:149]
	v_pk_mul_f32 v[150:151], v[150:151], v[152:153]
	v_pk_mul_f32 v[102:103], v[102:103], v[146:147]
	v_pk_mul_f32 v[104:105], v[104:105], v[150:151]
	v_lshlrev_b32_e32 v168, 16, v218
	v_and_b32_e32 v169, 0xffff0000, v218
	v_lshlrev_b32_e32 v178, 16, v226
	v_and_b32_e32 v179, 0xffff0000, v226
	v_lshlrev_b32_e32 v180, 16, v219
	v_and_b32_e32 v181, 0xffff0000, v219
	v_lshlrev_b32_e32 v244, 16, v227
	v_and_b32_e32 v245, 0xffff0000, v227
	v_pk_mul_f32 v[168:169], v[168:169], s[100:101] op_sel_hi:[1,0]
	v_pk_mul_f32 v[178:179], v[178:179], s[100:101] op_sel_hi:[1,0]
	v_pk_mul_f32 v[180:181], v[180:181], s[100:101] op_sel_hi:[1,0]
	v_pk_mul_f32 v[244:245], v[244:245], s[100:101] op_sel_hi:[1,0]
	v_min_f32_e32 v168, 0x42b80000, v168
	v_min_f32_e32 v169, 0x42b80000, v169
	v_min_f32_e32 v178, 0x42b80000, v178
	v_min_f32_e32 v179, 0x42b80000, v179
	v_min_f32_e32 v180, 0x42b80000, v180
	v_min_f32_e32 v181, 0x42b80000, v181
	v_min_f32_e32 v244, 0x42b80000, v244
	v_min_f32_e32 v245, 0x42b80000, v245
	v_exp_f32_e32 v168, v168
	v_exp_f32_e32 v169, v169
	v_exp_f32_e32 v178, v178
	v_exp_f32_e32 v179, v179
	v_exp_f32_e32 v180, v180
	v_exp_f32_e32 v181, v181
	v_exp_f32_e32 v244, v244
	v_exp_f32_e32 v245, v245
	s_nop 0
	v_add_f32_e32 v168, 1.0, v168
	v_add_f32_e32 v169, 1.0, v169
	v_add_f32_e32 v178, 1.0, v178
	v_add_f32_e32 v179, 1.0, v179
	v_add_f32_e32 v180, 1.0, v180
	v_add_f32_e32 v181, 1.0, v181
	v_add_f32_e32 v244, 1.0, v244
	v_add_f32_e32 v245, 1.0, v245
	v_rcp_f32_e32 v168, v168
	v_rcp_f32_e32 v169, v169
	v_rcp_f32_e32 v180, v180
	v_rcp_f32_e32 v181, v181
	s_nop 0
	v_pk_mul_f32 v[168:169], v[168:169], v[178:179]
	v_pk_mul_f32 v[180:181], v[180:181], v[244:245]
	v_pk_mul_f32 v[94:95], v[94:95], v[168:169]
	v_pk_mul_f32 v[96:97], v[96:97], v[180:181]
	v_lshlrev_b32_e32 v168, 16, v220
	v_and_b32_e32 v169, 0xffff0000, v220
	v_lshlrev_b32_e32 v178, 16, v228
	v_and_b32_e32 v179, 0xffff0000, v228
	v_lshlrev_b32_e32 v180, 16, v221
	v_and_b32_e32 v181, 0xffff0000, v221
	v_lshlrev_b32_e32 v244, 16, v229
	v_and_b32_e32 v245, 0xffff0000, v229
	v_pk_mul_f32 v[168:169], v[168:169], s[100:101] op_sel_hi:[1,0]
	v_pk_mul_f32 v[178:179], v[178:179], s[100:101] op_sel_hi:[1,0]
	v_pk_mul_f32 v[180:181], v[180:181], s[100:101] op_sel_hi:[1,0]
	v_pk_mul_f32 v[244:245], v[244:245], s[100:101] op_sel_hi:[1,0]
	v_min_f32_e32 v168, 0x42b80000, v168
	v_min_f32_e32 v169, 0x42b80000, v169
	v_min_f32_e32 v178, 0x42b80000, v178
	v_min_f32_e32 v179, 0x42b80000, v179
	v_min_f32_e32 v180, 0x42b80000, v180
	v_min_f32_e32 v181, 0x42b80000, v181
	v_min_f32_e32 v244, 0x42b80000, v244
	v_min_f32_e32 v245, 0x42b80000, v245
	v_exp_f32_e32 v168, v168
	v_exp_f32_e32 v169, v169
	v_exp_f32_e32 v178, v178
	v_exp_f32_e32 v179, v179
	v_exp_f32_e32 v180, v180
	v_exp_f32_e32 v181, v181
	v_exp_f32_e32 v244, v244
	v_exp_f32_e32 v245, v245
	s_nop 0
	v_add_f32_e32 v168, 1.0, v168
	v_add_f32_e32 v169, 1.0, v169
	v_add_f32_e32 v178, 1.0, v178
	v_add_f32_e32 v179, 1.0, v179
	v_add_f32_e32 v180, 1.0, v180
	v_add_f32_e32 v181, 1.0, v181
	v_add_f32_e32 v244, 1.0, v244
	v_add_f32_e32 v245, 1.0, v245
	v_rcp_f32_e32 v168, v168
	v_rcp_f32_e32 v169, v169
	v_rcp_f32_e32 v180, v180
	v_rcp_f32_e32 v181, v181
	s_nop 0
	v_pk_mul_f32 v[168:169], v[168:169], v[178:179]
	v_pk_mul_f32 v[180:181], v[180:181], v[244:245]
	v_pk_mul_f32 v[82:83], v[82:83], v[168:169]
	v_pk_mul_f32 v[84:85], v[84:85], v[180:181]
	v_lshlrev_b32_e32 v146, 16, v222
	v_and_b32_e32 v147, 0xffff0000, v222
	v_lshlrev_b32_e32 v148, 16, v230
	v_and_b32_e32 v149, 0xffff0000, v230
	v_lshlrev_b32_e32 v150, 16, v223
	v_and_b32_e32 v151, 0xffff0000, v223
	v_lshlrev_b32_e32 v152, 16, v231
	v_and_b32_e32 v153, 0xffff0000, v231
	v_pk_mul_f32 v[146:147], v[146:147], s[100:101] op_sel_hi:[1,0]
	v_pk_mul_f32 v[148:149], v[148:149], s[100:101] op_sel_hi:[1,0]
	v_pk_mul_f32 v[150:151], v[150:151], s[100:101] op_sel_hi:[1,0]
	v_pk_mul_f32 v[152:153], v[152:153], s[100:101] op_sel_hi:[1,0]
	v_min_f32_e32 v146, 0x42b80000, v146
	v_min_f32_e32 v147, 0x42b80000, v147
	v_min_f32_e32 v148, 0x42b80000, v148
	v_min_f32_e32 v149, 0x42b80000, v149
	v_min_f32_e32 v150, 0x42b80000, v150
	v_min_f32_e32 v151, 0x42b80000, v151
	v_min_f32_e32 v152, 0x42b80000, v152
	v_min_f32_e32 v153, 0x42b80000, v153
	v_exp_f32_e32 v146, v146
	v_exp_f32_e32 v147, v147
	v_exp_f32_e32 v148, v148
	v_exp_f32_e32 v149, v149
	v_exp_f32_e32 v150, v150
	v_exp_f32_e32 v151, v151
	v_exp_f32_e32 v152, v152
	v_exp_f32_e32 v153, v153
	s_nop 0
	v_add_f32_e32 v146, 1.0, v146
	v_add_f32_e32 v147, 1.0, v147
	v_add_f32_e32 v148, 1.0, v148
	v_add_f32_e32 v149, 1.0, v149
	v_add_f32_e32 v150, 1.0, v150
	v_add_f32_e32 v151, 1.0, v151
	v_add_f32_e32 v152, 1.0, v152
	v_add_f32_e32 v153, 1.0, v153
	v_rcp_f32_e32 v146, v146
	v_rcp_f32_e32 v147, v147
	v_rcp_f32_e32 v150, v150
	v_rcp_f32_e32 v151, v151
	s_nop 0
	v_pk_mul_f32 v[146:147], v[146:147], v[148:149]
	v_pk_mul_f32 v[150:151], v[150:151], v[152:153]
	v_pk_mul_f32 v[74:75], v[74:75], v[146:147]
	v_pk_mul_f32 v[76:77], v[76:77], v[150:151]
	global_load_dwordx4 v[216:219], v[140:141], off
	global_load_dwordx4 v[220:223], v[140:141], off offset:256
	global_load_dwordx4 v[224:227], v[140:141], off offset:2048
	global_load_dwordx4 v[228:231], v[140:141], off offset:2304
	s_waitcnt vmcnt(8)
; DI float bflo(unsigned w) { return __uint_as_float(w << 16); }
; DI float bfhi(unsigned w) { return __uint_as_float(w & 0xffff0000u); }
; DI float fexp(float x) { return __builtin_amdgcn_exp2f(x * LOG2E); }
; DI float frcp(float x) { return __builtin_amdgcn_rcpf(x); }
; DI float fsigmoid(float x) { return frcp(1.0f + fexp(-x)); }
;     DI void operator()(Acc& acc, const Unit& u, int wr, int wc, int fr, int fq) const {
;     ...
;                     for (int bj = 0; bj < 2; ++bj) g[ai][m][bj] = *(const u32x4*)(base + (size_t)(ai * 128 + m * 16) * NPJ + u.k * 1024 + bj * 128);
; #pragma unroll
;             for (int ai = 0; ai < 2; ++ai)
; #pragma unroll
;                 for (int m = 0; m < 4; ++m)
; #pragma unroll
;                     for (int bj = 0; bj < 2; ++bj) { const u32x4 q = g[ai][m][bj]; f32x4& v0 = acc[ai][bj][m][0]; f32x4& v1 = acc[ai][bj][m][1];
;                         v0[0] *= bflo(q.x); v0[1] *= bfhi(q.x); v0[2] *= bflo(q.y); v0[3] *= bfhi(q.y); v1[0] *= bflo(q.z); v1[1] *= bfhi(q.z); v1[2] *= bflo(q.w); v1[3] *= bfhi(q.w); }
	v_lshlrev_b32_e32 v146, 16, v184
	v_and_b32_e32 v147, 0xffff0000, v184
	v_lshlrev_b32_e32 v148, 16, v192
	v_and_b32_e32 v149, 0xffff0000, v192
	v_lshlrev_b32_e32 v150, 16, v185
	v_and_b32_e32 v151, 0xffff0000, v185
	v_lshlrev_b32_e32 v152, 16, v193
	v_and_b32_e32 v153, 0xffff0000, v193
	v_pk_mul_f32 v[146:147], v[146:147], s[100:101] op_sel_hi:[1,0]
	v_pk_mul_f32 v[148:149], v[148:149], s[100:101] op_sel_hi:[1,0]
	v_pk_mul_f32 v[150:151], v[150:151], s[100:101] op_sel_hi:[1,0]
	v_pk_mul_f32 v[152:153], v[152:153], s[100:101] op_sel_hi:[1,0]
	v_min_f32_e32 v146, 0x42b80000, v146
	v_min_f32_e32 v147, 0x42b80000, v147
	v_min_f32_e32 v148, 0x42b80000, v148
	v_min_f32_e32 v149, 0x42b80000, v149
	v_min_f32_e32 v150, 0x42b80000, v150
	v_min_f32_e32 v151, 0x42b80000, v151
	v_min_f32_e32 v152, 0x42b80000, v152
	v_min_f32_e32 v153, 0x42b80000, v153
	v_exp_f32_e32 v146, v146
	v_exp_f32_e32 v147, v147
	v_exp_f32_e32 v148, v148
	v_exp_f32_e32 v149, v149
	v_exp_f32_e32 v150, v150
	v_exp_f32_e32 v151, v151
	v_exp_f32_e32 v152, v152
	v_exp_f32_e32 v153, v153
	s_nop 0
	v_add_f32_e32 v146, 1.0, v146
	v_add_f32_e32 v147, 1.0, v147
	v_add_f32_e32 v148, 1.0, v148
	v_add_f32_e32 v149, 1.0, v149
	v_add_f32_e32 v150, 1.0, v150
	v_add_f32_e32 v151, 1.0, v151
	v_add_f32_e32 v152, 1.0, v152
	v_add_f32_e32 v153, 1.0, v153
	v_rcp_f32_e32 v146, v146
	v_rcp_f32_e32 v147, v147
	v_rcp_f32_e32 v150, v150
	v_rcp_f32_e32 v151, v151
	s_nop 0
	v_pk_mul_f32 v[146:147], v[146:147], v[148:149]
	v_pk_mul_f32 v[150:151], v[150:151], v[152:153]
	v_pk_mul_f32 v[86:87], v[86:87], v[146:147]
	v_pk_mul_f32 v[88:89], v[88:89], v[150:151]
	v_lshlrev_b32_e32 v168, 16, v186
	v_and_b32_e32 v169, 0xffff0000, v186
	v_lshlrev_b32_e32 v178, 16, v194
	v_and_b32_e32 v179, 0xffff0000, v194
	v_lshlrev_b32_e32 v180, 16, v187
	v_and_b32_e32 v181, 0xffff0000, v187
	v_lshlrev_b32_e32 v244, 16, v195
	v_and_b32_e32 v245, 0xffff0000, v195
	v_pk_mul_f32 v[168:169], v[168:169], s[100:101] op_sel_hi:[1,0]
	v_pk_mul_f32 v[178:179], v[178:179], s[100:101] op_sel_hi:[1,0]
	v_pk_mul_f32 v[180:181], v[180:181], s[100:101] op_sel_hi:[1,0]
	v_pk_mul_f32 v[244:245], v[244:245], s[100:101] op_sel_hi:[1,0]
	v_min_f32_e32 v168, 0x42b80000, v168
	v_min_f32_e32 v169, 0x42b80000, v169
	v_min_f32_e32 v178, 0x42b80000, v178
	v_min_f32_e32 v179, 0x42b80000, v179
	v_min_f32_e32 v180, 0x42b80000, v180
	v_min_f32_e32 v181, 0x42b80000, v181
	v_min_f32_e32 v244, 0x42b80000, v244
	v_min_f32_e32 v245, 0x42b80000, v245
	v_exp_f32_e32 v168, v168
	v_exp_f32_e32 v169, v169
	v_exp_f32_e32 v178, v178
	v_exp_f32_e32 v179, v179
	v_exp_f32_e32 v180, v180
	v_exp_f32_e32 v181, v181
	v_exp_f32_e32 v244, v244
	v_exp_f32_e32 v245, v245
	s_nop 0
	v_add_f32_e32 v168, 1.0, v168
	v_add_f32_e32 v169, 1.0, v169
	v_add_f32_e32 v178, 1.0, v178
	v_add_f32_e32 v179, 1.0, v179
	v_add_f32_e32 v180, 1.0, v180
	v_add_f32_e32 v181, 1.0, v181
	v_add_f32_e32 v244, 1.0, v244
	v_add_f32_e32 v245, 1.0, v245
	v_rcp_f32_e32 v168, v168
	v_rcp_f32_e32 v169, v169
	v_rcp_f32_e32 v180, v180
	v_rcp_f32_e32 v181, v181
	s_nop 0
	v_pk_mul_f32 v[168:169], v[168:169], v[178:179]
	v_pk_mul_f32 v[180:181], v[180:181], v[244:245]
	v_pk_mul_f32 v[78:79], v[78:79], v[168:169]
	v_pk_mul_f32 v[80:81], v[80:81], v[180:181]
	v_lshlrev_b32_e32 v168, 16, v188
	v_and_b32_e32 v169, 0xffff0000, v188
	v_lshlrev_b32_e32 v178, 16, v196
	v_and_b32_e32 v179, 0xffff0000, v196
	v_lshlrev_b32_e32 v180, 16, v189
	v_and_b32_e32 v181, 0xffff0000, v189
	v_lshlrev_b32_e32 v244, 16, v197
	v_and_b32_e32 v245, 0xffff0000, v197
	v_pk_mul_f32 v[168:169], v[168:169], s[100:101] op_sel_hi:[1,0]
	v_pk_mul_f32 v[178:179], v[178:179], s[100:101] op_sel_hi:[1,0]
	v_pk_mul_f32 v[180:181], v[180:181], s[100:101] op_sel_hi:[1,0]
	v_pk_mul_f32 v[244:245], v[244:245], s[100:101] op_sel_hi:[1,0]
	v_min_f32_e32 v168, 0x42b80000, v168
	v_min_f32_e32 v169, 0x42b80000, v169
	v_min_f32_e32 v178, 0x42b80000, v178
	v_min_f32_e32 v179, 0x42b80000, v179
	v_min_f32_e32 v180, 0x42b80000, v180
	v_min_f32_e32 v181, 0x42b80000, v181
	v_min_f32_e32 v244, 0x42b80000, v244
	v_min_f32_e32 v245, 0x42b80000, v245
	v_exp_f32_e32 v168, v168
	v_exp_f32_e32 v169, v169
	v_exp_f32_e32 v178, v178
	v_exp_f32_e32 v179, v179
	v_exp_f32_e32 v180, v180
	v_exp_f32_e32 v181, v181
	v_exp_f32_e32 v244, v244
	v_exp_f32_e32 v245, v245
	s_nop 0
	v_add_f32_e32 v168, 1.0, v168
	v_add_f32_e32 v169, 1.0, v169
	v_add_f32_e32 v178, 1.0, v178
	v_add_f32_e32 v179, 1.0, v179
	v_add_f32_e32 v180, 1.0, v180
	v_add_f32_e32 v181, 1.0, v181
	v_add_f32_e32 v244, 1.0, v244
	v_add_f32_e32 v245, 1.0, v245
	v_rcp_f32_e32 v168, v168
	v_rcp_f32_e32 v169, v169
	v_rcp_f32_e32 v180, v180
	v_rcp_f32_e32 v181, v181
	s_nop 0
	v_pk_mul_f32 v[168:169], v[168:169], v[178:179]
	v_pk_mul_f32 v[180:181], v[180:181], v[244:245]
	v_pk_mul_f32 v[70:71], v[70:71], v[168:169]
	v_pk_mul_f32 v[72:73], v[72:73], v[180:181]
	v_lshlrev_b32_e32 v146, 16, v190
	v_and_b32_e32 v147, 0xffff0000, v190
	v_lshlrev_b32_e32 v148, 16, v198
	v_and_b32_e32 v149, 0xffff0000, v198
	v_lshlrev_b32_e32 v150, 16, v191
	v_and_b32_e32 v151, 0xffff0000, v191
	v_lshlrev_b32_e32 v152, 16, v199
	v_and_b32_e32 v153, 0xffff0000, v199
	v_pk_mul_f32 v[146:147], v[146:147], s[100:101] op_sel_hi:[1,0]
	v_pk_mul_f32 v[148:149], v[148:149], s[100:101] op_sel_hi:[1,0]
	v_pk_mul_f32 v[150:151], v[150:151], s[100:101] op_sel_hi:[1,0]
	v_pk_mul_f32 v[152:153], v[152:153], s[100:101] op_sel_hi:[1,0]
	v_min_f32_e32 v146, 0x42b80000, v146
	v_min_f32_e32 v147, 0x42b80000, v147
	v_min_f32_e32 v148, 0x42b80000, v148
	v_min_f32_e32 v149, 0x42b80000, v149
	v_min_f32_e32 v150, 0x42b80000, v150
	v_min_f32_e32 v151, 0x42b80000, v151
	v_min_f32_e32 v152, 0x42b80000, v152
	v_min_f32_e32 v153, 0x42b80000, v153
	v_exp_f32_e32 v146, v146
	v_exp_f32_e32 v147, v147
	v_exp_f32_e32 v148, v148
	v_exp_f32_e32 v149, v149
	v_exp_f32_e32 v150, v150
	v_exp_f32_e32 v151, v151
	v_exp_f32_e32 v152, v152
	v_exp_f32_e32 v153, v153
	s_nop 0
	v_add_f32_e32 v146, 1.0, v146
	v_add_f32_e32 v147, 1.0, v147
	v_add_f32_e32 v148, 1.0, v148
	v_add_f32_e32 v149, 1.0, v149
	v_add_f32_e32 v150, 1.0, v150
	v_add_f32_e32 v151, 1.0, v151
	v_add_f32_e32 v152, 1.0, v152
	v_add_f32_e32 v153, 1.0, v153
	v_rcp_f32_e32 v146, v146
	v_rcp_f32_e32 v147, v147
	v_rcp_f32_e32 v150, v150
	v_rcp_f32_e32 v151, v151
	s_nop 0
	v_pk_mul_f32 v[146:147], v[146:147], v[148:149]
	v_pk_mul_f32 v[150:151], v[150:151], v[152:153]
	v_pk_mul_f32 v[66:67], v[66:67], v[146:147]
	v_pk_mul_f32 v[68:69], v[68:69], v[150:151]
	global_load_dwordx4 v[184:187], v[142:143], off
	global_load_dwordx4 v[188:191], v[142:143], off offset:256
	global_load_dwordx4 v[192:195], v[142:143], off offset:2048
	global_load_dwordx4 v[196:199], v[142:143], off offset:2304
	s_waitcnt vmcnt(8)
; DI float bflo(unsigned w) { return __uint_as_float(w << 16); }
; DI float bfhi(unsigned w) { return __uint_as_float(w & 0xffff0000u); }
; DI float fexp(float x) { return __builtin_amdgcn_exp2f(x * LOG2E); }
; DI float frcp(float x) { return __builtin_amdgcn_rcpf(x); }
; DI float fsigmoid(float x) { return frcp(1.0f + fexp(-x)); }
;     DI void operator()(Acc& acc, const Unit& u, int wr, int wc, int fr, int fq) const {
;     ...
;                     for (int bj = 0; bj < 2; ++bj) g[ai][m][bj] = *(const u32x4*)(base + (size_t)(ai * 128 + m * 16) * NPJ + u.k * 1024 + bj * 128);
; #pragma unroll
;             for (int ai = 0; ai < 2; ++ai)
; #pragma unroll
;                 for (int m = 0; m < 4; ++m)
; #pragma unroll
;                     for (int bj = 0; bj < 2; ++bj) { const u32x4 q = g[ai][m][bj]; f32x4& v0 = acc[ai][bj][m][0]; f32x4& v1 = acc[ai][bj][m][1];
;                         v0[0] *= bflo(q.x); v0[1] *= bfhi(q.x); v0[2] *= bflo(q.y); v0[3] *= bfhi(q.y); v1[0] *= bflo(q.z); v1[1] *= bfhi(q.z); v1[2] *= bflo(q.w); v1[3] *= bfhi(q.w); }
	v_lshlrev_b32_e32 v146, 16, v200
	v_and_b32_e32 v147, 0xffff0000, v200
	v_lshlrev_b32_e32 v148, 16, v208
	v_and_b32_e32 v149, 0xffff0000, v208
	v_lshlrev_b32_e32 v150, 16, v201
	v_and_b32_e32 v151, 0xffff0000, v201
	v_lshlrev_b32_e32 v152, 16, v209
	v_and_b32_e32 v153, 0xffff0000, v209
	v_pk_mul_f32 v[146:147], v[146:147], s[100:101] op_sel_hi:[1,0]
	v_pk_mul_f32 v[148:149], v[148:149], s[100:101] op_sel_hi:[1,0]
	v_pk_mul_f32 v[150:151], v[150:151], s[100:101] op_sel_hi:[1,0]
	v_pk_mul_f32 v[152:153], v[152:153], s[100:101] op_sel_hi:[1,0]
	v_min_f32_e32 v146, 0x42b80000, v146
	v_min_f32_e32 v147, 0x42b80000, v147
	v_min_f32_e32 v148, 0x42b80000, v148
	v_min_f32_e32 v149, 0x42b80000, v149
	v_min_f32_e32 v150, 0x42b80000, v150
	v_min_f32_e32 v151, 0x42b80000, v151
	v_min_f32_e32 v152, 0x42b80000, v152
	v_min_f32_e32 v153, 0x42b80000, v153
	v_exp_f32_e32 v146, v146
	v_exp_f32_e32 v147, v147
	v_exp_f32_e32 v148, v148
	v_exp_f32_e32 v149, v149
	v_exp_f32_e32 v150, v150
	v_exp_f32_e32 v151, v151
	v_exp_f32_e32 v152, v152
	v_exp_f32_e32 v153, v153
	s_nop 0
	v_add_f32_e32 v146, 1.0, v146
	v_add_f32_e32 v147, 1.0, v147
	v_add_f32_e32 v148, 1.0, v148
	v_add_f32_e32 v149, 1.0, v149
	v_add_f32_e32 v150, 1.0, v150
	v_add_f32_e32 v151, 1.0, v151
	v_add_f32_e32 v152, 1.0, v152
	v_add_f32_e32 v153, 1.0, v153
	v_rcp_f32_e32 v146, v146
	v_rcp_f32_e32 v147, v147
	v_rcp_f32_e32 v150, v150
	v_rcp_f32_e32 v151, v151
	s_nop 0
	v_pk_mul_f32 v[146:147], v[146:147], v[148:149]
	v_pk_mul_f32 v[150:151], v[150:151], v[152:153]
	v_pk_mul_f32 v[62:63], v[62:63], v[146:147]
	v_pk_mul_f32 v[64:65], v[64:65], v[150:151]
	v_lshlrev_b32_e32 v168, 16, v202
	v_and_b32_e32 v169, 0xffff0000, v202
	v_lshlrev_b32_e32 v178, 16, v210
	v_and_b32_e32 v179, 0xffff0000, v210
	v_lshlrev_b32_e32 v180, 16, v203
	v_and_b32_e32 v181, 0xffff0000, v203
	v_lshlrev_b32_e32 v244, 16, v211
	v_and_b32_e32 v245, 0xffff0000, v211
	v_pk_mul_f32 v[168:169], v[168:169], s[100:101] op_sel_hi:[1,0]
	v_pk_mul_f32 v[178:179], v[178:179], s[100:101] op_sel_hi:[1,0]
	v_pk_mul_f32 v[180:181], v[180:181], s[100:101] op_sel_hi:[1,0]
	v_pk_mul_f32 v[244:245], v[244:245], s[100:101] op_sel_hi:[1,0]
	v_min_f32_e32 v168, 0x42b80000, v168
	v_min_f32_e32 v169, 0x42b80000, v169
	v_min_f32_e32 v178, 0x42b80000, v178
	v_min_f32_e32 v179, 0x42b80000, v179
	v_min_f32_e32 v180, 0x42b80000, v180
	v_min_f32_e32 v181, 0x42b80000, v181
	v_min_f32_e32 v244, 0x42b80000, v244
	v_min_f32_e32 v245, 0x42b80000, v245
	v_exp_f32_e32 v168, v168
	v_exp_f32_e32 v169, v169
	v_exp_f32_e32 v178, v178
	v_exp_f32_e32 v179, v179
	v_exp_f32_e32 v180, v180
	v_exp_f32_e32 v181, v181
	v_exp_f32_e32 v244, v244
	v_exp_f32_e32 v245, v245
	s_nop 0
	v_add_f32_e32 v168, 1.0, v168
	v_add_f32_e32 v169, 1.0, v169
	v_add_f32_e32 v178, 1.0, v178
	v_add_f32_e32 v179, 1.0, v179
	v_add_f32_e32 v180, 1.0, v180
	v_add_f32_e32 v181, 1.0, v181
	v_add_f32_e32 v244, 1.0, v244
	v_add_f32_e32 v245, 1.0, v245
	v_rcp_f32_e32 v168, v168
	v_rcp_f32_e32 v169, v169
	v_rcp_f32_e32 v180, v180
	v_rcp_f32_e32 v181, v181
	s_nop 0
	v_pk_mul_f32 v[168:169], v[168:169], v[178:179]
	v_pk_mul_f32 v[180:181], v[180:181], v[244:245]
	v_pk_mul_f32 v[58:59], v[58:59], v[168:169]
	v_pk_mul_f32 v[60:61], v[60:61], v[180:181]
	v_lshlrev_b32_e32 v168, 16, v204
	v_and_b32_e32 v169, 0xffff0000, v204
	v_lshlrev_b32_e32 v178, 16, v212
	v_and_b32_e32 v179, 0xffff0000, v212
	v_lshlrev_b32_e32 v180, 16, v205
	v_and_b32_e32 v181, 0xffff0000, v205
	v_lshlrev_b32_e32 v244, 16, v213
	v_and_b32_e32 v245, 0xffff0000, v213
	v_pk_mul_f32 v[168:169], v[168:169], s[100:101] op_sel_hi:[1,0]
	v_pk_mul_f32 v[178:179], v[178:179], s[100:101] op_sel_hi:[1,0]
	v_pk_mul_f32 v[180:181], v[180:181], s[100:101] op_sel_hi:[1,0]
	v_pk_mul_f32 v[244:245], v[244:245], s[100:101] op_sel_hi:[1,0]
	v_min_f32_e32 v168, 0x42b80000, v168
	v_min_f32_e32 v169, 0x42b80000, v169
	v_min_f32_e32 v178, 0x42b80000, v178
	v_min_f32_e32 v179, 0x42b80000, v179
	v_min_f32_e32 v180, 0x42b80000, v180
	v_min_f32_e32 v181, 0x42b80000, v181
	v_min_f32_e32 v244, 0x42b80000, v244
	v_min_f32_e32 v245, 0x42b80000, v245
	v_exp_f32_e32 v168, v168
	v_exp_f32_e32 v169, v169
	v_exp_f32_e32 v178, v178
	v_exp_f32_e32 v179, v179
	v_exp_f32_e32 v180, v180
	v_exp_f32_e32 v181, v181
	v_exp_f32_e32 v244, v244
	v_exp_f32_e32 v245, v245
	s_nop 0
	v_add_f32_e32 v168, 1.0, v168
	v_add_f32_e32 v169, 1.0, v169
	v_add_f32_e32 v178, 1.0, v178
	v_add_f32_e32 v179, 1.0, v179
	v_add_f32_e32 v180, 1.0, v180
	v_add_f32_e32 v181, 1.0, v181
	v_add_f32_e32 v244, 1.0, v244
	v_add_f32_e32 v245, 1.0, v245
	v_rcp_f32_e32 v168, v168
	v_rcp_f32_e32 v169, v169
	v_rcp_f32_e32 v180, v180
	v_rcp_f32_e32 v181, v181
	s_nop 0
	v_pk_mul_f32 v[168:169], v[168:169], v[178:179]
	v_pk_mul_f32 v[180:181], v[180:181], v[244:245]
	v_pk_mul_f32 v[50:51], v[50:51], v[168:169]
	v_pk_mul_f32 v[52:53], v[52:53], v[180:181]
	v_lshlrev_b32_e32 v146, 16, v206
	v_and_b32_e32 v147, 0xffff0000, v206
	v_lshlrev_b32_e32 v148, 16, v214
	v_and_b32_e32 v149, 0xffff0000, v214
	v_lshlrev_b32_e32 v150, 16, v207
	v_and_b32_e32 v151, 0xffff0000, v207
	v_lshlrev_b32_e32 v152, 16, v215
	v_and_b32_e32 v153, 0xffff0000, v215
	v_pk_mul_f32 v[146:147], v[146:147], s[100:101] op_sel_hi:[1,0]
	v_pk_mul_f32 v[148:149], v[148:149], s[100:101] op_sel_hi:[1,0]
	v_pk_mul_f32 v[150:151], v[150:151], s[100:101] op_sel_hi:[1,0]
	v_pk_mul_f32 v[152:153], v[152:153], s[100:101] op_sel_hi:[1,0]
	v_min_f32_e32 v146, 0x42b80000, v146
	v_min_f32_e32 v147, 0x42b80000, v147
	v_min_f32_e32 v148, 0x42b80000, v148
	v_min_f32_e32 v149, 0x42b80000, v149
	v_min_f32_e32 v150, 0x42b80000, v150
	v_min_f32_e32 v151, 0x42b80000, v151
	v_min_f32_e32 v152, 0x42b80000, v152
	v_min_f32_e32 v153, 0x42b80000, v153
	v_exp_f32_e32 v146, v146
	v_exp_f32_e32 v147, v147
	v_exp_f32_e32 v148, v148
	v_exp_f32_e32 v149, v149
	v_exp_f32_e32 v150, v150
	v_exp_f32_e32 v151, v151
	v_exp_f32_e32 v152, v152
	v_exp_f32_e32 v153, v153
	s_nop 0
	v_add_f32_e32 v146, 1.0, v146
	v_add_f32_e32 v147, 1.0, v147
	v_add_f32_e32 v148, 1.0, v148
	v_add_f32_e32 v149, 1.0, v149
	v_add_f32_e32 v150, 1.0, v150
	v_add_f32_e32 v151, 1.0, v151
	v_add_f32_e32 v152, 1.0, v152
	v_add_f32_e32 v153, 1.0, v153
	v_rcp_f32_e32 v146, v146
	v_rcp_f32_e32 v147, v147
	v_rcp_f32_e32 v150, v150
	v_rcp_f32_e32 v151, v151
	s_nop 0
	v_pk_mul_f32 v[146:147], v[146:147], v[148:149]
	v_pk_mul_f32 v[150:151], v[150:151], v[152:153]
	v_pk_mul_f32 v[42:43], v[42:43], v[146:147]
	v_pk_mul_f32 v[44:45], v[44:45], v[150:151]
	global_load_dwordx4 v[200:203], v[144:145], off
	global_load_dwordx4 v[204:207], v[144:145], off offset:256
	global_load_dwordx4 v[208:211], v[144:145], off offset:2048
	global_load_dwordx4 v[212:215], v[144:145], off offset:2304
	s_waitcnt vmcnt(8)
; DI float bflo(unsigned w) { return __uint_as_float(w << 16); }
; DI float bfhi(unsigned w) { return __uint_as_float(w & 0xffff0000u); }
; DI float fexp(float x) { return __builtin_amdgcn_exp2f(x * LOG2E); }
; DI float frcp(float x) { return __builtin_amdgcn_rcpf(x); }
; DI float fsigmoid(float x) { return frcp(1.0f + fexp(-x)); }
;     DI void operator()(Acc& acc, const Unit& u, int wr, int wc, int fr, int fq) const {
;     ...
;                     for (int bj = 0; bj < 2; ++bj) g[ai][m][bj] = *(const u32x4*)(base + (size_t)(ai * 128 + m * 16) * NPJ + u.k * 1024 + bj * 128);
; #pragma unroll
;             for (int ai = 0; ai < 2; ++ai)
; #pragma unroll
;                 for (int m = 0; m < 4; ++m)
; #pragma unroll
;                     for (int bj = 0; bj < 2; ++bj) { const u32x4 q = g[ai][m][bj]; f32x4& v0 = acc[ai][bj][m][0]; f32x4& v1 = acc[ai][bj][m][1];
;                         v0[0] *= bflo(q.x); v0[1] *= bfhi(q.x); v0[2] *= bflo(q.y); v0[3] *= bfhi(q.y); v1[0] *= bflo(q.z); v1[1] *= bfhi(q.z); v1[2] *= bflo(q.w); v1[3] *= bfhi(q.w); }
	v_lshlrev_b32_e32 v146, 16, v216
	v_and_b32_e32 v147, 0xffff0000, v216
	v_lshlrev_b32_e32 v148, 16, v224
	v_and_b32_e32 v149, 0xffff0000, v224
	v_lshlrev_b32_e32 v150, 16, v217
	v_and_b32_e32 v151, 0xffff0000, v217
	v_lshlrev_b32_e32 v152, 16, v225
	v_and_b32_e32 v153, 0xffff0000, v225
	v_pk_mul_f32 v[146:147], v[146:147], s[100:101] op_sel_hi:[1,0]
	v_pk_mul_f32 v[148:149], v[148:149], s[100:101] op_sel_hi:[1,0]
	v_pk_mul_f32 v[150:151], v[150:151], s[100:101] op_sel_hi:[1,0]
	v_pk_mul_f32 v[152:153], v[152:153], s[100:101] op_sel_hi:[1,0]
	v_min_f32_e32 v146, 0x42b80000, v146
	v_min_f32_e32 v147, 0x42b80000, v147
	v_min_f32_e32 v148, 0x42b80000, v148
	v_min_f32_e32 v149, 0x42b80000, v149
	v_min_f32_e32 v150, 0x42b80000, v150
	v_min_f32_e32 v151, 0x42b80000, v151
	v_min_f32_e32 v152, 0x42b80000, v152
	v_min_f32_e32 v153, 0x42b80000, v153
	v_exp_f32_e32 v146, v146
	v_exp_f32_e32 v147, v147
	v_exp_f32_e32 v148, v148
	v_exp_f32_e32 v149, v149
	v_exp_f32_e32 v150, v150
	v_exp_f32_e32 v151, v151
	v_exp_f32_e32 v152, v152
	v_exp_f32_e32 v153, v153
	s_nop 0
	v_add_f32_e32 v146, 1.0, v146
	v_add_f32_e32 v147, 1.0, v147
	v_add_f32_e32 v148, 1.0, v148
	v_add_f32_e32 v149, 1.0, v149
	v_add_f32_e32 v150, 1.0, v150
	v_add_f32_e32 v151, 1.0, v151
	v_add_f32_e32 v152, 1.0, v152
	v_add_f32_e32 v153, 1.0, v153
	v_rcp_f32_e32 v146, v146
	v_rcp_f32_e32 v147, v147
	v_rcp_f32_e32 v150, v150
	v_rcp_f32_e32 v151, v151
	s_nop 0
	v_pk_mul_f32 v[146:147], v[146:147], v[148:149]
	v_pk_mul_f32 v[150:151], v[150:151], v[152:153]
	v_pk_mul_f32 v[54:55], v[54:55], v[146:147]
	v_pk_mul_f32 v[56:57], v[56:57], v[150:151]
	v_lshlrev_b32_e32 v168, 16, v218
	v_and_b32_e32 v169, 0xffff0000, v218
	v_lshlrev_b32_e32 v178, 16, v226
	v_and_b32_e32 v179, 0xffff0000, v226
	v_lshlrev_b32_e32 v180, 16, v219
	v_and_b32_e32 v181, 0xffff0000, v219
	v_lshlrev_b32_e32 v244, 16, v227
	v_and_b32_e32 v245, 0xffff0000, v227
	v_pk_mul_f32 v[168:169], v[168:169], s[100:101] op_sel_hi:[1,0]
	v_pk_mul_f32 v[178:179], v[178:179], s[100:101] op_sel_hi:[1,0]
	v_pk_mul_f32 v[180:181], v[180:181], s[100:101] op_sel_hi:[1,0]
	v_pk_mul_f32 v[244:245], v[244:245], s[100:101] op_sel_hi:[1,0]
	v_min_f32_e32 v168, 0x42b80000, v168
	v_min_f32_e32 v169, 0x42b80000, v169
	v_min_f32_e32 v178, 0x42b80000, v178
	v_min_f32_e32 v179, 0x42b80000, v179
	v_min_f32_e32 v180, 0x42b80000, v180
	v_min_f32_e32 v181, 0x42b80000, v181
	v_min_f32_e32 v244, 0x42b80000, v244
	v_min_f32_e32 v245, 0x42b80000, v245
	v_exp_f32_e32 v168, v168
	v_exp_f32_e32 v169, v169
	v_exp_f32_e32 v178, v178
	v_exp_f32_e32 v179, v179
	v_exp_f32_e32 v180, v180
	v_exp_f32_e32 v181, v181
	v_exp_f32_e32 v244, v244
	v_exp_f32_e32 v245, v245
	s_nop 0
	v_add_f32_e32 v168, 1.0, v168
	v_add_f32_e32 v169, 1.0, v169
	v_add_f32_e32 v178, 1.0, v178
	v_add_f32_e32 v179, 1.0, v179
	v_add_f32_e32 v180, 1.0, v180
	v_add_f32_e32 v181, 1.0, v181
	v_add_f32_e32 v244, 1.0, v244
	v_add_f32_e32 v245, 1.0, v245
	v_rcp_f32_e32 v168, v168
	v_rcp_f32_e32 v169, v169
	v_rcp_f32_e32 v180, v180
	v_rcp_f32_e32 v181, v181
	s_nop 0
	v_pk_mul_f32 v[168:169], v[168:169], v[178:179]
	v_pk_mul_f32 v[180:181], v[180:181], v[244:245]
	v_pk_mul_f32 v[46:47], v[46:47], v[168:169]
	v_pk_mul_f32 v[48:49], v[48:49], v[180:181]
	v_lshlrev_b32_e32 v168, 16, v220
	v_and_b32_e32 v169, 0xffff0000, v220
	v_lshlrev_b32_e32 v178, 16, v228
	v_and_b32_e32 v179, 0xffff0000, v228
	v_lshlrev_b32_e32 v180, 16, v221
	v_and_b32_e32 v181, 0xffff0000, v221
	v_lshlrev_b32_e32 v244, 16, v229
	v_and_b32_e32 v245, 0xffff0000, v229
	v_pk_mul_f32 v[168:169], v[168:169], s[100:101] op_sel_hi:[1,0]
	v_pk_mul_f32 v[178:179], v[178:179], s[100:101] op_sel_hi:[1,0]
	v_pk_mul_f32 v[180:181], v[180:181], s[100:101] op_sel_hi:[1,0]
	v_pk_mul_f32 v[244:245], v[244:245], s[100:101] op_sel_hi:[1,0]
	v_min_f32_e32 v168, 0x42b80000, v168
	v_min_f32_e32 v169, 0x42b80000, v169
	v_min_f32_e32 v178, 0x42b80000, v178
	v_min_f32_e32 v179, 0x42b80000, v179
	v_min_f32_e32 v180, 0x42b80000, v180
	v_min_f32_e32 v181, 0x42b80000, v181
	v_min_f32_e32 v244, 0x42b80000, v244
	v_min_f32_e32 v245, 0x42b80000, v245
	v_exp_f32_e32 v168, v168
	v_exp_f32_e32 v169, v169
	v_exp_f32_e32 v178, v178
	v_exp_f32_e32 v179, v179
	v_exp_f32_e32 v180, v180
	v_exp_f32_e32 v181, v181
	v_exp_f32_e32 v244, v244
	v_exp_f32_e32 v245, v245
	s_nop 0
	v_add_f32_e32 v168, 1.0, v168
	v_add_f32_e32 v169, 1.0, v169
	v_add_f32_e32 v178, 1.0, v178
	v_add_f32_e32 v179, 1.0, v179
	v_add_f32_e32 v180, 1.0, v180
	v_add_f32_e32 v181, 1.0, v181
	v_add_f32_e32 v244, 1.0, v244
	v_add_f32_e32 v245, 1.0, v245
	v_rcp_f32_e32 v168, v168
	v_rcp_f32_e32 v169, v169
	v_rcp_f32_e32 v180, v180
	v_rcp_f32_e32 v181, v181
	s_nop 0
	v_pk_mul_f32 v[168:169], v[168:169], v[178:179]
	v_pk_mul_f32 v[180:181], v[180:181], v[244:245]
	v_pk_mul_f32 v[34:35], v[34:35], v[168:169]
	v_pk_mul_f32 v[36:37], v[36:37], v[180:181]
	v_lshlrev_b32_e32 v146, 16, v222
	v_and_b32_e32 v147, 0xffff0000, v222
	v_lshlrev_b32_e32 v148, 16, v230
	v_and_b32_e32 v149, 0xffff0000, v230
	v_lshlrev_b32_e32 v150, 16, v223
	v_and_b32_e32 v151, 0xffff0000, v223
	v_lshlrev_b32_e32 v152, 16, v231
	v_and_b32_e32 v153, 0xffff0000, v231
	v_pk_mul_f32 v[146:147], v[146:147], s[100:101] op_sel_hi:[1,0]
	v_pk_mul_f32 v[148:149], v[148:149], s[100:101] op_sel_hi:[1,0]
	v_pk_mul_f32 v[150:151], v[150:151], s[100:101] op_sel_hi:[1,0]
	v_pk_mul_f32 v[152:153], v[152:153], s[100:101] op_sel_hi:[1,0]
	v_min_f32_e32 v146, 0x42b80000, v146
	v_min_f32_e32 v147, 0x42b80000, v147
	v_min_f32_e32 v148, 0x42b80000, v148
	v_min_f32_e32 v149, 0x42b80000, v149
	v_min_f32_e32 v150, 0x42b80000, v150
	v_min_f32_e32 v151, 0x42b80000, v151
	v_min_f32_e32 v152, 0x42b80000, v152
	v_min_f32_e32 v153, 0x42b80000, v153
	v_exp_f32_e32 v146, v146
	v_exp_f32_e32 v147, v147
	v_exp_f32_e32 v148, v148
	v_exp_f32_e32 v149, v149
	v_exp_f32_e32 v150, v150
	v_exp_f32_e32 v151, v151
	v_exp_f32_e32 v152, v152
	v_exp_f32_e32 v153, v153
	s_nop 0
	v_add_f32_e32 v146, 1.0, v146
	v_add_f32_e32 v147, 1.0, v147
	v_add_f32_e32 v148, 1.0, v148
	v_add_f32_e32 v149, 1.0, v149
	v_add_f32_e32 v150, 1.0, v150
	v_add_f32_e32 v151, 1.0, v151
	v_add_f32_e32 v152, 1.0, v152
	v_add_f32_e32 v153, 1.0, v153
	v_rcp_f32_e32 v146, v146
	v_rcp_f32_e32 v147, v147
	v_rcp_f32_e32 v150, v150
	v_rcp_f32_e32 v151, v151
	s_nop 0
	v_pk_mul_f32 v[146:147], v[146:147], v[148:149]
	v_pk_mul_f32 v[150:151], v[150:151], v[152:153]
	v_pk_mul_f32 v[26:27], v[26:27], v[146:147]
	v_pk_mul_f32 v[28:29], v[28:29], v[150:151]
	s_waitcnt vmcnt(4)
; DI float bflo(unsigned w) { return __uint_as_float(w << 16); }
; DI float bfhi(unsigned w) { return __uint_as_float(w & 0xffff0000u); }
; DI float fexp(float x) { return __builtin_amdgcn_exp2f(x * LOG2E); }
; DI float frcp(float x) { return __builtin_amdgcn_rcpf(x); }
; DI float fsigmoid(float x) { return frcp(1.0f + fexp(-x)); }
;     DI void operator()(Acc& acc, const Unit& u, int wr, int wc, int fr, int fq) const {
;     ...
;                     for (int bj = 0; bj < 2; ++bj) g[ai][m][bj] = *(const u32x4*)(base + (size_t)(ai * 128 + m * 16) * NPJ + u.k * 1024 + bj * 128);
; #pragma unroll
;             for (int ai = 0; ai < 2; ++ai)
; #pragma unroll
;                 for (int m = 0; m < 4; ++m)
; #pragma unroll
;                     for (int bj = 0; bj < 2; ++bj) { const u32x4 q = g[ai][m][bj]; f32x4& v0 = acc[ai][bj][m][0]; f32x4& v1 = acc[ai][bj][m][1];
;                         v0[0] *= bflo(q.x); v0[1] *= bfhi(q.x); v0[2] *= bflo(q.y); v0[3] *= bfhi(q.y); v1[0] *= bflo(q.z); v1[1] *= bfhi(q.z); v1[2] *= bflo(q.w); v1[3] *= bfhi(q.w); }
	v_lshlrev_b32_e32 v146, 16, v184
	v_and_b32_e32 v147, 0xffff0000, v184
	v_lshlrev_b32_e32 v148, 16, v192
	v_and_b32_e32 v149, 0xffff0000, v192
	v_lshlrev_b32_e32 v150, 16, v185
	v_and_b32_e32 v151, 0xffff0000, v185
	v_lshlrev_b32_e32 v152, 16, v193
	v_and_b32_e32 v153, 0xffff0000, v193
	v_pk_mul_f32 v[146:147], v[146:147], s[100:101] op_sel_hi:[1,0]
	v_pk_mul_f32 v[148:149], v[148:149], s[100:101] op_sel_hi:[1,0]
	v_pk_mul_f32 v[150:151], v[150:151], s[100:101] op_sel_hi:[1,0]
	v_pk_mul_f32 v[152:153], v[152:153], s[100:101] op_sel_hi:[1,0]
	v_min_f32_e32 v146, 0x42b80000, v146
	v_min_f32_e32 v147, 0x42b80000, v147
	v_min_f32_e32 v148, 0x42b80000, v148
	v_min_f32_e32 v149, 0x42b80000, v149
	v_min_f32_e32 v150, 0x42b80000, v150
	v_min_f32_e32 v151, 0x42b80000, v151
	v_min_f32_e32 v152, 0x42b80000, v152
	v_min_f32_e32 v153, 0x42b80000, v153
	v_exp_f32_e32 v146, v146
	v_exp_f32_e32 v147, v147
	v_exp_f32_e32 v148, v148
	v_exp_f32_e32 v149, v149
	v_exp_f32_e32 v150, v150
	v_exp_f32_e32 v151, v151
	v_exp_f32_e32 v152, v152
	v_exp_f32_e32 v153, v153
	s_nop 0
	v_add_f32_e32 v146, 1.0, v146
	v_add_f32_e32 v147, 1.0, v147
	v_add_f32_e32 v148, 1.0, v148
	v_add_f32_e32 v149, 1.0, v149
	v_add_f32_e32 v150, 1.0, v150
	v_add_f32_e32 v151, 1.0, v151
	v_add_f32_e32 v152, 1.0, v152
	v_add_f32_e32 v153, 1.0, v153
	v_rcp_f32_e32 v146, v146
	v_rcp_f32_e32 v147, v147
	v_rcp_f32_e32 v150, v150
	v_rcp_f32_e32 v151, v151
	s_nop 0
	v_pk_mul_f32 v[146:147], v[146:147], v[148:149]
	v_pk_mul_f32 v[150:151], v[150:151], v[152:153]
	v_pk_mul_f32 v[38:39], v[38:39], v[146:147]
	v_pk_mul_f32 v[40:41], v[40:41], v[150:151]
	v_lshlrev_b32_e32 v168, 16, v186
	v_and_b32_e32 v169, 0xffff0000, v186
	v_lshlrev_b32_e32 v178, 16, v194
	v_and_b32_e32 v179, 0xffff0000, v194
	v_lshlrev_b32_e32 v180, 16, v187
	v_and_b32_e32 v181, 0xffff0000, v187
	v_lshlrev_b32_e32 v244, 16, v195
	v_and_b32_e32 v245, 0xffff0000, v195
	v_pk_mul_f32 v[168:169], v[168:169], s[100:101] op_sel_hi:[1,0]
	v_pk_mul_f32 v[178:179], v[178:179], s[100:101] op_sel_hi:[1,0]
	v_pk_mul_f32 v[180:181], v[180:181], s[100:101] op_sel_hi:[1,0]
	v_pk_mul_f32 v[244:245], v[244:245], s[100:101] op_sel_hi:[1,0]
	v_min_f32_e32 v168, 0x42b80000, v168
	v_min_f32_e32 v169, 0x42b80000, v169
	v_min_f32_e32 v178, 0x42b80000, v178
	v_min_f32_e32 v179, 0x42b80000, v179
	v_min_f32_e32 v180, 0x42b80000, v180
	v_min_f32_e32 v181, 0x42b80000, v181
	v_min_f32_e32 v244, 0x42b80000, v244
	v_min_f32_e32 v245, 0x42b80000, v245
	v_exp_f32_e32 v168, v168
	v_exp_f32_e32 v169, v169
	v_exp_f32_e32 v178, v178
	v_exp_f32_e32 v179, v179
	v_exp_f32_e32 v180, v180
	v_exp_f32_e32 v181, v181
	v_exp_f32_e32 v244, v244
	v_exp_f32_e32 v245, v245
	s_nop 0
	v_add_f32_e32 v168, 1.0, v168
	v_add_f32_e32 v169, 1.0, v169
	v_add_f32_e32 v178, 1.0, v178
	v_add_f32_e32 v179, 1.0, v179
	v_add_f32_e32 v180, 1.0, v180
	v_add_f32_e32 v181, 1.0, v181
	v_add_f32_e32 v244, 1.0, v244
	v_add_f32_e32 v245, 1.0, v245
	v_rcp_f32_e32 v168, v168
	v_rcp_f32_e32 v169, v169
	v_rcp_f32_e32 v180, v180
	v_rcp_f32_e32 v181, v181
	s_nop 0
	v_pk_mul_f32 v[168:169], v[168:169], v[178:179]
	v_pk_mul_f32 v[180:181], v[180:181], v[244:245]
	v_pk_mul_f32 v[30:31], v[30:31], v[168:169]
	v_pk_mul_f32 v[32:33], v[32:33], v[180:181]
	v_lshlrev_b32_e32 v168, 16, v188
	v_and_b32_e32 v169, 0xffff0000, v188
	v_lshlrev_b32_e32 v178, 16, v196
	v_and_b32_e32 v179, 0xffff0000, v196
	v_lshlrev_b32_e32 v180, 16, v189
	v_and_b32_e32 v181, 0xffff0000, v189
	v_lshlrev_b32_e32 v244, 16, v197
	v_and_b32_e32 v245, 0xffff0000, v197
	v_pk_mul_f32 v[168:169], v[168:169], s[100:101] op_sel_hi:[1,0]
	v_pk_mul_f32 v[178:179], v[178:179], s[100:101] op_sel_hi:[1,0]
	v_pk_mul_f32 v[180:181], v[180:181], s[100:101] op_sel_hi:[1,0]
	v_pk_mul_f32 v[244:245], v[244:245], s[100:101] op_sel_hi:[1,0]
	v_min_f32_e32 v168, 0x42b80000, v168
	v_min_f32_e32 v169, 0x42b80000, v169
	v_min_f32_e32 v178, 0x42b80000, v178
	v_min_f32_e32 v179, 0x42b80000, v179
	v_min_f32_e32 v180, 0x42b80000, v180
	v_min_f32_e32 v181, 0x42b80000, v181
	v_min_f32_e32 v244, 0x42b80000, v244
	v_min_f32_e32 v245, 0x42b80000, v245
	v_exp_f32_e32 v168, v168
	v_exp_f32_e32 v169, v169
	v_exp_f32_e32 v178, v178
	v_exp_f32_e32 v179, v179
	v_exp_f32_e32 v180, v180
	v_exp_f32_e32 v181, v181
	v_exp_f32_e32 v244, v244
	v_exp_f32_e32 v245, v245
	s_nop 0
	v_add_f32_e32 v168, 1.0, v168
	v_add_f32_e32 v169, 1.0, v169
	v_add_f32_e32 v178, 1.0, v178
	v_add_f32_e32 v179, 1.0, v179
	v_add_f32_e32 v180, 1.0, v180
	v_add_f32_e32 v181, 1.0, v181
	v_add_f32_e32 v244, 1.0, v244
	v_add_f32_e32 v245, 1.0, v245
	v_rcp_f32_e32 v168, v168
	v_rcp_f32_e32 v169, v169
	v_rcp_f32_e32 v180, v180
	v_rcp_f32_e32 v181, v181
	s_nop 0
	v_pk_mul_f32 v[168:169], v[168:169], v[178:179]
	v_pk_mul_f32 v[180:181], v[180:181], v[244:245]
	v_pk_mul_f32 v[18:19], v[18:19], v[168:169]
	v_pk_mul_f32 v[20:21], v[20:21], v[180:181]
	v_lshlrev_b32_e32 v146, 16, v190
	v_and_b32_e32 v147, 0xffff0000, v190
	v_lshlrev_b32_e32 v148, 16, v198
	v_and_b32_e32 v149, 0xffff0000, v198
	v_lshlrev_b32_e32 v150, 16, v191
	v_and_b32_e32 v151, 0xffff0000, v191
	v_lshlrev_b32_e32 v152, 16, v199
	v_and_b32_e32 v153, 0xffff0000, v199
	v_pk_mul_f32 v[146:147], v[146:147], s[100:101] op_sel_hi:[1,0]
	v_pk_mul_f32 v[148:149], v[148:149], s[100:101] op_sel_hi:[1,0]
	v_pk_mul_f32 v[150:151], v[150:151], s[100:101] op_sel_hi:[1,0]
	v_pk_mul_f32 v[152:153], v[152:153], s[100:101] op_sel_hi:[1,0]
	v_min_f32_e32 v146, 0x42b80000, v146
	v_min_f32_e32 v147, 0x42b80000, v147
	v_min_f32_e32 v148, 0x42b80000, v148
	v_min_f32_e32 v149, 0x42b80000, v149
	v_min_f32_e32 v150, 0x42b80000, v150
	v_min_f32_e32 v151, 0x42b80000, v151
	v_min_f32_e32 v152, 0x42b80000, v152
	v_min_f32_e32 v153, 0x42b80000, v153
	v_exp_f32_e32 v146, v146
	v_exp_f32_e32 v147, v147
	v_exp_f32_e32 v148, v148
	v_exp_f32_e32 v149, v149
	v_exp_f32_e32 v150, v150
	v_exp_f32_e32 v151, v151
	v_exp_f32_e32 v152, v152
	v_exp_f32_e32 v153, v153
	s_nop 0
	v_add_f32_e32 v146, 1.0, v146
	v_add_f32_e32 v147, 1.0, v147
	v_add_f32_e32 v148, 1.0, v148
	v_add_f32_e32 v149, 1.0, v149
	v_add_f32_e32 v150, 1.0, v150
	v_add_f32_e32 v151, 1.0, v151
	v_add_f32_e32 v152, 1.0, v152
	v_add_f32_e32 v153, 1.0, v153
	v_rcp_f32_e32 v146, v146
	v_rcp_f32_e32 v147, v147
	v_rcp_f32_e32 v150, v150
	v_rcp_f32_e32 v151, v151
	s_nop 0
	v_pk_mul_f32 v[146:147], v[146:147], v[148:149]
	v_pk_mul_f32 v[150:151], v[150:151], v[152:153]
	v_pk_mul_f32 v[10:11], v[10:11], v[146:147]
	v_pk_mul_f32 v[12:13], v[12:13], v[150:151]
	s_waitcnt vmcnt(0)
; DI float bflo(unsigned w) { return __uint_as_float(w << 16); }
; DI float bfhi(unsigned w) { return __uint_as_float(w & 0xffff0000u); }
; DI float fexp(float x) { return __builtin_amdgcn_exp2f(x * LOG2E); }
; DI float frcp(float x) { return __builtin_amdgcn_rcpf(x); }
; DI float fsigmoid(float x) { return frcp(1.0f + fexp(-x)); }
;     DI void operator()(Acc& acc, const Unit& u, int wr, int wc, int fr, int fq) const {
;     ...
;                     for (int bj = 0; bj < 2; ++bj) g[ai][m][bj] = *(const u32x4*)(base + (size_t)(ai * 128 + m * 16) * NPJ + u.k * 1024 + bj * 128);
; #pragma unroll
;             for (int ai = 0; ai < 2; ++ai)
; #pragma unroll
;                 for (int m = 0; m < 4; ++m)
; #pragma unroll
;                     for (int bj = 0; bj < 2; ++bj) { const u32x4 q = g[ai][m][bj]; f32x4& v0 = acc[ai][bj][m][0]; f32x4& v1 = acc[ai][bj][m][1];
;                         v0[0] *= bflo(q.x); v0[1] *= bfhi(q.x); v0[2] *= bflo(q.y); v0[3] *= bfhi(q.y); v1[0] *= bflo(q.z); v1[1] *= bfhi(q.z); v1[2] *= bflo(q.w); v1[3] *= bfhi(q.w); }
	v_lshlrev_b32_e32 v146, 16, v200
	v_and_b32_e32 v147, 0xffff0000, v200
	v_lshlrev_b32_e32 v148, 16, v208
	v_and_b32_e32 v149, 0xffff0000, v208
	v_lshlrev_b32_e32 v150, 16, v201
	v_and_b32_e32 v151, 0xffff0000, v201
	v_lshlrev_b32_e32 v152, 16, v209
	v_and_b32_e32 v153, 0xffff0000, v209
	v_pk_mul_f32 v[146:147], v[146:147], s[100:101] op_sel_hi:[1,0]
	v_pk_mul_f32 v[148:149], v[148:149], s[100:101] op_sel_hi:[1,0]
	v_pk_mul_f32 v[150:151], v[150:151], s[100:101] op_sel_hi:[1,0]
	v_pk_mul_f32 v[152:153], v[152:153], s[100:101] op_sel_hi:[1,0]
	v_min_f32_e32 v146, 0x42b80000, v146
	v_min_f32_e32 v147, 0x42b80000, v147
	v_min_f32_e32 v148, 0x42b80000, v148
	v_min_f32_e32 v149, 0x42b80000, v149
	v_min_f32_e32 v150, 0x42b80000, v150
	v_min_f32_e32 v151, 0x42b80000, v151
	v_min_f32_e32 v152, 0x42b80000, v152
	v_min_f32_e32 v153, 0x42b80000, v153
	v_exp_f32_e32 v146, v146
	v_exp_f32_e32 v147, v147
	v_exp_f32_e32 v148, v148
	v_exp_f32_e32 v149, v149
	v_exp_f32_e32 v150, v150
	v_exp_f32_e32 v151, v151
	v_exp_f32_e32 v152, v152
	v_exp_f32_e32 v153, v153
	s_nop 0
	v_add_f32_e32 v146, 1.0, v146
	v_add_f32_e32 v147, 1.0, v147
	v_add_f32_e32 v148, 1.0, v148
	v_add_f32_e32 v149, 1.0, v149
	v_add_f32_e32 v150, 1.0, v150
	v_add_f32_e32 v151, 1.0, v151
	v_add_f32_e32 v152, 1.0, v152
	v_add_f32_e32 v153, 1.0, v153
	v_rcp_f32_e32 v146, v146
	v_rcp_f32_e32 v147, v147
	v_rcp_f32_e32 v150, v150
	v_rcp_f32_e32 v151, v151
	s_nop 0
	v_pk_mul_f32 v[146:147], v[146:147], v[148:149]
	v_pk_mul_f32 v[150:151], v[150:151], v[152:153]
	v_pk_mul_f32 v[22:23], v[22:23], v[146:147]
	v_pk_mul_f32 v[24:25], v[24:25], v[150:151]
	v_lshlrev_b32_e32 v168, 16, v202
	v_and_b32_e32 v169, 0xffff0000, v202
	v_lshlrev_b32_e32 v178, 16, v210
	v_and_b32_e32 v179, 0xffff0000, v210
	v_lshlrev_b32_e32 v180, 16, v203
	v_and_b32_e32 v181, 0xffff0000, v203
	v_lshlrev_b32_e32 v244, 16, v211
	v_and_b32_e32 v245, 0xffff0000, v211
	v_pk_mul_f32 v[168:169], v[168:169], s[100:101] op_sel_hi:[1,0]
	v_pk_mul_f32 v[178:179], v[178:179], s[100:101] op_sel_hi:[1,0]
	v_pk_mul_f32 v[180:181], v[180:181], s[100:101] op_sel_hi:[1,0]
	v_pk_mul_f32 v[244:245], v[244:245], s[100:101] op_sel_hi:[1,0]
	v_min_f32_e32 v168, 0x42b80000, v168
	v_min_f32_e32 v169, 0x42b80000, v169
	v_min_f32_e32 v178, 0x42b80000, v178
	v_min_f32_e32 v179, 0x42b80000, v179
	v_min_f32_e32 v180, 0x42b80000, v180
	v_min_f32_e32 v181, 0x42b80000, v181
	v_min_f32_e32 v244, 0x42b80000, v244
	v_min_f32_e32 v245, 0x42b80000, v245
	v_exp_f32_e32 v168, v168
	v_exp_f32_e32 v169, v169
	v_exp_f32_e32 v178, v178
	v_exp_f32_e32 v179, v179
	v_exp_f32_e32 v180, v180
	v_exp_f32_e32 v181, v181
	v_exp_f32_e32 v244, v244
	v_exp_f32_e32 v245, v245
	s_nop 0
	v_add_f32_e32 v168, 1.0, v168
	v_add_f32_e32 v169, 1.0, v169
	v_add_f32_e32 v178, 1.0, v178
	v_add_f32_e32 v179, 1.0, v179
	v_add_f32_e32 v180, 1.0, v180
	v_add_f32_e32 v181, 1.0, v181
	v_add_f32_e32 v244, 1.0, v244
	v_add_f32_e32 v245, 1.0, v245
	v_rcp_f32_e32 v168, v168
	v_rcp_f32_e32 v169, v169
	v_rcp_f32_e32 v180, v180
	v_rcp_f32_e32 v181, v181
	s_nop 0
	v_pk_mul_f32 v[168:169], v[168:169], v[178:179]
	v_pk_mul_f32 v[180:181], v[180:181], v[244:245]
	v_pk_mul_f32 v[14:15], v[14:15], v[168:169]
	v_pk_mul_f32 v[16:17], v[16:17], v[180:181]
	v_lshlrev_b32_e32 v168, 16, v204
	v_and_b32_e32 v169, 0xffff0000, v204
	v_lshlrev_b32_e32 v178, 16, v212
	v_and_b32_e32 v179, 0xffff0000, v212
	v_lshlrev_b32_e32 v180, 16, v205
	v_and_b32_e32 v181, 0xffff0000, v205
	v_lshlrev_b32_e32 v244, 16, v213
	v_and_b32_e32 v245, 0xffff0000, v213
	v_pk_mul_f32 v[168:169], v[168:169], s[100:101] op_sel_hi:[1,0]
	v_pk_mul_f32 v[178:179], v[178:179], s[100:101] op_sel_hi:[1,0]
	v_pk_mul_f32 v[180:181], v[180:181], s[100:101] op_sel_hi:[1,0]
	v_pk_mul_f32 v[244:245], v[244:245], s[100:101] op_sel_hi:[1,0]
	v_min_f32_e32 v168, 0x42b80000, v168
	v_min_f32_e32 v169, 0x42b80000, v169
	v_min_f32_e32 v178, 0x42b80000, v178
	v_min_f32_e32 v179, 0x42b80000, v179
	v_min_f32_e32 v180, 0x42b80000, v180
	v_min_f32_e32 v181, 0x42b80000, v181
	v_min_f32_e32 v244, 0x42b80000, v244
	v_min_f32_e32 v245, 0x42b80000, v245
	v_exp_f32_e32 v168, v168
	v_exp_f32_e32 v169, v169
	v_exp_f32_e32 v178, v178
	v_exp_f32_e32 v179, v179
	v_exp_f32_e32 v180, v180
	v_exp_f32_e32 v181, v181
	v_exp_f32_e32 v244, v244
	v_exp_f32_e32 v245, v245
	s_nop 0
	v_add_f32_e32 v168, 1.0, v168
	v_add_f32_e32 v169, 1.0, v169
	v_add_f32_e32 v178, 1.0, v178
	v_add_f32_e32 v179, 1.0, v179
	v_add_f32_e32 v180, 1.0, v180
	v_add_f32_e32 v181, 1.0, v181
	v_add_f32_e32 v244, 1.0, v244
	v_add_f32_e32 v245, 1.0, v245
	v_rcp_f32_e32 v168, v168
	v_rcp_f32_e32 v169, v169
	v_rcp_f32_e32 v180, v180
	v_rcp_f32_e32 v181, v181
	s_nop 0
	v_pk_mul_f32 v[168:169], v[168:169], v[178:179]
	v_pk_mul_f32 v[180:181], v[180:181], v[244:245]
	v_pk_mul_f32 v[6:7], v[6:7], v[168:169]
	v_pk_mul_f32 v[8:9], v[8:9], v[180:181]
	v_lshlrev_b32_e32 v146, 16, v206
	v_and_b32_e32 v147, 0xffff0000, v206
	v_lshlrev_b32_e32 v148, 16, v214
	v_and_b32_e32 v149, 0xffff0000, v214
	v_lshlrev_b32_e32 v150, 16, v207
	v_and_b32_e32 v151, 0xffff0000, v207
	v_lshlrev_b32_e32 v152, 16, v215
	v_and_b32_e32 v153, 0xffff0000, v215
	v_pk_mul_f32 v[146:147], v[146:147], s[100:101] op_sel_hi:[1,0]
	v_pk_mul_f32 v[148:149], v[148:149], s[100:101] op_sel_hi:[1,0]
	v_pk_mul_f32 v[150:151], v[150:151], s[100:101] op_sel_hi:[1,0]
	v_pk_mul_f32 v[152:153], v[152:153], s[100:101] op_sel_hi:[1,0]
	v_min_f32_e32 v146, 0x42b80000, v146
	v_min_f32_e32 v147, 0x42b80000, v147
	v_min_f32_e32 v148, 0x42b80000, v148
	v_min_f32_e32 v149, 0x42b80000, v149
	v_min_f32_e32 v150, 0x42b80000, v150
	v_min_f32_e32 v151, 0x42b80000, v151
	v_min_f32_e32 v152, 0x42b80000, v152
	v_min_f32_e32 v153, 0x42b80000, v153
	v_exp_f32_e32 v146, v146
	v_exp_f32_e32 v147, v147
	v_exp_f32_e32 v148, v148
	v_exp_f32_e32 v149, v149
	v_exp_f32_e32 v150, v150
	v_exp_f32_e32 v151, v151
	v_exp_f32_e32 v152, v152
	v_exp_f32_e32 v153, v153
	s_nop 0
	v_add_f32_e32 v146, 1.0, v146
	v_add_f32_e32 v147, 1.0, v147
	v_add_f32_e32 v148, 1.0, v148
	v_add_f32_e32 v149, 1.0, v149
	v_add_f32_e32 v150, 1.0, v150
	v_add_f32_e32 v151, 1.0, v151
	v_add_f32_e32 v152, 1.0, v152
	v_add_f32_e32 v153, 1.0, v153
	v_rcp_f32_e32 v146, v146
	v_rcp_f32_e32 v147, v147
	v_rcp_f32_e32 v150, v150
	v_rcp_f32_e32 v151, v151
	s_nop 0
	v_pk_mul_f32 v[146:147], v[146:147], v[148:149]
	v_pk_mul_f32 v[150:151], v[150:151], v[152:153]
	v_pk_mul_f32 v[2:3], v[2:3], v[146:147]
	v_pk_mul_f32 v[4:5], v[4:5], v[150:151]
	s_branch .Lup3_tail
; DI float bflo(unsigned w) { return __uint_as_float(w << 16); }
; DI float bfhi(unsigned w) { return __uint_as_float(w & 0xffff0000u); }
; DI u32x4 pack8(f32x4 a, f32x4 b) { u32x4 w; w.x = pk2(a[0], a[1]); w.y = pk2(a[2], a[3]); w.z = pk2(b[0], b[1]); w.w = pk2(b[2], b[3]); return w; }
;     DI void operator()(Acc& acc, const Unit& u, int wr, int wc, int fr, int fq) const {
;     ...
;                     for (int bj = 0; bj < 2; ++bj) g[ai][m][bj] = *(const u32x4*)(base + (size_t)(ai * 128 + m * 16) * NPJ + u.k * 1024 + bj * 128);
; #pragma unroll
;             for (int ai = 0; ai < 2; ++ai)
; #pragma unroll
;                 for (int m = 0; m < 4; ++m)
; #pragma unroll
;                     for (int bj = 0; bj < 2; ++bj) { const u32x4 q = g[ai][m][bj]; f32x4& v0 = acc[ai][bj][m][0]; f32x4& v1 = acc[ai][bj][m][1];
;                         v0[0] *= bflo(q.x); v0[1] *= bfhi(q.x); v0[2] *= bflo(q.y); v0[3] *= bfhi(q.y); v1[0] *= bflo(q.z); v1[1] *= bfhi(q.z); v1[2] *= bflo(q.w); v1[3] *= bfhi(q.w); }
;         }
;         if (u.k > 0) {
;             u32x4 g[2][4][2];
; #pragma unroll
;             for (int ai = 0; ai < 2; ++ai)
; #pragma unroll
;                 for (int m = 0; m < 4; ++m)
; #pragma unroll
;                     for (int bj = 0; bj < 2; ++bj) g[ai][m][bj] = *(const u32x4*)(base + (size_t)(ai * 128 + m * 16) * NPJ + bj * 128);
; #pragma unroll
;             for (int ai = 0; ai < 2; ++ai)
; #pragma unroll
;                 for (int m = 0; m < 4; ++m)
; #pragma unroll
;                     for (int bj = 0; bj < 2; ++bj) { const u32x4 q = g[ai][m][bj]; f32x4& v0 = acc[ai][bj][m][0]; f32x4& v1 = acc[ai][bj][m][1];
;                         v0[0] += bflo(q.x); v0[1] += bfhi(q.x); v0[2] += bflo(q.y); v0[3] += bfhi(q.y); v1[0] += bflo(q.z); v1[1] += bfhi(q.z); v1[2] += bflo(q.w); v1[3] += bfhi(q.w); }
;         }
;         if (!dry) {
; #pragma unroll
;             for (int ai = 0; ai < 2; ++ai)
; #pragma unroll
;                 for (int m = 0; m < 4; ++m)
; #pragma unroll
;                     for (int bj = 0; bj < 2; ++bj) *(u32x4*)(base + (size_t)(ai * 128 + m * 16) * NPJ + bj * 128) = pack8(acc[ai][bj][m][0], acc[ai][bj][m][1]);
.Lup3_final:
	global_load_dwordx4 v[184:187], v[130:131], off
	global_load_dwordx4 v[188:191], v[130:131], off offset:256
	global_load_dwordx4 v[192:195], v[132:133], off
	global_load_dwordx4 v[196:199], v[132:133], off offset:256
	global_load_dwordx4 v[200:203], v[134:135], off
	global_load_dwordx4 v[204:207], v[134:135], off offset:256
	global_load_dwordx4 v[208:211], v[136:137], off
	global_load_dwordx4 v[212:215], v[136:137], off offset:256
	global_load_dwordx4 v[216:219], v[138:139], off
	global_load_dwordx4 v[220:223], v[138:139], off offset:256
	global_load_dwordx4 v[224:227], v[140:141], off
	global_load_dwordx4 v[228:231], v[140:141], off offset:256
	s_waitcnt vmcnt(10)
	v_lshlrev_b32_e32 v146, 16, v184
	v_and_b32_e32 v147, 0xffff0000, v184
	v_lshlrev_b32_e32 v148, 16, v185
	v_and_b32_e32 v149, 0xffff0000, v185
	v_lshlrev_b32_e32 v150, 16, v186
	v_and_b32_e32 v151, 0xffff0000, v186
	v_lshlrev_b32_e32 v152, 16, v187
	v_and_b32_e32 v153, 0xffff0000, v187
	v_pk_mul_f32 v[146:147], v[146:147], s[100:101] op_sel_hi:[1,0]
	v_pk_mul_f32 v[148:149], v[148:149], s[100:101] op_sel_hi:[1,0]
	v_pk_mul_f32 v[150:151], v[150:151], s[100:101] op_sel_hi:[1,0]
	v_pk_mul_f32 v[152:153], v[152:153], s[100:101] op_sel_hi:[1,0]
	v_min_f32_e32 v146, 0x42b80000, v146
	v_min_f32_e32 v147, 0x42b80000, v147
	v_min_f32_e32 v148, 0x42b80000, v148
	v_min_f32_e32 v149, 0x42b80000, v149
	v_min_f32_e32 v150, 0x42b80000, v150
	v_min_f32_e32 v151, 0x42b80000, v151
	v_min_f32_e32 v152, 0x42b80000, v152
	v_min_f32_e32 v153, 0x42b80000, v153
	v_exp_f32_e32 v146, v146
	v_exp_f32_e32 v147, v147
	v_exp_f32_e32 v148, v148
	v_exp_f32_e32 v149, v149
	v_exp_f32_e32 v150, v150
	v_exp_f32_e32 v151, v151
	v_exp_f32_e32 v152, v152
	v_exp_f32_e32 v153, v153
	s_nop 0
	v_add_f32_e32 v146, 1.0, v146
	v_add_f32_e32 v147, 1.0, v147
	v_add_f32_e32 v148, 1.0, v148
	v_add_f32_e32 v149, 1.0, v149
	v_add_f32_e32 v150, 1.0, v150
	v_add_f32_e32 v151, 1.0, v151
	v_add_f32_e32 v152, 1.0, v152
	v_add_f32_e32 v153, 1.0, v153
	v_rcp_f32_e32 v146, v146
	v_rcp_f32_e32 v147, v147
	v_rcp_f32_e32 v148, v148
	v_rcp_f32_e32 v149, v149
	v_rcp_f32_e32 v150, v150
	v_rcp_f32_e32 v151, v151
	v_rcp_f32_e32 v152, v152
	v_rcp_f32_e32 v153, v153
	s_nop 0
	v_pk_mul_f32 v[126:127], v[126:127], v[146:147]
	v_pk_mul_f32 v[128:129], v[128:129], v[148:149]
	v_pk_mul_f32 v[122:123], v[122:123], v[150:151]
	v_pk_mul_f32 v[124:125], v[124:125], v[152:153]
	v_cvt_pk_bf16_f32 v184, v126, v127
	v_cvt_pk_bf16_f32 v185, v128, v129
	v_cvt_pk_bf16_f32 v186, v122, v123
	v_cvt_pk_bf16_f32 v187, v124, v125
	v_lshlrev_b32_e32 v168, 16, v188
	v_and_b32_e32 v169, 0xffff0000, v188
	v_lshlrev_b32_e32 v178, 16, v189
	v_and_b32_e32 v179, 0xffff0000, v189
	v_lshlrev_b32_e32 v180, 16, v190
	v_and_b32_e32 v181, 0xffff0000, v190
	v_lshlrev_b32_e32 v244, 16, v191
	v_and_b32_e32 v245, 0xffff0000, v191
	v_pk_mul_f32 v[168:169], v[168:169], s[100:101] op_sel_hi:[1,0]
	v_pk_mul_f32 v[178:179], v[178:179], s[100:101] op_sel_hi:[1,0]
	v_pk_mul_f32 v[180:181], v[180:181], s[100:101] op_sel_hi:[1,0]
	v_pk_mul_f32 v[244:245], v[244:245], s[100:101] op_sel_hi:[1,0]
	v_min_f32_e32 v168, 0x42b80000, v168
	v_min_f32_e32 v169, 0x42b80000, v169
	v_min_f32_e32 v178, 0x42b80000, v178
	v_min_f32_e32 v179, 0x42b80000, v179
	v_min_f32_e32 v180, 0x42b80000, v180
	v_min_f32_e32 v181, 0x42b80000, v181
	v_min_f32_e32 v244, 0x42b80000, v244
	v_min_f32_e32 v245, 0x42b80000, v245
	v_exp_f32_e32 v168, v168
	v_exp_f32_e32 v169, v169
	v_exp_f32_e32 v178, v178
	v_exp_f32_e32 v179, v179
	v_exp_f32_e32 v180, v180
	v_exp_f32_e32 v181, v181
	v_exp_f32_e32 v244, v244
	v_exp_f32_e32 v245, v245
	s_nop 0
	v_add_f32_e32 v168, 1.0, v168
	v_add_f32_e32 v169, 1.0, v169
	v_add_f32_e32 v178, 1.0, v178
	v_add_f32_e32 v179, 1.0, v179
	v_add_f32_e32 v180, 1.0, v180
	v_add_f32_e32 v181, 1.0, v181
	v_add_f32_e32 v244, 1.0, v244
	v_add_f32_e32 v245, 1.0, v245
	v_rcp_f32_e32 v168, v168
	v_rcp_f32_e32 v169, v169
	v_rcp_f32_e32 v178, v178
	v_rcp_f32_e32 v179, v179
	v_rcp_f32_e32 v180, v180
	v_rcp_f32_e32 v181, v181
	v_rcp_f32_e32 v244, v244
	v_rcp_f32_e32 v245, v245
	s_nop 0
	v_pk_mul_f32 v[114:115], v[114:115], v[168:169]
	v_pk_mul_f32 v[116:117], v[116:117], v[178:179]
	v_pk_mul_f32 v[110:111], v[110:111], v[180:181]
	v_pk_mul_f32 v[112:113], v[112:113], v[244:245]
	v_cvt_pk_bf16_f32 v188, v114, v115
	v_cvt_pk_bf16_f32 v189, v116, v117
	v_cvt_pk_bf16_f32 v190, v110, v111
	v_cvt_pk_bf16_f32 v191, v112, v113
	global_store_dwordx4 v[130:131], v[184:187], off offset:-4096
	global_store_dwordx4 v[130:131], v[188:191], off offset:-3840
	s_nop 1
	global_load_dwordx4 v[184:187], v[142:143], off
	global_load_dwordx4 v[188:191], v[142:143], off offset:256
	s_waitcnt vmcnt(12)
; DI float bflo(unsigned w) { return __uint_as_float(w << 16); }
; DI float bfhi(unsigned w) { return __uint_as_float(w & 0xffff0000u); }
; DI u32x4 pack8(f32x4 a, f32x4 b) { u32x4 w; w.x = pk2(a[0], a[1]); w.y = pk2(a[2], a[3]); w.z = pk2(b[0], b[1]); w.w = pk2(b[2], b[3]); return w; }
;     DI void operator()(Acc& acc, const Unit& u, int wr, int wc, int fr, int fq) const {
;     ...
;                     for (int bj = 0; bj < 2; ++bj) g[ai][m][bj] = *(const u32x4*)(base + (size_t)(ai * 128 + m * 16) * NPJ + u.k * 1024 + bj * 128);
; #pragma unroll
;             for (int ai = 0; ai < 2; ++ai)
; #pragma unroll
;                 for (int m = 0; m < 4; ++m)
; #pragma unroll
;                     for (int bj = 0; bj < 2; ++bj) { const u32x4 q = g[ai][m][bj]; f32x4& v0 = acc[ai][bj][m][0]; f32x4& v1 = acc[ai][bj][m][1];
;                         v0[0] *= bflo(q.x); v0[1] *= bfhi(q.x); v0[2] *= bflo(q.y); v0[3] *= bfhi(q.y); v1[0] *= bflo(q.z); v1[1] *= bfhi(q.z); v1[2] *= bflo(q.w); v1[3] *= bfhi(q.w); }
;         }
;         if (u.k > 0) {
;             u32x4 g[2][4][2];
; #pragma unroll
;             for (int ai = 0; ai < 2; ++ai)
; #pragma unroll
;                 for (int m = 0; m < 4; ++m)
; #pragma unroll
;                     for (int bj = 0; bj < 2; ++bj) g[ai][m][bj] = *(const u32x4*)(base + (size_t)(ai * 128 + m * 16) * NPJ + bj * 128);
; #pragma unroll
;             for (int ai = 0; ai < 2; ++ai)
; #pragma unroll
;                 for (int m = 0; m < 4; ++m)
; #pragma unroll
;                     for (int bj = 0; bj < 2; ++bj) { const u32x4 q = g[ai][m][bj]; f32x4& v0 = acc[ai][bj][m][0]; f32x4& v1 = acc[ai][bj][m][1];
;                         v0[0] += bflo(q.x); v0[1] += bfhi(q.x); v0[2] += bflo(q.y); v0[3] += bfhi(q.y); v1[0] += bflo(q.z); v1[1] += bfhi(q.z); v1[2] += bflo(q.w); v1[3] += bfhi(q.w); }
;         }
;         if (!dry) {
; #pragma unroll
;             for (int ai = 0; ai < 2; ++ai)
; #pragma unroll
;                 for (int m = 0; m < 4; ++m)
; #pragma unroll
;                     for (int bj = 0; bj < 2; ++bj) *(u32x4*)(base + (size_t)(ai * 128 + m * 16) * NPJ + bj * 128) = pack8(acc[ai][bj][m][0], acc[ai][bj][m][1]);
	v_lshlrev_b32_e32 v146, 16, v192
	v_and_b32_e32 v147, 0xffff0000, v192
	v_lshlrev_b32_e32 v148, 16, v193
	v_and_b32_e32 v149, 0xffff0000, v193
	v_lshlrev_b32_e32 v150, 16, v194
	v_and_b32_e32 v151, 0xffff0000, v194
	v_lshlrev_b32_e32 v152, 16, v195
	v_and_b32_e32 v153, 0xffff0000, v195
	v_pk_mul_f32 v[146:147], v[146:147], s[100:101] op_sel_hi:[1,0]
	v_pk_mul_f32 v[148:149], v[148:149], s[100:101] op_sel_hi:[1,0]
	v_pk_mul_f32 v[150:151], v[150:151], s[100:101] op_sel_hi:[1,0]
	v_pk_mul_f32 v[152:153], v[152:153], s[100:101] op_sel_hi:[1,0]
	v_min_f32_e32 v146, 0x42b80000, v146
	v_min_f32_e32 v147, 0x42b80000, v147
	v_min_f32_e32 v148, 0x42b80000, v148
	v_min_f32_e32 v149, 0x42b80000, v149
	v_min_f32_e32 v150, 0x42b80000, v150
	v_min_f32_e32 v151, 0x42b80000, v151
	v_min_f32_e32 v152, 0x42b80000, v152
	v_min_f32_e32 v153, 0x42b80000, v153
	v_exp_f32_e32 v146, v146
	v_exp_f32_e32 v147, v147
	v_exp_f32_e32 v148, v148
	v_exp_f32_e32 v149, v149
	v_exp_f32_e32 v150, v150
	v_exp_f32_e32 v151, v151
	v_exp_f32_e32 v152, v152
	v_exp_f32_e32 v153, v153
	s_nop 0
	v_add_f32_e32 v146, 1.0, v146
	v_add_f32_e32 v147, 1.0, v147
	v_add_f32_e32 v148, 1.0, v148
	v_add_f32_e32 v149, 1.0, v149
	v_add_f32_e32 v150, 1.0, v150
	v_add_f32_e32 v151, 1.0, v151
	v_add_f32_e32 v152, 1.0, v152
	v_add_f32_e32 v153, 1.0, v153
	v_rcp_f32_e32 v146, v146
	v_rcp_f32_e32 v147, v147
	v_rcp_f32_e32 v148, v148
	v_rcp_f32_e32 v149, v149
	v_rcp_f32_e32 v150, v150
	v_rcp_f32_e32 v151, v151
	v_rcp_f32_e32 v152, v152
	v_rcp_f32_e32 v153, v153
	s_nop 0
	v_pk_mul_f32 v[118:119], v[118:119], v[146:147]
	v_pk_mul_f32 v[120:121], v[120:121], v[148:149]
	v_pk_mul_f32 v[106:107], v[106:107], v[150:151]
	v_pk_mul_f32 v[108:109], v[108:109], v[152:153]
	v_cvt_pk_bf16_f32 v192, v118, v119
	v_cvt_pk_bf16_f32 v193, v120, v121
	v_cvt_pk_bf16_f32 v194, v106, v107
	v_cvt_pk_bf16_f32 v195, v108, v109
	v_lshlrev_b32_e32 v168, 16, v196
	v_and_b32_e32 v169, 0xffff0000, v196
	v_lshlrev_b32_e32 v178, 16, v197
	v_and_b32_e32 v179, 0xffff0000, v197
	v_lshlrev_b32_e32 v180, 16, v198
	v_and_b32_e32 v181, 0xffff0000, v198
	v_lshlrev_b32_e32 v244, 16, v199
	v_and_b32_e32 v245, 0xffff0000, v199
	v_pk_mul_f32 v[168:169], v[168:169], s[100:101] op_sel_hi:[1,0]
	v_pk_mul_f32 v[178:179], v[178:179], s[100:101] op_sel_hi:[1,0]
	v_pk_mul_f32 v[180:181], v[180:181], s[100:101] op_sel_hi:[1,0]
	v_pk_mul_f32 v[244:245], v[244:245], s[100:101] op_sel_hi:[1,0]
	v_min_f32_e32 v168, 0x42b80000, v168
	v_min_f32_e32 v169, 0x42b80000, v169
	v_min_f32_e32 v178, 0x42b80000, v178
	v_min_f32_e32 v179, 0x42b80000, v179
	v_min_f32_e32 v180, 0x42b80000, v180
	v_min_f32_e32 v181, 0x42b80000, v181
	v_min_f32_e32 v244, 0x42b80000, v244
	v_min_f32_e32 v245, 0x42b80000, v245
	v_exp_f32_e32 v168, v168
	v_exp_f32_e32 v169, v169
	v_exp_f32_e32 v178, v178
	v_exp_f32_e32 v179, v179
	v_exp_f32_e32 v180, v180
	v_exp_f32_e32 v181, v181
	v_exp_f32_e32 v244, v244
	v_exp_f32_e32 v245, v245
	s_nop 0
	v_add_f32_e32 v168, 1.0, v168
	v_add_f32_e32 v169, 1.0, v169
	v_add_f32_e32 v178, 1.0, v178
	v_add_f32_e32 v179, 1.0, v179
	v_add_f32_e32 v180, 1.0, v180
	v_add_f32_e32 v181, 1.0, v181
	v_add_f32_e32 v244, 1.0, v244
	v_add_f32_e32 v245, 1.0, v245
	v_rcp_f32_e32 v168, v168
	v_rcp_f32_e32 v169, v169
	v_rcp_f32_e32 v178, v178
	v_rcp_f32_e32 v179, v179
	v_rcp_f32_e32 v180, v180
	v_rcp_f32_e32 v181, v181
	v_rcp_f32_e32 v244, v244
	v_rcp_f32_e32 v245, v245
	s_nop 0
	v_pk_mul_f32 v[98:99], v[98:99], v[168:169]
	v_pk_mul_f32 v[100:101], v[100:101], v[178:179]
	v_pk_mul_f32 v[90:91], v[90:91], v[180:181]
	v_pk_mul_f32 v[92:93], v[92:93], v[244:245]
	v_cvt_pk_bf16_f32 v196, v98, v99
	v_cvt_pk_bf16_f32 v197, v100, v101
	v_cvt_pk_bf16_f32 v198, v90, v91
	v_cvt_pk_bf16_f32 v199, v92, v93
	global_store_dwordx4 v[132:133], v[192:195], off offset:-4096
	global_store_dwordx4 v[132:133], v[196:199], off offset:-3840
	s_nop 1
	global_load_dwordx4 v[192:195], v[144:145], off
	global_load_dwordx4 v[196:199], v[144:145], off offset:256
	s_waitcnt vmcnt(14)
	v_lshlrev_b32_e32 v146, 16, v200
	v_and_b32_e32 v147, 0xffff0000, v200
	v_lshlrev_b32_e32 v148, 16, v201
	v_and_b32_e32 v149, 0xffff0000, v201
	v_lshlrev_b32_e32 v150, 16, v202
	v_and_b32_e32 v151, 0xffff0000, v202
	v_lshlrev_b32_e32 v152, 16, v203
	v_and_b32_e32 v153, 0xffff0000, v203
	v_pk_mul_f32 v[146:147], v[146:147], s[100:101] op_sel_hi:[1,0]
	v_pk_mul_f32 v[148:149], v[148:149], s[100:101] op_sel_hi:[1,0]
	v_pk_mul_f32 v[150:151], v[150:151], s[100:101] op_sel_hi:[1,0]
	v_pk_mul_f32 v[152:153], v[152:153], s[100:101] op_sel_hi:[1,0]
	v_min_f32_e32 v146, 0x42b80000, v146
	v_min_f32_e32 v147, 0x42b80000, v147
	v_min_f32_e32 v148, 0x42b80000, v148
	v_min_f32_e32 v149, 0x42b80000, v149
	v_min_f32_e32 v150, 0x42b80000, v150
	v_min_f32_e32 v151, 0x42b80000, v151
	v_min_f32_e32 v152, 0x42b80000, v152
	v_min_f32_e32 v153, 0x42b80000, v153
	v_exp_f32_e32 v146, v146
	v_exp_f32_e32 v147, v147
	v_exp_f32_e32 v148, v148
	v_exp_f32_e32 v149, v149
	v_exp_f32_e32 v150, v150
	v_exp_f32_e32 v151, v151
	v_exp_f32_e32 v152, v152
	v_exp_f32_e32 v153, v153
	s_nop 0
	v_add_f32_e32 v146, 1.0, v146
	v_add_f32_e32 v147, 1.0, v147
	v_add_f32_e32 v148, 1.0, v148
	v_add_f32_e32 v149, 1.0, v149
	v_add_f32_e32 v150, 1.0, v150
	v_add_f32_e32 v151, 1.0, v151
	v_add_f32_e32 v152, 1.0, v152
	v_add_f32_e32 v153, 1.0, v153
	v_rcp_f32_e32 v146, v146
	v_rcp_f32_e32 v147, v147
	v_rcp_f32_e32 v148, v148
	v_rcp_f32_e32 v149, v149
	v_rcp_f32_e32 v150, v150
	v_rcp_f32_e32 v151, v151
	v_rcp_f32_e32 v152, v152
	v_rcp_f32_e32 v153, v153
	s_nop 0
	v_pk_mul_f32 v[102:103], v[102:103], v[146:147]
	v_pk_mul_f32 v[104:105], v[104:105], v[148:149]
; DI float bflo(unsigned w) { return __uint_as_float(w << 16); }
; DI float bfhi(unsigned w) { return __uint_as_float(w & 0xffff0000u); }
; DI u32x4 pack8(f32x4 a, f32x4 b) { u32x4 w; w.x = pk2(a[0], a[1]); w.y = pk2(a[2], a[3]); w.z = pk2(b[0], b[1]); w.w = pk2(b[2], b[3]); return w; }
; DI float fexp2(float x) { return __builtin_amdgcn_exp2f(x); }
; DI float fexp(float x) { return __builtin_amdgcn_exp2f(x * LOG2E); }
; DI float frcp(float x) { return __builtin_amdgcn_rcpf(x); }
; DI float fsigmoid(float x) { return frcp(1.0f + fexp(-x)); }
;     DI void operator()(Acc& acc, const Unit& u, int wr, int wc, int fr, int fq) const {
;     ...
;                     for (int bj = 0; bj < 2; ++bj) { const u32x4 q = g[ai][m][bj]; f32x4& v0 = acc[ai][bj][m][0]; f32x4& v1 = acc[ai][bj][m][1];
;                         v0[0] *= bflo(q.x); v0[1] *= bfhi(q.x); v0[2] *= bflo(q.y); v0[3] *= bfhi(q.y); v1[0] *= bflo(q.z); v1[1] *= bfhi(q.z); v1[2] *= bflo(q.w); v1[3] *= bfhi(q.w); }
;     ...
;                     for (int bj = 0; bj < 2; ++bj) *(u32x4*)(base + (size_t)(ai * 128 + m * 16) * NPJ + bj * 128) = pack8(acc[ai][bj][m][0], acc[ai][bj][m][1]);
	v_pk_mul_f32 v[94:95], v[94:95], v[150:151]
	v_pk_mul_f32 v[96:97], v[96:97], v[152:153]
	v_cvt_pk_bf16_f32 v200, v102, v103
	v_cvt_pk_bf16_f32 v201, v104, v105
	v_cvt_pk_bf16_f32 v202, v94, v95
	v_cvt_pk_bf16_f32 v203, v96, v97
	v_lshlrev_b32_e32 v168, 16, v204
	v_and_b32_e32 v169, 0xffff0000, v204
	v_lshlrev_b32_e32 v178, 16, v205
	v_and_b32_e32 v179, 0xffff0000, v205
	v_lshlrev_b32_e32 v180, 16, v206
	v_and_b32_e32 v181, 0xffff0000, v206
	v_lshlrev_b32_e32 v244, 16, v207
	v_and_b32_e32 v245, 0xffff0000, v207
	v_pk_mul_f32 v[168:169], v[168:169], s[100:101] op_sel_hi:[1,0]
	v_pk_mul_f32 v[178:179], v[178:179], s[100:101] op_sel_hi:[1,0]
	v_pk_mul_f32 v[180:181], v[180:181], s[100:101] op_sel_hi:[1,0]
	v_pk_mul_f32 v[244:245], v[244:245], s[100:101] op_sel_hi:[1,0]
	v_min_f32_e32 v168, 0x42b80000, v168
	v_min_f32_e32 v169, 0x42b80000, v169
	v_min_f32_e32 v178, 0x42b80000, v178
	v_min_f32_e32 v179, 0x42b80000, v179
	v_min_f32_e32 v180, 0x42b80000, v180
	v_min_f32_e32 v181, 0x42b80000, v181
	v_min_f32_e32 v244, 0x42b80000, v244
	v_min_f32_e32 v245, 0x42b80000, v245
	v_exp_f32_e32 v168, v168
	v_exp_f32_e32 v169, v169
	v_exp_f32_e32 v178, v178
	v_exp_f32_e32 v179, v179
	v_exp_f32_e32 v180, v180
	v_exp_f32_e32 v181, v181
	v_exp_f32_e32 v244, v244
	v_exp_f32_e32 v245, v245
	s_nop 0
	v_add_f32_e32 v168, 1.0, v168
	v_add_f32_e32 v169, 1.0, v169
	v_add_f32_e32 v178, 1.0, v178
	v_add_f32_e32 v179, 1.0, v179
	v_add_f32_e32 v180, 1.0, v180
	v_add_f32_e32 v181, 1.0, v181
	v_add_f32_e32 v244, 1.0, v244
	v_add_f32_e32 v245, 1.0, v245
	v_rcp_f32_e32 v168, v168
	v_rcp_f32_e32 v169, v169
	v_rcp_f32_e32 v178, v178
	v_rcp_f32_e32 v179, v179
	v_rcp_f32_e32 v180, v180
	v_rcp_f32_e32 v181, v181
	v_rcp_f32_e32 v244, v244
	v_rcp_f32_e32 v245, v245
	s_nop 0
	v_pk_mul_f32 v[82:83], v[82:83], v[168:169]
	v_pk_mul_f32 v[84:85], v[84:85], v[178:179]
	v_pk_mul_f32 v[74:75], v[74:75], v[180:181]
	v_pk_mul_f32 v[76:77], v[76:77], v[244:245]
	v_cvt_pk_bf16_f32 v204, v82, v83
	v_cvt_pk_bf16_f32 v205, v84, v85
	v_cvt_pk_bf16_f32 v206, v74, v75
	v_cvt_pk_bf16_f32 v207, v76, v77
	global_store_dwordx4 v[134:135], v[200:203], off offset:-4096
	global_store_dwordx4 v[134:135], v[204:207], off offset:-3840
	s_waitcnt vmcnt(14)
	v_lshlrev_b32_e32 v146, 16, v208
	v_and_b32_e32 v147, 0xffff0000, v208
	v_lshlrev_b32_e32 v148, 16, v209
	v_and_b32_e32 v149, 0xffff0000, v209
	v_lshlrev_b32_e32 v150, 16, v210
	v_and_b32_e32 v151, 0xffff0000, v210
	v_lshlrev_b32_e32 v152, 16, v211
	v_and_b32_e32 v153, 0xffff0000, v211
	v_pk_mul_f32 v[146:147], v[146:147], s[100:101] op_sel_hi:[1,0]
	v_pk_mul_f32 v[148:149], v[148:149], s[100:101] op_sel_hi:[1,0]
	v_pk_mul_f32 v[150:151], v[150:151], s[100:101] op_sel_hi:[1,0]
	v_pk_mul_f32 v[152:153], v[152:153], s[100:101] op_sel_hi:[1,0]
	v_min_f32_e32 v146, 0x42b80000, v146
	v_min_f32_e32 v147, 0x42b80000, v147
	v_min_f32_e32 v148, 0x42b80000, v148
	v_min_f32_e32 v149, 0x42b80000, v149
	v_min_f32_e32 v150, 0x42b80000, v150
	v_min_f32_e32 v151, 0x42b80000, v151
	v_min_f32_e32 v152, 0x42b80000, v152
	v_min_f32_e32 v153, 0x42b80000, v153
	v_exp_f32_e32 v146, v146
	v_exp_f32_e32 v147, v147
	v_exp_f32_e32 v148, v148
	v_exp_f32_e32 v149, v149
	v_exp_f32_e32 v150, v150
	v_exp_f32_e32 v151, v151
	v_exp_f32_e32 v152, v152
	v_exp_f32_e32 v153, v153
	s_nop 0
	v_add_f32_e32 v146, 1.0, v146
	v_add_f32_e32 v147, 1.0, v147
	v_add_f32_e32 v148, 1.0, v148
	v_add_f32_e32 v149, 1.0, v149
	v_add_f32_e32 v150, 1.0, v150
	v_add_f32_e32 v151, 1.0, v151
	v_add_f32_e32 v152, 1.0, v152
	v_add_f32_e32 v153, 1.0, v153
	v_rcp_f32_e32 v146, v146
	v_rcp_f32_e32 v147, v147
	v_rcp_f32_e32 v148, v148
	v_rcp_f32_e32 v149, v149
	v_rcp_f32_e32 v150, v150
	v_rcp_f32_e32 v151, v151
	v_rcp_f32_e32 v152, v152
	v_rcp_f32_e32 v153, v153
	s_nop 0
	v_pk_mul_f32 v[86:87], v[86:87], v[146:147]
	v_pk_mul_f32 v[88:89], v[88:89], v[148:149]
	v_pk_mul_f32 v[78:79], v[78:79], v[150:151]
	v_pk_mul_f32 v[80:81], v[80:81], v[152:153]
	v_cvt_pk_bf16_f32 v208, v86, v87
	v_cvt_pk_bf16_f32 v209, v88, v89
	v_cvt_pk_bf16_f32 v210, v78, v79
	v_cvt_pk_bf16_f32 v211, v80, v81
	v_lshlrev_b32_e32 v168, 16, v212
	v_and_b32_e32 v169, 0xffff0000, v212
	v_lshlrev_b32_e32 v178, 16, v213
	v_and_b32_e32 v179, 0xffff0000, v213
	v_lshlrev_b32_e32 v180, 16, v214
	v_and_b32_e32 v181, 0xffff0000, v214
	v_lshlrev_b32_e32 v244, 16, v215
	v_and_b32_e32 v245, 0xffff0000, v215
	v_pk_mul_f32 v[168:169], v[168:169], s[100:101] op_sel_hi:[1,0]
	v_pk_mul_f32 v[178:179], v[178:179], s[100:101] op_sel_hi:[1,0]
	v_pk_mul_f32 v[180:181], v[180:181], s[100:101] op_sel_hi:[1,0]
	v_pk_mul_f32 v[244:245], v[244:245], s[100:101] op_sel_hi:[1,0]
	v_min_f32_e32 v168, 0x42b80000, v168
	v_min_f32_e32 v169, 0x42b80000, v169
	v_min_f32_e32 v178, 0x42b80000, v178
	v_min_f32_e32 v179, 0x42b80000, v179
	v_min_f32_e32 v180, 0x42b80000, v180
	v_min_f32_e32 v181, 0x42b80000, v181
	v_min_f32_e32 v244, 0x42b80000, v244
	v_min_f32_e32 v245, 0x42b80000, v245
	v_exp_f32_e32 v168, v168
	v_exp_f32_e32 v169, v169
	v_exp_f32_e32 v178, v178
	v_exp_f32_e32 v179, v179
	v_exp_f32_e32 v180, v180
	v_exp_f32_e32 v181, v181
	v_exp_f32_e32 v244, v244
	v_exp_f32_e32 v245, v245
	s_nop 0
	v_add_f32_e32 v168, 1.0, v168
	v_add_f32_e32 v169, 1.0, v169
	v_add_f32_e32 v178, 1.0, v178
	v_add_f32_e32 v179, 1.0, v179
	v_add_f32_e32 v180, 1.0, v180
	v_add_f32_e32 v181, 1.0, v181
	v_add_f32_e32 v244, 1.0, v244
	v_add_f32_e32 v245, 1.0, v245
	v_rcp_f32_e32 v168, v168
	v_rcp_f32_e32 v169, v169
	v_rcp_f32_e32 v178, v178
	v_rcp_f32_e32 v179, v179
	v_rcp_f32_e32 v180, v180
	v_rcp_f32_e32 v181, v181
	v_rcp_f32_e32 v244, v244
	v_rcp_f32_e32 v245, v245
	s_nop 0
	v_pk_mul_f32 v[70:71], v[70:71], v[168:169]
	v_pk_mul_f32 v[72:73], v[72:73], v[178:179]
	v_pk_mul_f32 v[66:67], v[66:67], v[180:181]
	v_pk_mul_f32 v[68:69], v[68:69], v[244:245]
	v_cvt_pk_bf16_f32 v212, v70, v71
	v_cvt_pk_bf16_f32 v213, v72, v73
	v_cvt_pk_bf16_f32 v214, v66, v67
	v_cvt_pk_bf16_f32 v215, v68, v69
	global_store_dwordx4 v[136:137], v[208:211], off offset:-4096
	global_store_dwordx4 v[136:137], v[212:215], off offset:-3840
	s_waitcnt vmcnt(14)
; DI float bflo(unsigned w) { return __uint_as_float(w << 16); }
; DI float bfhi(unsigned w) { return __uint_as_float(w & 0xffff0000u); }
; DI u32x4 pack8(f32x4 a, f32x4 b) { u32x4 w; w.x = pk2(a[0], a[1]); w.y = pk2(a[2], a[3]); w.z = pk2(b[0], b[1]); w.w = pk2(b[2], b[3]); return w; }
; DI float fexp2(float x) { return __builtin_amdgcn_exp2f(x); }
; DI float fexp(float x) { return __builtin_amdgcn_exp2f(x * LOG2E); }
; DI float frcp(float x) { return __builtin_amdgcn_rcpf(x); }
; DI float fsigmoid(float x) { return frcp(1.0f + fexp(-x)); }
;     DI void operator()(Acc& acc, const Unit& u, int wr, int wc, int fr, int fq) const {
;     ...
;                     for (int bj = 0; bj < 2; ++bj) { const u32x4 q = g[ai][m][bj]; f32x4& v0 = acc[ai][bj][m][0]; f32x4& v1 = acc[ai][bj][m][1];
;                         v0[0] *= bflo(q.x); v0[1] *= bfhi(q.x); v0[2] *= bflo(q.y); v0[3] *= bfhi(q.y); v1[0] *= bflo(q.z); v1[1] *= bfhi(q.z); v1[2] *= bflo(q.w); v1[3] *= bfhi(q.w); }
;     ...
;                     for (int bj = 0; bj < 2; ++bj) *(u32x4*)(base + (size_t)(ai * 128 + m * 16) * NPJ + bj * 128) = pack8(acc[ai][bj][m][0], acc[ai][bj][m][1]);
	v_lshlrev_b32_e32 v146, 16, v216
	v_and_b32_e32 v147, 0xffff0000, v216
	v_lshlrev_b32_e32 v148, 16, v217
	v_and_b32_e32 v149, 0xffff0000, v217
	v_lshlrev_b32_e32 v150, 16, v218
	v_and_b32_e32 v151, 0xffff0000, v218
	v_lshlrev_b32_e32 v152, 16, v219
	v_and_b32_e32 v153, 0xffff0000, v219
	v_pk_mul_f32 v[146:147], v[146:147], s[100:101] op_sel_hi:[1,0]
	v_pk_mul_f32 v[148:149], v[148:149], s[100:101] op_sel_hi:[1,0]
	v_pk_mul_f32 v[150:151], v[150:151], s[100:101] op_sel_hi:[1,0]
	v_pk_mul_f32 v[152:153], v[152:153], s[100:101] op_sel_hi:[1,0]
	v_min_f32_e32 v146, 0x42b80000, v146
	v_min_f32_e32 v147, 0x42b80000, v147
	v_min_f32_e32 v148, 0x42b80000, v148
	v_min_f32_e32 v149, 0x42b80000, v149
	v_min_f32_e32 v150, 0x42b80000, v150
	v_min_f32_e32 v151, 0x42b80000, v151
	v_min_f32_e32 v152, 0x42b80000, v152
	v_min_f32_e32 v153, 0x42b80000, v153
	v_exp_f32_e32 v146, v146
	v_exp_f32_e32 v147, v147
	v_exp_f32_e32 v148, v148
	v_exp_f32_e32 v149, v149
	v_exp_f32_e32 v150, v150
	v_exp_f32_e32 v151, v151
	v_exp_f32_e32 v152, v152
	v_exp_f32_e32 v153, v153
	s_nop 0
	v_add_f32_e32 v146, 1.0, v146
	v_add_f32_e32 v147, 1.0, v147
	v_add_f32_e32 v148, 1.0, v148
	v_add_f32_e32 v149, 1.0, v149
	v_add_f32_e32 v150, 1.0, v150
	v_add_f32_e32 v151, 1.0, v151
	v_add_f32_e32 v152, 1.0, v152
	v_add_f32_e32 v153, 1.0, v153
	v_rcp_f32_e32 v146, v146
	v_rcp_f32_e32 v147, v147
	v_rcp_f32_e32 v148, v148
	v_rcp_f32_e32 v149, v149
	v_rcp_f32_e32 v150, v150
	v_rcp_f32_e32 v151, v151
	v_rcp_f32_e32 v152, v152
	v_rcp_f32_e32 v153, v153
	s_nop 0
	v_pk_mul_f32 v[62:63], v[62:63], v[146:147]
	v_pk_mul_f32 v[64:65], v[64:65], v[148:149]
	v_pk_mul_f32 v[58:59], v[58:59], v[150:151]
	v_pk_mul_f32 v[60:61], v[60:61], v[152:153]
	v_cvt_pk_bf16_f32 v216, v62, v63
	v_cvt_pk_bf16_f32 v217, v64, v65
	v_cvt_pk_bf16_f32 v218, v58, v59
	v_cvt_pk_bf16_f32 v219, v60, v61
	v_lshlrev_b32_e32 v168, 16, v220
	v_and_b32_e32 v169, 0xffff0000, v220
	v_lshlrev_b32_e32 v178, 16, v221
	v_and_b32_e32 v179, 0xffff0000, v221
	v_lshlrev_b32_e32 v180, 16, v222
	v_and_b32_e32 v181, 0xffff0000, v222
	v_lshlrev_b32_e32 v244, 16, v223
	v_and_b32_e32 v245, 0xffff0000, v223
	v_pk_mul_f32 v[168:169], v[168:169], s[100:101] op_sel_hi:[1,0]
	v_pk_mul_f32 v[178:179], v[178:179], s[100:101] op_sel_hi:[1,0]
	v_pk_mul_f32 v[180:181], v[180:181], s[100:101] op_sel_hi:[1,0]
	v_pk_mul_f32 v[244:245], v[244:245], s[100:101] op_sel_hi:[1,0]
	v_min_f32_e32 v168, 0x42b80000, v168
	v_min_f32_e32 v169, 0x42b80000, v169
	v_min_f32_e32 v178, 0x42b80000, v178
	v_min_f32_e32 v179, 0x42b80000, v179
	v_min_f32_e32 v180, 0x42b80000, v180
	v_min_f32_e32 v181, 0x42b80000, v181
	v_min_f32_e32 v244, 0x42b80000, v244
	v_min_f32_e32 v245, 0x42b80000, v245
	v_exp_f32_e32 v168, v168
	v_exp_f32_e32 v169, v169
	v_exp_f32_e32 v178, v178
	v_exp_f32_e32 v179, v179
	v_exp_f32_e32 v180, v180
	v_exp_f32_e32 v181, v181
	v_exp_f32_e32 v244, v244
	v_exp_f32_e32 v245, v245
	s_nop 0
	v_add_f32_e32 v168, 1.0, v168
	v_add_f32_e32 v169, 1.0, v169
	v_add_f32_e32 v178, 1.0, v178
	v_add_f32_e32 v179, 1.0, v179
	v_add_f32_e32 v180, 1.0, v180
	v_add_f32_e32 v181, 1.0, v181
	v_add_f32_e32 v244, 1.0, v244
	v_add_f32_e32 v245, 1.0, v245
	v_rcp_f32_e32 v168, v168
	v_rcp_f32_e32 v169, v169
	v_rcp_f32_e32 v178, v178
	v_rcp_f32_e32 v179, v179
	v_rcp_f32_e32 v180, v180
	v_rcp_f32_e32 v181, v181
	v_rcp_f32_e32 v244, v244
	v_rcp_f32_e32 v245, v245
	s_nop 0
	v_pk_mul_f32 v[50:51], v[50:51], v[168:169]
	v_pk_mul_f32 v[52:53], v[52:53], v[178:179]
	v_pk_mul_f32 v[42:43], v[42:43], v[180:181]
	v_pk_mul_f32 v[44:45], v[44:45], v[244:245]
	v_cvt_pk_bf16_f32 v220, v50, v51
	v_cvt_pk_bf16_f32 v221, v52, v53
	v_cvt_pk_bf16_f32 v222, v42, v43
	v_cvt_pk_bf16_f32 v223, v44, v45
	global_store_dwordx4 v[138:139], v[216:219], off offset:-4096
	global_store_dwordx4 v[138:139], v[220:223], off offset:-3840
	s_waitcnt vmcnt(14)
	v_lshlrev_b32_e32 v146, 16, v224
	v_and_b32_e32 v147, 0xffff0000, v224
	v_lshlrev_b32_e32 v148, 16, v225
	v_and_b32_e32 v149, 0xffff0000, v225
	v_lshlrev_b32_e32 v150, 16, v226
	v_and_b32_e32 v151, 0xffff0000, v226
	v_lshlrev_b32_e32 v152, 16, v227
	v_and_b32_e32 v153, 0xffff0000, v227
	v_pk_mul_f32 v[146:147], v[146:147], s[100:101] op_sel_hi:[1,0]
	v_pk_mul_f32 v[148:149], v[148:149], s[100:101] op_sel_hi:[1,0]
	v_pk_mul_f32 v[150:151], v[150:151], s[100:101] op_sel_hi:[1,0]
	v_pk_mul_f32 v[152:153], v[152:153], s[100:101] op_sel_hi:[1,0]
	v_min_f32_e32 v146, 0x42b80000, v146
	v_min_f32_e32 v147, 0x42b80000, v147
	v_min_f32_e32 v148, 0x42b80000, v148
	v_min_f32_e32 v149, 0x42b80000, v149
	v_min_f32_e32 v150, 0x42b80000, v150
	v_min_f32_e32 v151, 0x42b80000, v151
	v_min_f32_e32 v152, 0x42b80000, v152
	v_min_f32_e32 v153, 0x42b80000, v153
	v_exp_f32_e32 v146, v146
	v_exp_f32_e32 v147, v147
	v_exp_f32_e32 v148, v148
	v_exp_f32_e32 v149, v149
	v_exp_f32_e32 v150, v150
	v_exp_f32_e32 v151, v151
	v_exp_f32_e32 v152, v152
	v_exp_f32_e32 v153, v153
	s_nop 0
	v_add_f32_e32 v146, 1.0, v146
	v_add_f32_e32 v147, 1.0, v147
	v_add_f32_e32 v148, 1.0, v148
	v_add_f32_e32 v149, 1.0, v149
	v_add_f32_e32 v150, 1.0, v150
	v_add_f32_e32 v151, 1.0, v151
	v_add_f32_e32 v152, 1.0, v152
	v_add_f32_e32 v153, 1.0, v153
	v_rcp_f32_e32 v146, v146
	v_rcp_f32_e32 v147, v147
	v_rcp_f32_e32 v148, v148
	v_rcp_f32_e32 v149, v149
	v_rcp_f32_e32 v150, v150
	v_rcp_f32_e32 v151, v151
	v_rcp_f32_e32 v152, v152
	v_rcp_f32_e32 v153, v153
	s_nop 0
	v_pk_mul_f32 v[54:55], v[54:55], v[146:147]
	v_pk_mul_f32 v[56:57], v[56:57], v[148:149]
	v_pk_mul_f32 v[46:47], v[46:47], v[150:151]
	v_pk_mul_f32 v[48:49], v[48:49], v[152:153]
	v_cvt_pk_bf16_f32 v224, v54, v55
	v_cvt_pk_bf16_f32 v225, v56, v57
; DI float bflo(unsigned w) { return __uint_as_float(w << 16); }
; DI float bfhi(unsigned w) { return __uint_as_float(w & 0xffff0000u); }
; DI u32x4 pack8(f32x4 a, f32x4 b) { u32x4 w; w.x = pk2(a[0], a[1]); w.y = pk2(a[2], a[3]); w.z = pk2(b[0], b[1]); w.w = pk2(b[2], b[3]); return w; }
; DI float fexp2(float x) { return __builtin_amdgcn_exp2f(x); }
; DI float fexp(float x) { return __builtin_amdgcn_exp2f(x * LOG2E); }
; DI float frcp(float x) { return __builtin_amdgcn_rcpf(x); }
; DI float fsigmoid(float x) { return frcp(1.0f + fexp(-x)); }
;     DI void operator()(Acc& acc, const Unit& u, int wr, int wc, int fr, int fq) const {
;     ...
;                     for (int bj = 0; bj < 2; ++bj) { const u32x4 q = g[ai][m][bj]; f32x4& v0 = acc[ai][bj][m][0]; f32x4& v1 = acc[ai][bj][m][1];
;                         v0[0] *= bflo(q.x); v0[1] *= bfhi(q.x); v0[2] *= bflo(q.y); v0[3] *= bfhi(q.y); v1[0] *= bflo(q.z); v1[1] *= bfhi(q.z); v1[2] *= bflo(q.w); v1[3] *= bfhi(q.w); }
;     ...
;                     for (int bj = 0; bj < 2; ++bj) *(u32x4*)(base + (size_t)(ai * 128 + m * 16) * NPJ + bj * 128) = pack8(acc[ai][bj][m][0], acc[ai][bj][m][1]);
	v_cvt_pk_bf16_f32 v226, v46, v47
	v_cvt_pk_bf16_f32 v227, v48, v49
	v_lshlrev_b32_e32 v168, 16, v228
	v_and_b32_e32 v169, 0xffff0000, v228
	v_lshlrev_b32_e32 v178, 16, v229
	v_and_b32_e32 v179, 0xffff0000, v229
	v_lshlrev_b32_e32 v180, 16, v230
	v_and_b32_e32 v181, 0xffff0000, v230
	v_lshlrev_b32_e32 v244, 16, v231
	v_and_b32_e32 v245, 0xffff0000, v231
	v_pk_mul_f32 v[168:169], v[168:169], s[100:101] op_sel_hi:[1,0]
	v_pk_mul_f32 v[178:179], v[178:179], s[100:101] op_sel_hi:[1,0]
	v_pk_mul_f32 v[180:181], v[180:181], s[100:101] op_sel_hi:[1,0]
	v_pk_mul_f32 v[244:245], v[244:245], s[100:101] op_sel_hi:[1,0]
	v_min_f32_e32 v168, 0x42b80000, v168
	v_min_f32_e32 v169, 0x42b80000, v169
	v_min_f32_e32 v178, 0x42b80000, v178
	v_min_f32_e32 v179, 0x42b80000, v179
	v_min_f32_e32 v180, 0x42b80000, v180
	v_min_f32_e32 v181, 0x42b80000, v181
	v_min_f32_e32 v244, 0x42b80000, v244
	v_min_f32_e32 v245, 0x42b80000, v245
	v_exp_f32_e32 v168, v168
	v_exp_f32_e32 v169, v169
	v_exp_f32_e32 v178, v178
	v_exp_f32_e32 v179, v179
	v_exp_f32_e32 v180, v180
	v_exp_f32_e32 v181, v181
	v_exp_f32_e32 v244, v244
	v_exp_f32_e32 v245, v245
	s_nop 0
	v_add_f32_e32 v168, 1.0, v168
	v_add_f32_e32 v169, 1.0, v169
	v_add_f32_e32 v178, 1.0, v178
	v_add_f32_e32 v179, 1.0, v179
	v_add_f32_e32 v180, 1.0, v180
	v_add_f32_e32 v181, 1.0, v181
	v_add_f32_e32 v244, 1.0, v244
	v_add_f32_e32 v245, 1.0, v245
	v_rcp_f32_e32 v168, v168
	v_rcp_f32_e32 v169, v169
	v_rcp_f32_e32 v178, v178
	v_rcp_f32_e32 v179, v179
	v_rcp_f32_e32 v180, v180
	v_rcp_f32_e32 v181, v181
	v_rcp_f32_e32 v244, v244
	v_rcp_f32_e32 v245, v245
	s_nop 0
	v_pk_mul_f32 v[34:35], v[34:35], v[168:169]
	v_pk_mul_f32 v[36:37], v[36:37], v[178:179]
	v_pk_mul_f32 v[26:27], v[26:27], v[180:181]
	v_pk_mul_f32 v[28:29], v[28:29], v[244:245]
	v_cvt_pk_bf16_f32 v228, v34, v35
	v_cvt_pk_bf16_f32 v229, v36, v37
	v_cvt_pk_bf16_f32 v230, v26, v27
	v_cvt_pk_bf16_f32 v231, v28, v29
	global_store_dwordx4 v[140:141], v[224:227], off offset:-4096
	global_store_dwordx4 v[140:141], v[228:231], off offset:-3840
	s_waitcnt vmcnt(12)
	v_lshlrev_b32_e32 v146, 16, v184
	v_and_b32_e32 v147, 0xffff0000, v184
	v_lshlrev_b32_e32 v148, 16, v185
	v_and_b32_e32 v149, 0xffff0000, v185
	v_lshlrev_b32_e32 v150, 16, v186
	v_and_b32_e32 v151, 0xffff0000, v186
	v_lshlrev_b32_e32 v152, 16, v187
	v_and_b32_e32 v153, 0xffff0000, v187
	v_pk_mul_f32 v[146:147], v[146:147], s[100:101] op_sel_hi:[1,0]
	v_pk_mul_f32 v[148:149], v[148:149], s[100:101] op_sel_hi:[1,0]
	v_pk_mul_f32 v[150:151], v[150:151], s[100:101] op_sel_hi:[1,0]
	v_pk_mul_f32 v[152:153], v[152:153], s[100:101] op_sel_hi:[1,0]
	v_min_f32_e32 v146, 0x42b80000, v146
	v_min_f32_e32 v147, 0x42b80000, v147
	v_min_f32_e32 v148, 0x42b80000, v148
	v_min_f32_e32 v149, 0x42b80000, v149
	v_min_f32_e32 v150, 0x42b80000, v150
	v_min_f32_e32 v151, 0x42b80000, v151
	v_min_f32_e32 v152, 0x42b80000, v152
	v_min_f32_e32 v153, 0x42b80000, v153
	v_exp_f32_e32 v146, v146
	v_exp_f32_e32 v147, v147
	v_exp_f32_e32 v148, v148
	v_exp_f32_e32 v149, v149
	v_exp_f32_e32 v150, v150
	v_exp_f32_e32 v151, v151
	v_exp_f32_e32 v152, v152
	v_exp_f32_e32 v153, v153
	s_nop 0
	v_add_f32_e32 v146, 1.0, v146
	v_add_f32_e32 v147, 1.0, v147
	v_add_f32_e32 v148, 1.0, v148
	v_add_f32_e32 v149, 1.0, v149
	v_add_f32_e32 v150, 1.0, v150
	v_add_f32_e32 v151, 1.0, v151
	v_add_f32_e32 v152, 1.0, v152
	v_add_f32_e32 v153, 1.0, v153
	v_rcp_f32_e32 v146, v146
	v_rcp_f32_e32 v147, v147
	v_rcp_f32_e32 v148, v148
	v_rcp_f32_e32 v149, v149
	v_rcp_f32_e32 v150, v150
	v_rcp_f32_e32 v151, v151
	v_rcp_f32_e32 v152, v152
	v_rcp_f32_e32 v153, v153
	s_nop 0
	v_pk_mul_f32 v[38:39], v[38:39], v[146:147]
	v_pk_mul_f32 v[40:41], v[40:41], v[148:149]
	v_pk_mul_f32 v[30:31], v[30:31], v[150:151]
	v_pk_mul_f32 v[32:33], v[32:33], v[152:153]
	v_cvt_pk_bf16_f32 v184, v38, v39
	v_cvt_pk_bf16_f32 v185, v40, v41
	v_cvt_pk_bf16_f32 v186, v30, v31
	v_cvt_pk_bf16_f32 v187, v32, v33
	v_lshlrev_b32_e32 v168, 16, v188
	v_and_b32_e32 v169, 0xffff0000, v188
	v_lshlrev_b32_e32 v178, 16, v189
	v_and_b32_e32 v179, 0xffff0000, v189
	v_lshlrev_b32_e32 v180, 16, v190
	v_and_b32_e32 v181, 0xffff0000, v190
	v_lshlrev_b32_e32 v244, 16, v191
	v_and_b32_e32 v245, 0xffff0000, v191
	v_pk_mul_f32 v[168:169], v[168:169], s[100:101] op_sel_hi:[1,0]
	v_pk_mul_f32 v[178:179], v[178:179], s[100:101] op_sel_hi:[1,0]
	v_pk_mul_f32 v[180:181], v[180:181], s[100:101] op_sel_hi:[1,0]
	v_pk_mul_f32 v[244:245], v[244:245], s[100:101] op_sel_hi:[1,0]
	v_min_f32_e32 v168, 0x42b80000, v168
	v_min_f32_e32 v169, 0x42b80000, v169
	v_min_f32_e32 v178, 0x42b80000, v178
	v_min_f32_e32 v179, 0x42b80000, v179
	v_min_f32_e32 v180, 0x42b80000, v180
	v_min_f32_e32 v181, 0x42b80000, v181
	v_min_f32_e32 v244, 0x42b80000, v244
	v_min_f32_e32 v245, 0x42b80000, v245
	v_exp_f32_e32 v168, v168
	v_exp_f32_e32 v169, v169
	v_exp_f32_e32 v178, v178
	v_exp_f32_e32 v179, v179
	v_exp_f32_e32 v180, v180
	v_exp_f32_e32 v181, v181
	v_exp_f32_e32 v244, v244
	v_exp_f32_e32 v245, v245
	s_nop 0
	v_add_f32_e32 v168, 1.0, v168
	v_add_f32_e32 v169, 1.0, v169
	v_add_f32_e32 v178, 1.0, v178
	v_add_f32_e32 v179, 1.0, v179
	v_add_f32_e32 v180, 1.0, v180
	v_add_f32_e32 v181, 1.0, v181
	v_add_f32_e32 v244, 1.0, v244
	v_add_f32_e32 v245, 1.0, v245
	v_rcp_f32_e32 v168, v168
	v_rcp_f32_e32 v169, v169
	v_rcp_f32_e32 v178, v178
	v_rcp_f32_e32 v179, v179
	v_rcp_f32_e32 v180, v180
	v_rcp_f32_e32 v181, v181
	v_rcp_f32_e32 v244, v244
	v_rcp_f32_e32 v245, v245
	s_nop 0
	v_pk_mul_f32 v[18:19], v[18:19], v[168:169]
	v_pk_mul_f32 v[20:21], v[20:21], v[178:179]
	v_pk_mul_f32 v[10:11], v[10:11], v[180:181]
	v_pk_mul_f32 v[12:13], v[12:13], v[244:245]
	v_cvt_pk_bf16_f32 v188, v18, v19
	v_cvt_pk_bf16_f32 v189, v20, v21
	v_cvt_pk_bf16_f32 v190, v10, v11
	v_cvt_pk_bf16_f32 v191, v12, v13
	global_store_dwordx4 v[142:143], v[184:187], off offset:-4096
	global_store_dwordx4 v[142:143], v[188:191], off offset:-3840
	s_waitcnt vmcnt(10)
; DI float bflo(unsigned w) { return __uint_as_float(w << 16); }
; DI float bfhi(unsigned w) { return __uint_as_float(w & 0xffff0000u); }
; DI u32x4 pack8(f32x4 a, f32x4 b) { u32x4 w; w.x = pk2(a[0], a[1]); w.y = pk2(a[2], a[3]); w.z = pk2(b[0], b[1]); w.w = pk2(b[2], b[3]); return w; }
; DI float fexp2(float x) { return __builtin_amdgcn_exp2f(x); }
; DI float fexp(float x) { return __builtin_amdgcn_exp2f(x * LOG2E); }
; DI float frcp(float x) { return __builtin_amdgcn_rcpf(x); }
; DI float fsigmoid(float x) { return frcp(1.0f + fexp(-x)); }
;     DI void operator()(Acc& acc, const Unit& u, int wr, int wc, int fr, int fq) const {
;     ...
;                     for (int bj = 0; bj < 2; ++bj) { const u32x4 q = g[ai][m][bj]; f32x4& v0 = acc[ai][bj][m][0]; f32x4& v1 = acc[ai][bj][m][1];
;                         v0[0] *= bflo(q.x); v0[1] *= bfhi(q.x); v0[2] *= bflo(q.y); v0[3] *= bfhi(q.y); v1[0] *= bflo(q.z); v1[1] *= bfhi(q.z); v1[2] *= bflo(q.w); v1[3] *= bfhi(q.w); }
;     ...
;                     for (int bj = 0; bj < 2; ++bj) *(u32x4*)(base + (size_t)(ai * 128 + m * 16) * NPJ + bj * 128) = pack8(acc[ai][bj][m][0], acc[ai][bj][m][1]);
	v_lshlrev_b32_e32 v146, 16, v192
	v_and_b32_e32 v147, 0xffff0000, v192
	v_lshlrev_b32_e32 v148, 16, v193
	v_and_b32_e32 v149, 0xffff0000, v193
	v_lshlrev_b32_e32 v150, 16, v194
	v_and_b32_e32 v151, 0xffff0000, v194
	v_lshlrev_b32_e32 v152, 16, v195
	v_and_b32_e32 v153, 0xffff0000, v195
	v_pk_mul_f32 v[146:147], v[146:147], s[100:101] op_sel_hi:[1,0]
	v_pk_mul_f32 v[148:149], v[148:149], s[100:101] op_sel_hi:[1,0]
	v_pk_mul_f32 v[150:151], v[150:151], s[100:101] op_sel_hi:[1,0]
	v_pk_mul_f32 v[152:153], v[152:153], s[100:101] op_sel_hi:[1,0]
	v_min_f32_e32 v146, 0x42b80000, v146
	v_min_f32_e32 v147, 0x42b80000, v147
	v_min_f32_e32 v148, 0x42b80000, v148
	v_min_f32_e32 v149, 0x42b80000, v149
	v_min_f32_e32 v150, 0x42b80000, v150
	v_min_f32_e32 v151, 0x42b80000, v151
	v_min_f32_e32 v152, 0x42b80000, v152
	v_min_f32_e32 v153, 0x42b80000, v153
	v_exp_f32_e32 v146, v146
	v_exp_f32_e32 v147, v147
	v_exp_f32_e32 v148, v148
	v_exp_f32_e32 v149, v149
	v_exp_f32_e32 v150, v150
	v_exp_f32_e32 v151, v151
	v_exp_f32_e32 v152, v152
	v_exp_f32_e32 v153, v153
	s_nop 0
	v_add_f32_e32 v146, 1.0, v146
	v_add_f32_e32 v147, 1.0, v147
	v_add_f32_e32 v148, 1.0, v148
	v_add_f32_e32 v149, 1.0, v149
	v_add_f32_e32 v150, 1.0, v150
	v_add_f32_e32 v151, 1.0, v151
	v_add_f32_e32 v152, 1.0, v152
	v_add_f32_e32 v153, 1.0, v153
	v_rcp_f32_e32 v146, v146
	v_rcp_f32_e32 v147, v147
	v_rcp_f32_e32 v148, v148
	v_rcp_f32_e32 v149, v149
	v_rcp_f32_e32 v150, v150
	v_rcp_f32_e32 v151, v151
	v_rcp_f32_e32 v152, v152
	v_rcp_f32_e32 v153, v153
	s_nop 0
	v_pk_mul_f32 v[22:23], v[22:23], v[146:147]
	v_pk_mul_f32 v[24:25], v[24:25], v[148:149]
	v_pk_mul_f32 v[14:15], v[14:15], v[150:151]
	v_pk_mul_f32 v[16:17], v[16:17], v[152:153]
	v_cvt_pk_bf16_f32 v192, v22, v23
	v_cvt_pk_bf16_f32 v193, v24, v25
	v_cvt_pk_bf16_f32 v194, v14, v15
	v_cvt_pk_bf16_f32 v195, v16, v17
	v_lshlrev_b32_e32 v168, 16, v196
	v_and_b32_e32 v169, 0xffff0000, v196
	v_lshlrev_b32_e32 v178, 16, v197
	v_and_b32_e32 v179, 0xffff0000, v197
	v_lshlrev_b32_e32 v180, 16, v198
	v_and_b32_e32 v181, 0xffff0000, v198
	v_lshlrev_b32_e32 v244, 16, v199
	v_and_b32_e32 v245, 0xffff0000, v199
	v_pk_mul_f32 v[168:169], v[168:169], s[100:101] op_sel_hi:[1,0]
	v_pk_mul_f32 v[178:179], v[178:179], s[100:101] op_sel_hi:[1,0]
	v_pk_mul_f32 v[180:181], v[180:181], s[100:101] op_sel_hi:[1,0]
	v_pk_mul_f32 v[244:245], v[244:245], s[100:101] op_sel_hi:[1,0]
	v_min_f32_e32 v168, 0x42b80000, v168
	v_min_f32_e32 v169, 0x42b80000, v169
	v_min_f32_e32 v178, 0x42b80000, v178
	v_min_f32_e32 v179, 0x42b80000, v179
	v_min_f32_e32 v180, 0x42b80000, v180
	v_min_f32_e32 v181, 0x42b80000, v181
	v_min_f32_e32 v244, 0x42b80000, v244
	v_min_f32_e32 v245, 0x42b80000, v245
	v_exp_f32_e32 v168, v168
	v_exp_f32_e32 v169, v169
	v_exp_f32_e32 v178, v178
	v_exp_f32_e32 v179, v179
	v_exp_f32_e32 v180, v180
	v_exp_f32_e32 v181, v181
	v_exp_f32_e32 v244, v244
	v_exp_f32_e32 v245, v245
	s_nop 0
	v_add_f32_e32 v168, 1.0, v168
	v_add_f32_e32 v169, 1.0, v169
	v_add_f32_e32 v178, 1.0, v178
	v_add_f32_e32 v179, 1.0, v179
	v_add_f32_e32 v180, 1.0, v180
	v_add_f32_e32 v181, 1.0, v181
	v_add_f32_e32 v244, 1.0, v244
	v_add_f32_e32 v245, 1.0, v245
	v_rcp_f32_e32 v168, v168
	v_rcp_f32_e32 v169, v169
	v_rcp_f32_e32 v178, v178
	v_rcp_f32_e32 v179, v179
	v_rcp_f32_e32 v180, v180
	v_rcp_f32_e32 v181, v181
	v_rcp_f32_e32 v244, v244
	v_rcp_f32_e32 v245, v245
	s_nop 0
	v_pk_mul_f32 v[6:7], v[6:7], v[168:169]
	v_pk_mul_f32 v[8:9], v[8:9], v[178:179]
	v_pk_mul_f32 v[2:3], v[2:3], v[180:181]
	v_pk_mul_f32 v[4:5], v[4:5], v[244:245]
	v_cvt_pk_bf16_f32 v196, v6, v7
	v_cvt_pk_bf16_f32 v197, v8, v9
	v_cvt_pk_bf16_f32 v198, v2, v3
	v_cvt_pk_bf16_f32 v199, v4, v5
	global_store_dwordx4 v[144:145], v[192:195], off offset:-4096
	global_store_dwordx4 v[144:145], v[196:199], off offset:-3840

; DI float bflo(unsigned w) { return __uint_as_float(w << 16); }
; DI float bfhi(unsigned w) { return __uint_as_float(w & 0xffff0000u); }
; DI float fexp2(float x) { return __builtin_amdgcn_exp2f(x); }
; DI float fexp(float x) { return __builtin_amdgcn_exp2f(x * LOG2E); }
; DI float frcp(float x) { return __builtin_amdgcn_rcpf(x); }
; DI float fsigmoid(float x) { return frcp(1.0f + fexp(-x)); }
;     DI void operator()(Acc& acc, const Unit& u, int wr, int wc, int fr, int fq) const {
;     ...
;         bf16_t* base = proj + (size_t)(u.pm * 256 + wr * 64 + fr) * NPJ + C_GL + u.pn * 256 + wc * 32 + fq * 8;
;     ...
;                     for (int bj = 0; bj < 2; ++bj) g[ai][m][bj] = *(const u32x4*)(base + (size_t)(ai * 128 + m * 16) * NPJ + u.k * 1024 + bj * 128);
; #pragma unroll
;             for (int ai = 0; ai < 2; ++ai)
; #pragma unroll
;                 for (int m = 0; m < 4; ++m)
; #pragma unroll
;                     for (int bj = 0; bj < 2; ++bj) { const u32x4 q = g[ai][m][bj]; f32x4& v0 = acc[ai][bj][m][0]; f32x4& v1 = acc[ai][bj][m][1];
;                         v0[0] *= bflo(q.x); v0[1] *= bfhi(q.x); v0[2] *= bflo(q.y); v0[3] *= bfhi(q.y); v1[0] *= bflo(q.z); v1[1] *= bfhi(q.z); v1[2] *= bflo(q.w); v1[3] *= bfhi(q.w); }
.LBB0_1266:
	v_mov_b32_e32 v130, v1
	v_mov_b32_e32 v132, v170
	s_lshl_b32 s22, s69, 8
	s_add_i32 s22, s22, s34
	v_add_u32_e32 v133, s22, v130
	v_mov_b64_e32 v[130:131], s[48:49]
	v_mad_i64_i32 v[130:131], s[22:23], v133, s40, v[130:131]
	s_lshl_b32 s22, s68, 8
	s_ashr_i32 s23, s22, 31
	v_lshl_add_u64 v[130:131], s[22:23], 1, v[130:131]
	v_lshlrev_b32_e32 v132, 3, v132
	v_lshl_add_u64 v[130:131], v[130:131], 0, s[8:9]
	v_ashrrev_i32_e32 v133, 31, v132
	v_lshl_add_u64 v[130:131], v[132:133], 1, v[130:131]
	s_lshl_b32 s22, s67, 10
	v_lshl_add_u64 v[166:167], v[130:131], 0, s[16:17]
	s_ashr_i32 s23, s22, 31
	v_lshl_add_u64 v[130:131], s[22:23], 1, v[166:167]
	s_mov_b32 s101, 0
	s_mov_b32 s100, 0x32000
	v_lshl_add_u64 v[132:133], v[130:131], 0, s[100:101]
	s_mov_b32 s100, 0x64000
	v_lshl_add_u64 v[134:135], v[130:131], 0, s[100:101]
	s_mov_b32 s100, 0x96000
	v_lshl_add_u64 v[136:137], v[130:131], 0, s[100:101]
	s_mov_b32 s100, 0x190000
	v_lshl_add_u64 v[138:139], v[130:131], 0, s[100:101]
	s_mov_b32 s100, 0x1c2000
	v_lshl_add_u64 v[140:141], v[130:131], 0, s[100:101]
	s_mov_b32 s100, 0x1f4000
	v_lshl_add_u64 v[142:143], v[130:131], 0, s[100:101]
	s_mov_b32 s100, 0x226000
	v_lshl_add_u64 v[144:145], v[130:131], 0, s[100:101]
	s_mov_b32 s100, 0xbfb8aa3b
	s_cmp_eq_u32 s67, 2
	s_cbranch_scc1 .Lup6_final
	global_load_dwordx4 v[184:187], v[130:131], off
	global_load_dwordx4 v[188:191], v[130:131], off offset:256
	global_load_dwordx4 v[192:195], v[130:131], off offset:2048
	global_load_dwordx4 v[196:199], v[130:131], off offset:2304
	global_load_dwordx4 v[200:203], v[132:133], off
	global_load_dwordx4 v[204:207], v[132:133], off offset:256
	global_load_dwordx4 v[208:211], v[132:133], off offset:2048
	global_load_dwordx4 v[212:215], v[132:133], off offset:2304
	global_load_dwordx4 v[216:219], v[134:135], off
	global_load_dwordx4 v[220:223], v[134:135], off offset:256
	global_load_dwordx4 v[224:227], v[134:135], off offset:2048
	global_load_dwordx4 v[228:231], v[134:135], off offset:2304
	s_waitcnt vmcnt(8)
	v_lshlrev_b32_e32 v148, 16, v184
	v_and_b32_e32 v149, 0xffff0000, v184
	v_lshlrev_b32_e32 v150, 16, v192
	v_and_b32_e32 v151, 0xffff0000, v192
	v_lshlrev_b32_e32 v152, 16, v185
	v_and_b32_e32 v153, 0xffff0000, v185
	v_lshlrev_b32_e32 v168, 16, v193
	v_and_b32_e32 v169, 0xffff0000, v193
	v_pk_mul_f32 v[148:149], v[148:149], s[100:101] op_sel_hi:[1,0]
	v_pk_mul_f32 v[150:151], v[150:151], s[100:101] op_sel_hi:[1,0]
	v_pk_mul_f32 v[152:153], v[152:153], s[100:101] op_sel_hi:[1,0]
	v_pk_mul_f32 v[168:169], v[168:169], s[100:101] op_sel_hi:[1,0]
	v_min_f32_e32 v148, 0x42b80000, v148
	v_min_f32_e32 v149, 0x42b80000, v149
	v_min_f32_e32 v150, 0x42b80000, v150
	v_min_f32_e32 v151, 0x42b80000, v151
	v_min_f32_e32 v152, 0x42b80000, v152
	v_min_f32_e32 v153, 0x42b80000, v153
	v_min_f32_e32 v168, 0x42b80000, v168
	v_min_f32_e32 v169, 0x42b80000, v169
	v_exp_f32_e32 v148, v148
	v_exp_f32_e32 v149, v149
	v_exp_f32_e32 v150, v150
	v_exp_f32_e32 v151, v151
	v_exp_f32_e32 v152, v152
	v_exp_f32_e32 v153, v153
	v_exp_f32_e32 v168, v168
	v_exp_f32_e32 v169, v169
	s_nop 0
	v_add_f32_e32 v148, 1.0, v148
	v_add_f32_e32 v149, 1.0, v149
	v_add_f32_e32 v150, 1.0, v150
	v_add_f32_e32 v151, 1.0, v151
	v_add_f32_e32 v152, 1.0, v152
	v_add_f32_e32 v153, 1.0, v153
	v_add_f32_e32 v168, 1.0, v168
	v_add_f32_e32 v169, 1.0, v169
	v_rcp_f32_e32 v148, v148
	v_rcp_f32_e32 v149, v149
	v_rcp_f32_e32 v152, v152
	v_rcp_f32_e32 v153, v153
	s_nop 0
	v_pk_mul_f32 v[148:149], v[148:149], v[150:151]
	v_pk_mul_f32 v[152:153], v[152:153], v[168:169]
	v_pk_mul_f32 v[126:127], v[126:127], v[148:149]
	v_pk_mul_f32 v[128:129], v[128:129], v[152:153]
	v_lshlrev_b32_e32 v176, 16, v186
	v_and_b32_e32 v177, 0xffff0000, v186
	v_lshlrev_b32_e32 v178, 16, v194
	v_and_b32_e32 v179, 0xffff0000, v194
	v_lshlrev_b32_e32 v180, 16, v187
	v_and_b32_e32 v181, 0xffff0000, v187
	v_lshlrev_b32_e32 v244, 16, v195
	v_and_b32_e32 v245, 0xffff0000, v195
	v_pk_mul_f32 v[176:177], v[176:177], s[100:101] op_sel_hi:[1,0]
	v_pk_mul_f32 v[178:179], v[178:179], s[100:101] op_sel_hi:[1,0]
	v_pk_mul_f32 v[180:181], v[180:181], s[100:101] op_sel_hi:[1,0]
	v_pk_mul_f32 v[244:245], v[244:245], s[100:101] op_sel_hi:[1,0]
	v_min_f32_e32 v176, 0x42b80000, v176
	v_min_f32_e32 v177, 0x42b80000, v177
	v_min_f32_e32 v178, 0x42b80000, v178
	v_min_f32_e32 v179, 0x42b80000, v179
	v_min_f32_e32 v180, 0x42b80000, v180
	v_min_f32_e32 v181, 0x42b80000, v181
	v_min_f32_e32 v244, 0x42b80000, v244
	v_min_f32_e32 v245, 0x42b80000, v245
	v_exp_f32_e32 v176, v176
	v_exp_f32_e32 v177, v177
	v_exp_f32_e32 v178, v178
	v_exp_f32_e32 v179, v179
	v_exp_f32_e32 v180, v180
	v_exp_f32_e32 v181, v181
	v_exp_f32_e32 v244, v244
	v_exp_f32_e32 v245, v245
	s_nop 0
	v_add_f32_e32 v176, 1.0, v176
	v_add_f32_e32 v177, 1.0, v177
	v_add_f32_e32 v178, 1.0, v178
	v_add_f32_e32 v179, 1.0, v179
	v_add_f32_e32 v180, 1.0, v180
	v_add_f32_e32 v181, 1.0, v181
	v_add_f32_e32 v244, 1.0, v244
	v_add_f32_e32 v245, 1.0, v245
	v_rcp_f32_e32 v176, v176
	v_rcp_f32_e32 v177, v177
	v_rcp_f32_e32 v180, v180
	v_rcp_f32_e32 v181, v181
	s_nop 0
	v_pk_mul_f32 v[176:177], v[176:177], v[178:179]
	v_pk_mul_f32 v[180:181], v[180:181], v[244:245]
	v_pk_mul_f32 v[122:123], v[122:123], v[176:177]
	v_pk_mul_f32 v[124:125], v[124:125], v[180:181]
	v_lshlrev_b32_e32 v176, 16, v188
	v_and_b32_e32 v177, 0xffff0000, v188
	v_lshlrev_b32_e32 v178, 16, v196
	v_and_b32_e32 v179, 0xffff0000, v196
	v_lshlrev_b32_e32 v180, 16, v189
	v_and_b32_e32 v181, 0xffff0000, v189
	v_lshlrev_b32_e32 v244, 16, v197
	v_and_b32_e32 v245, 0xffff0000, v197
	v_pk_mul_f32 v[176:177], v[176:177], s[100:101] op_sel_hi:[1,0]
; DI float bflo(unsigned w) { return __uint_as_float(w << 16); }
; DI float bfhi(unsigned w) { return __uint_as_float(w & 0xffff0000u); }
; DI float fexp2(float x) { return __builtin_amdgcn_exp2f(x); }
; DI float fexp(float x) { return __builtin_amdgcn_exp2f(x * LOG2E); }
; DI float frcp(float x) { return __builtin_amdgcn_rcpf(x); }
; DI float fsigmoid(float x) { return frcp(1.0f + fexp(-x)); }
;     DI void operator()(Acc& acc, const Unit& u, int wr, int wc, int fr, int fq) const {
;     ...
;                     for (int bj = 0; bj < 2; ++bj) g[ai][m][bj] = *(const u32x4*)(base + (size_t)(ai * 128 + m * 16) * NPJ + u.k * 1024 + bj * 128);
; #pragma unroll
;             for (int ai = 0; ai < 2; ++ai)
; #pragma unroll
;                 for (int m = 0; m < 4; ++m)
; #pragma unroll
;                     for (int bj = 0; bj < 2; ++bj) { const u32x4 q = g[ai][m][bj]; f32x4& v0 = acc[ai][bj][m][0]; f32x4& v1 = acc[ai][bj][m][1];
;                         v0[0] *= bflo(q.x); v0[1] *= bfhi(q.x); v0[2] *= bflo(q.y); v0[3] *= bfhi(q.y); v1[0] *= bflo(q.z); v1[1] *= bfhi(q.z); v1[2] *= bflo(q.w); v1[3] *= bfhi(q.w); }
	v_pk_mul_f32 v[178:179], v[178:179], s[100:101] op_sel_hi:[1,0]
	v_pk_mul_f32 v[180:181], v[180:181], s[100:101] op_sel_hi:[1,0]
	v_pk_mul_f32 v[244:245], v[244:245], s[100:101] op_sel_hi:[1,0]
	v_min_f32_e32 v176, 0x42b80000, v176
	v_min_f32_e32 v177, 0x42b80000, v177
	v_min_f32_e32 v178, 0x42b80000, v178
	v_min_f32_e32 v179, 0x42b80000, v179
	v_min_f32_e32 v180, 0x42b80000, v180
	v_min_f32_e32 v181, 0x42b80000, v181
	v_min_f32_e32 v244, 0x42b80000, v244
	v_min_f32_e32 v245, 0x42b80000, v245
	v_exp_f32_e32 v176, v176
	v_exp_f32_e32 v177, v177
	v_exp_f32_e32 v178, v178
	v_exp_f32_e32 v179, v179
	v_exp_f32_e32 v180, v180
	v_exp_f32_e32 v181, v181
	v_exp_f32_e32 v244, v244
	v_exp_f32_e32 v245, v245
	s_nop 0
	v_add_f32_e32 v176, 1.0, v176
	v_add_f32_e32 v177, 1.0, v177
	v_add_f32_e32 v178, 1.0, v178
	v_add_f32_e32 v179, 1.0, v179
	v_add_f32_e32 v180, 1.0, v180
	v_add_f32_e32 v181, 1.0, v181
	v_add_f32_e32 v244, 1.0, v244
	v_add_f32_e32 v245, 1.0, v245
	v_rcp_f32_e32 v176, v176
	v_rcp_f32_e32 v177, v177
	v_rcp_f32_e32 v180, v180
	v_rcp_f32_e32 v181, v181
	s_nop 0
	v_pk_mul_f32 v[176:177], v[176:177], v[178:179]
	v_pk_mul_f32 v[180:181], v[180:181], v[244:245]
	v_pk_mul_f32 v[114:115], v[114:115], v[176:177]
	v_pk_mul_f32 v[116:117], v[116:117], v[180:181]
	v_lshlrev_b32_e32 v148, 16, v190
	v_and_b32_e32 v149, 0xffff0000, v190
	v_lshlrev_b32_e32 v150, 16, v198
	v_and_b32_e32 v151, 0xffff0000, v198
	v_lshlrev_b32_e32 v152, 16, v191
	v_and_b32_e32 v153, 0xffff0000, v191
	v_lshlrev_b32_e32 v168, 16, v199
	v_and_b32_e32 v169, 0xffff0000, v199
	v_pk_mul_f32 v[148:149], v[148:149], s[100:101] op_sel_hi:[1,0]
	v_pk_mul_f32 v[150:151], v[150:151], s[100:101] op_sel_hi:[1,0]
	v_pk_mul_f32 v[152:153], v[152:153], s[100:101] op_sel_hi:[1,0]
	v_pk_mul_f32 v[168:169], v[168:169], s[100:101] op_sel_hi:[1,0]
	v_min_f32_e32 v148, 0x42b80000, v148
	v_min_f32_e32 v149, 0x42b80000, v149
	v_min_f32_e32 v150, 0x42b80000, v150
	v_min_f32_e32 v151, 0x42b80000, v151
	v_min_f32_e32 v152, 0x42b80000, v152
	v_min_f32_e32 v153, 0x42b80000, v153
	v_min_f32_e32 v168, 0x42b80000, v168
	v_min_f32_e32 v169, 0x42b80000, v169
	v_exp_f32_e32 v148, v148
	v_exp_f32_e32 v149, v149
	v_exp_f32_e32 v150, v150
	v_exp_f32_e32 v151, v151
	v_exp_f32_e32 v152, v152
	v_exp_f32_e32 v153, v153
	v_exp_f32_e32 v168, v168
	v_exp_f32_e32 v169, v169
	s_nop 0
	v_add_f32_e32 v148, 1.0, v148
	v_add_f32_e32 v149, 1.0, v149
	v_add_f32_e32 v150, 1.0, v150
	v_add_f32_e32 v151, 1.0, v151
	v_add_f32_e32 v152, 1.0, v152
	v_add_f32_e32 v153, 1.0, v153
	v_add_f32_e32 v168, 1.0, v168
	v_add_f32_e32 v169, 1.0, v169
	v_rcp_f32_e32 v148, v148
	v_rcp_f32_e32 v149, v149
	v_rcp_f32_e32 v152, v152
	v_rcp_f32_e32 v153, v153
	s_nop 0
	v_pk_mul_f32 v[148:149], v[148:149], v[150:151]
	v_pk_mul_f32 v[152:153], v[152:153], v[168:169]
	v_pk_mul_f32 v[110:111], v[110:111], v[148:149]
	v_pk_mul_f32 v[112:113], v[112:113], v[152:153]
	global_load_dwordx4 v[184:187], v[136:137], off
	global_load_dwordx4 v[188:191], v[136:137], off offset:256
	global_load_dwordx4 v[192:195], v[136:137], off offset:2048
	global_load_dwordx4 v[196:199], v[136:137], off offset:2304
	s_waitcnt vmcnt(8)
	v_lshlrev_b32_e32 v148, 16, v200
	v_and_b32_e32 v149, 0xffff0000, v200
	v_lshlrev_b32_e32 v150, 16, v208
	v_and_b32_e32 v151, 0xffff0000, v208
	v_lshlrev_b32_e32 v152, 16, v201
	v_and_b32_e32 v153, 0xffff0000, v201
	v_lshlrev_b32_e32 v168, 16, v209
	v_and_b32_e32 v169, 0xffff0000, v209
	v_pk_mul_f32 v[148:149], v[148:149], s[100:101] op_sel_hi:[1,0]
	v_pk_mul_f32 v[150:151], v[150:151], s[100:101] op_sel_hi:[1,0]
	v_pk_mul_f32 v[152:153], v[152:153], s[100:101] op_sel_hi:[1,0]
	v_pk_mul_f32 v[168:169], v[168:169], s[100:101] op_sel_hi:[1,0]
	v_min_f32_e32 v148, 0x42b80000, v148
	v_min_f32_e32 v149, 0x42b80000, v149
	v_min_f32_e32 v150, 0x42b80000, v150
	v_min_f32_e32 v151, 0x42b80000, v151
	v_min_f32_e32 v152, 0x42b80000, v152
	v_min_f32_e32 v153, 0x42b80000, v153
	v_min_f32_e32 v168, 0x42b80000, v168
	v_min_f32_e32 v169, 0x42b80000, v169
	v_exp_f32_e32 v148, v148
	v_exp_f32_e32 v149, v149
	v_exp_f32_e32 v150, v150
	v_exp_f32_e32 v151, v151
	v_exp_f32_e32 v152, v152
	v_exp_f32_e32 v153, v153
	v_exp_f32_e32 v168, v168
	v_exp_f32_e32 v169, v169
	s_nop 0
	v_add_f32_e32 v148, 1.0, v148
	v_add_f32_e32 v149, 1.0, v149
	v_add_f32_e32 v150, 1.0, v150
	v_add_f32_e32 v151, 1.0, v151
	v_add_f32_e32 v152, 1.0, v152
	v_add_f32_e32 v153, 1.0, v153
	v_add_f32_e32 v168, 1.0, v168
	v_add_f32_e32 v169, 1.0, v169
	v_rcp_f32_e32 v148, v148
	v_rcp_f32_e32 v149, v149
	v_rcp_f32_e32 v152, v152
	v_rcp_f32_e32 v153, v153
	s_nop 0
	v_pk_mul_f32 v[148:149], v[148:149], v[150:151]
	v_pk_mul_f32 v[152:153], v[152:153], v[168:169]
	v_pk_mul_f32 v[118:119], v[118:119], v[148:149]
	v_pk_mul_f32 v[120:121], v[120:121], v[152:153]
	v_lshlrev_b32_e32 v176, 16, v202
	v_and_b32_e32 v177, 0xffff0000, v202
	v_lshlrev_b32_e32 v178, 16, v210
	v_and_b32_e32 v179, 0xffff0000, v210
	v_lshlrev_b32_e32 v180, 16, v203
	v_and_b32_e32 v181, 0xffff0000, v203
	v_lshlrev_b32_e32 v244, 16, v211
	v_and_b32_e32 v245, 0xffff0000, v211
	v_pk_mul_f32 v[176:177], v[176:177], s[100:101] op_sel_hi:[1,0]
	v_pk_mul_f32 v[178:179], v[178:179], s[100:101] op_sel_hi:[1,0]
	v_pk_mul_f32 v[180:181], v[180:181], s[100:101] op_sel_hi:[1,0]
	v_pk_mul_f32 v[244:245], v[244:245], s[100:101] op_sel_hi:[1,0]
	v_min_f32_e32 v176, 0x42b80000, v176
	v_min_f32_e32 v177, 0x42b80000, v177
	v_min_f32_e32 v178, 0x42b80000, v178
	v_min_f32_e32 v179, 0x42b80000, v179
	v_min_f32_e32 v180, 0x42b80000, v180
	v_min_f32_e32 v181, 0x42b80000, v181
	v_min_f32_e32 v244, 0x42b80000, v244
	v_min_f32_e32 v245, 0x42b80000, v245
; DI float bflo(unsigned w) { return __uint_as_float(w << 16); }
; DI float bfhi(unsigned w) { return __uint_as_float(w & 0xffff0000u); }
; DI float fexp2(float x) { return __builtin_amdgcn_exp2f(x); }
; DI float fexp(float x) { return __builtin_amdgcn_exp2f(x * LOG2E); }
; DI float frcp(float x) { return __builtin_amdgcn_rcpf(x); }
; DI float fsigmoid(float x) { return frcp(1.0f + fexp(-x)); }
;     DI void operator()(Acc& acc, const Unit& u, int wr, int wc, int fr, int fq) const {
;     ...
;                     for (int bj = 0; bj < 2; ++bj) g[ai][m][bj] = *(const u32x4*)(base + (size_t)(ai * 128 + m * 16) * NPJ + u.k * 1024 + bj * 128);
; #pragma unroll
;             for (int ai = 0; ai < 2; ++ai)
; #pragma unroll
;                 for (int m = 0; m < 4; ++m)
; #pragma unroll
;                     for (int bj = 0; bj < 2; ++bj) { const u32x4 q = g[ai][m][bj]; f32x4& v0 = acc[ai][bj][m][0]; f32x4& v1 = acc[ai][bj][m][1];
;                         v0[0] *= bflo(q.x); v0[1] *= bfhi(q.x); v0[2] *= bflo(q.y); v0[3] *= bfhi(q.y); v1[0] *= bflo(q.z); v1[1] *= bfhi(q.z); v1[2] *= bflo(q.w); v1[3] *= bfhi(q.w); }
	v_exp_f32_e32 v176, v176
	v_exp_f32_e32 v177, v177
	v_exp_f32_e32 v178, v178
	v_exp_f32_e32 v179, v179
	v_exp_f32_e32 v180, v180
	v_exp_f32_e32 v181, v181
	v_exp_f32_e32 v244, v244
	v_exp_f32_e32 v245, v245
	s_nop 0
	v_add_f32_e32 v176, 1.0, v176
	v_add_f32_e32 v177, 1.0, v177
	v_add_f32_e32 v178, 1.0, v178
	v_add_f32_e32 v179, 1.0, v179
	v_add_f32_e32 v180, 1.0, v180
	v_add_f32_e32 v181, 1.0, v181
	v_add_f32_e32 v244, 1.0, v244
	v_add_f32_e32 v245, 1.0, v245
	v_rcp_f32_e32 v176, v176
	v_rcp_f32_e32 v177, v177
	v_rcp_f32_e32 v180, v180
	v_rcp_f32_e32 v181, v181
	s_nop 0
	v_pk_mul_f32 v[176:177], v[176:177], v[178:179]
	v_pk_mul_f32 v[180:181], v[180:181], v[244:245]
	v_pk_mul_f32 v[106:107], v[106:107], v[176:177]
	v_pk_mul_f32 v[108:109], v[108:109], v[180:181]
	v_lshlrev_b32_e32 v176, 16, v204
	v_and_b32_e32 v177, 0xffff0000, v204
	v_lshlrev_b32_e32 v178, 16, v212
	v_and_b32_e32 v179, 0xffff0000, v212
	v_lshlrev_b32_e32 v180, 16, v205
	v_and_b32_e32 v181, 0xffff0000, v205
	v_lshlrev_b32_e32 v244, 16, v213
	v_and_b32_e32 v245, 0xffff0000, v213
	v_pk_mul_f32 v[176:177], v[176:177], s[100:101] op_sel_hi:[1,0]
	v_pk_mul_f32 v[178:179], v[178:179], s[100:101] op_sel_hi:[1,0]
	v_pk_mul_f32 v[180:181], v[180:181], s[100:101] op_sel_hi:[1,0]
	v_pk_mul_f32 v[244:245], v[244:245], s[100:101] op_sel_hi:[1,0]
	v_min_f32_e32 v176, 0x42b80000, v176
	v_min_f32_e32 v177, 0x42b80000, v177
	v_min_f32_e32 v178, 0x42b80000, v178
	v_min_f32_e32 v179, 0x42b80000, v179
	v_min_f32_e32 v180, 0x42b80000, v180
	v_min_f32_e32 v181, 0x42b80000, v181
	v_min_f32_e32 v244, 0x42b80000, v244
	v_min_f32_e32 v245, 0x42b80000, v245
	v_exp_f32_e32 v176, v176
	v_exp_f32_e32 v177, v177
	v_exp_f32_e32 v178, v178
	v_exp_f32_e32 v179, v179
	v_exp_f32_e32 v180, v180
	v_exp_f32_e32 v181, v181
	v_exp_f32_e32 v244, v244
	v_exp_f32_e32 v245, v245
	s_nop 0
	v_add_f32_e32 v176, 1.0, v176
	v_add_f32_e32 v177, 1.0, v177
	v_add_f32_e32 v178, 1.0, v178
	v_add_f32_e32 v179, 1.0, v179
	v_add_f32_e32 v180, 1.0, v180
	v_add_f32_e32 v181, 1.0, v181
	v_add_f32_e32 v244, 1.0, v244
	v_add_f32_e32 v245, 1.0, v245
	v_rcp_f32_e32 v176, v176
	v_rcp_f32_e32 v177, v177
	v_rcp_f32_e32 v180, v180
	v_rcp_f32_e32 v181, v181
	s_nop 0
	v_pk_mul_f32 v[176:177], v[176:177], v[178:179]
	v_pk_mul_f32 v[180:181], v[180:181], v[244:245]
	v_pk_mul_f32 v[98:99], v[98:99], v[176:177]
	v_pk_mul_f32 v[100:101], v[100:101], v[180:181]
	v_lshlrev_b32_e32 v148, 16, v206
	v_and_b32_e32 v149, 0xffff0000, v206
	v_lshlrev_b32_e32 v150, 16, v214
	v_and_b32_e32 v151, 0xffff0000, v214
	v_lshlrev_b32_e32 v152, 16, v207
	v_and_b32_e32 v153, 0xffff0000, v207
	v_lshlrev_b32_e32 v168, 16, v215
	v_and_b32_e32 v169, 0xffff0000, v215
	v_pk_mul_f32 v[148:149], v[148:149], s[100:101] op_sel_hi:[1,0]
	v_pk_mul_f32 v[150:151], v[150:151], s[100:101] op_sel_hi:[1,0]
	v_pk_mul_f32 v[152:153], v[152:153], s[100:101] op_sel_hi:[1,0]
	v_pk_mul_f32 v[168:169], v[168:169], s[100:101] op_sel_hi:[1,0]
	v_min_f32_e32 v148, 0x42b80000, v148
	v_min_f32_e32 v149, 0x42b80000, v149
	v_min_f32_e32 v150, 0x42b80000, v150
	v_min_f32_e32 v151, 0x42b80000, v151
	v_min_f32_e32 v152, 0x42b80000, v152
	v_min_f32_e32 v153, 0x42b80000, v153
	v_min_f32_e32 v168, 0x42b80000, v168
	v_min_f32_e32 v169, 0x42b80000, v169
	v_exp_f32_e32 v148, v148
	v_exp_f32_e32 v149, v149
	v_exp_f32_e32 v150, v150
	v_exp_f32_e32 v151, v151
	v_exp_f32_e32 v152, v152
	v_exp_f32_e32 v153, v153
	v_exp_f32_e32 v168, v168
	v_exp_f32_e32 v169, v169
	s_nop 0
	v_add_f32_e32 v148, 1.0, v148
	v_add_f32_e32 v149, 1.0, v149
	v_add_f32_e32 v150, 1.0, v150
	v_add_f32_e32 v151, 1.0, v151
	v_add_f32_e32 v152, 1.0, v152
	v_add_f32_e32 v153, 1.0, v153
	v_add_f32_e32 v168, 1.0, v168
	v_add_f32_e32 v169, 1.0, v169
	v_rcp_f32_e32 v148, v148
	v_rcp_f32_e32 v149, v149
	v_rcp_f32_e32 v152, v152
	v_rcp_f32_e32 v153, v153
	s_nop 0
	v_pk_mul_f32 v[148:149], v[148:149], v[150:151]
	v_pk_mul_f32 v[152:153], v[152:153], v[168:169]
	v_pk_mul_f32 v[90:91], v[90:91], v[148:149]
	v_pk_mul_f32 v[92:93], v[92:93], v[152:153]
	global_load_dwordx4 v[200:203], v[138:139], off
	global_load_dwordx4 v[204:207], v[138:139], off offset:256
	global_load_dwordx4 v[208:211], v[138:139], off offset:2048
	global_load_dwordx4 v[212:215], v[138:139], off offset:2304
	s_waitcnt vmcnt(8)
; DI float bflo(unsigned w) { return __uint_as_float(w << 16); }
; DI float bfhi(unsigned w) { return __uint_as_float(w & 0xffff0000u); }
; DI float fexp2(float x) { return __builtin_amdgcn_exp2f(x); }
; DI float fexp(float x) { return __builtin_amdgcn_exp2f(x * LOG2E); }
; DI float frcp(float x) { return __builtin_amdgcn_rcpf(x); }
; DI float fsigmoid(float x) { return frcp(1.0f + fexp(-x)); }
;     DI void operator()(Acc& acc, const Unit& u, int wr, int wc, int fr, int fq) const {
;     ...
;                     for (int bj = 0; bj < 2; ++bj) g[ai][m][bj] = *(const u32x4*)(base + (size_t)(ai * 128 + m * 16) * NPJ + u.k * 1024 + bj * 128);
; #pragma unroll
;             for (int ai = 0; ai < 2; ++ai)
; #pragma unroll
;                 for (int m = 0; m < 4; ++m)
; #pragma unroll
;                     for (int bj = 0; bj < 2; ++bj) { const u32x4 q = g[ai][m][bj]; f32x4& v0 = acc[ai][bj][m][0]; f32x4& v1 = acc[ai][bj][m][1];
;                         v0[0] *= bflo(q.x); v0[1] *= bfhi(q.x); v0[2] *= bflo(q.y); v0[3] *= bfhi(q.y); v1[0] *= bflo(q.z); v1[1] *= bfhi(q.z); v1[2] *= bflo(q.w); v1[3] *= bfhi(q.w); }
	v_lshlrev_b32_e32 v148, 16, v216
	v_and_b32_e32 v149, 0xffff0000, v216
	v_lshlrev_b32_e32 v150, 16, v224
	v_and_b32_e32 v151, 0xffff0000, v224
	v_lshlrev_b32_e32 v152, 16, v217
	v_and_b32_e32 v153, 0xffff0000, v217
	v_lshlrev_b32_e32 v168, 16, v225
	v_and_b32_e32 v169, 0xffff0000, v225
	v_pk_mul_f32 v[148:149], v[148:149], s[100:101] op_sel_hi:[1,0]
	v_pk_mul_f32 v[150:151], v[150:151], s[100:101] op_sel_hi:[1,0]
	v_pk_mul_f32 v[152:153], v[152:153], s[100:101] op_sel_hi:[1,0]
	v_pk_mul_f32 v[168:169], v[168:169], s[100:101] op_sel_hi:[1,0]
	v_min_f32_e32 v148, 0x42b80000, v148
	v_min_f32_e32 v149, 0x42b80000, v149
	v_min_f32_e32 v150, 0x42b80000, v150
	v_min_f32_e32 v151, 0x42b80000, v151
	v_min_f32_e32 v152, 0x42b80000, v152
	v_min_f32_e32 v153, 0x42b80000, v153
	v_min_f32_e32 v168, 0x42b80000, v168
	v_min_f32_e32 v169, 0x42b80000, v169
	v_exp_f32_e32 v148, v148
	v_exp_f32_e32 v149, v149
	v_exp_f32_e32 v150, v150
	v_exp_f32_e32 v151, v151
	v_exp_f32_e32 v152, v152
	v_exp_f32_e32 v153, v153
	v_exp_f32_e32 v168, v168
	v_exp_f32_e32 v169, v169
	s_nop 0
	v_add_f32_e32 v148, 1.0, v148
	v_add_f32_e32 v149, 1.0, v149
	v_add_f32_e32 v150, 1.0, v150
	v_add_f32_e32 v151, 1.0, v151
	v_add_f32_e32 v152, 1.0, v152
	v_add_f32_e32 v153, 1.0, v153
	v_add_f32_e32 v168, 1.0, v168
	v_add_f32_e32 v169, 1.0, v169
	v_rcp_f32_e32 v148, v148
	v_rcp_f32_e32 v149, v149
	v_rcp_f32_e32 v152, v152
	v_rcp_f32_e32 v153, v153
	s_nop 0
	v_pk_mul_f32 v[148:149], v[148:149], v[150:151]
	v_pk_mul_f32 v[152:153], v[152:153], v[168:169]
	v_pk_mul_f32 v[102:103], v[102:103], v[148:149]
	v_pk_mul_f32 v[104:105], v[104:105], v[152:153]
	v_lshlrev_b32_e32 v176, 16, v218
	v_and_b32_e32 v177, 0xffff0000, v218
	v_lshlrev_b32_e32 v178, 16, v226
	v_and_b32_e32 v179, 0xffff0000, v226
	v_lshlrev_b32_e32 v180, 16, v219
	v_and_b32_e32 v181, 0xffff0000, v219
	v_lshlrev_b32_e32 v244, 16, v227
	v_and_b32_e32 v245, 0xffff0000, v227
	v_pk_mul_f32 v[176:177], v[176:177], s[100:101] op_sel_hi:[1,0]
	v_pk_mul_f32 v[178:179], v[178:179], s[100:101] op_sel_hi:[1,0]
	v_pk_mul_f32 v[180:181], v[180:181], s[100:101] op_sel_hi:[1,0]
	v_pk_mul_f32 v[244:245], v[244:245], s[100:101] op_sel_hi:[1,0]
	v_min_f32_e32 v176, 0x42b80000, v176
	v_min_f32_e32 v177, 0x42b80000, v177
	v_min_f32_e32 v178, 0x42b80000, v178
	v_min_f32_e32 v179, 0x42b80000, v179
	v_min_f32_e32 v180, 0x42b80000, v180
	v_min_f32_e32 v181, 0x42b80000, v181
	v_min_f32_e32 v244, 0x42b80000, v244
	v_min_f32_e32 v245, 0x42b80000, v245
	v_exp_f32_e32 v176, v176
	v_exp_f32_e32 v177, v177
	v_exp_f32_e32 v178, v178
	v_exp_f32_e32 v179, v179
	v_exp_f32_e32 v180, v180
	v_exp_f32_e32 v181, v181
	v_exp_f32_e32 v244, v244
	v_exp_f32_e32 v245, v245
	s_nop 0
	v_add_f32_e32 v176, 1.0, v176
	v_add_f32_e32 v177, 1.0, v177
	v_add_f32_e32 v178, 1.0, v178
	v_add_f32_e32 v179, 1.0, v179
	v_add_f32_e32 v180, 1.0, v180
	v_add_f32_e32 v181, 1.0, v181
	v_add_f32_e32 v244, 1.0, v244
	v_add_f32_e32 v245, 1.0, v245
	v_rcp_f32_e32 v176, v176
	v_rcp_f32_e32 v177, v177
	v_rcp_f32_e32 v180, v180
	v_rcp_f32_e32 v181, v181
	s_nop 0
	v_pk_mul_f32 v[176:177], v[176:177], v[178:179]
	v_pk_mul_f32 v[180:181], v[180:181], v[244:245]
	v_pk_mul_f32 v[94:95], v[94:95], v[176:177]
	v_pk_mul_f32 v[96:97], v[96:97], v[180:181]
	v_lshlrev_b32_e32 v176, 16, v220
	v_and_b32_e32 v177, 0xffff0000, v220
	v_lshlrev_b32_e32 v178, 16, v228
	v_and_b32_e32 v179, 0xffff0000, v228
	v_lshlrev_b32_e32 v180, 16, v221
	v_and_b32_e32 v181, 0xffff0000, v221
	v_lshlrev_b32_e32 v244, 16, v229
	v_and_b32_e32 v245, 0xffff0000, v229
	v_pk_mul_f32 v[176:177], v[176:177], s[100:101] op_sel_hi:[1,0]
	v_pk_mul_f32 v[178:179], v[178:179], s[100:101] op_sel_hi:[1,0]
	v_pk_mul_f32 v[180:181], v[180:181], s[100:101] op_sel_hi:[1,0]
	v_pk_mul_f32 v[244:245], v[244:245], s[100:101] op_sel_hi:[1,0]
	v_min_f32_e32 v176, 0x42b80000, v176
	v_min_f32_e32 v177, 0x42b80000, v177
	v_min_f32_e32 v178, 0x42b80000, v178
	v_min_f32_e32 v179, 0x42b80000, v179
	v_min_f32_e32 v180, 0x42b80000, v180
	v_min_f32_e32 v181, 0x42b80000, v181
	v_min_f32_e32 v244, 0x42b80000, v244
	v_min_f32_e32 v245, 0x42b80000, v245
	v_exp_f32_e32 v176, v176
	v_exp_f32_e32 v177, v177
	v_exp_f32_e32 v178, v178
	v_exp_f32_e32 v179, v179
	v_exp_f32_e32 v180, v180
	v_exp_f32_e32 v181, v181
	v_exp_f32_e32 v244, v244
	v_exp_f32_e32 v245, v245
	s_nop 0
	v_add_f32_e32 v176, 1.0, v176
	v_add_f32_e32 v177, 1.0, v177
	v_add_f32_e32 v178, 1.0, v178
	v_add_f32_e32 v179, 1.0, v179
	v_add_f32_e32 v180, 1.0, v180
	v_add_f32_e32 v181, 1.0, v181
	v_add_f32_e32 v244, 1.0, v244
	v_add_f32_e32 v245, 1.0, v245
	v_rcp_f32_e32 v176, v176
	v_rcp_f32_e32 v177, v177
	v_rcp_f32_e32 v180, v180
	v_rcp_f32_e32 v181, v181
	s_nop 0
	v_pk_mul_f32 v[176:177], v[176:177], v[178:179]
	v_pk_mul_f32 v[180:181], v[180:181], v[244:245]
	v_pk_mul_f32 v[82:83], v[82:83], v[176:177]
	v_pk_mul_f32 v[84:85], v[84:85], v[180:181]
	v_lshlrev_b32_e32 v148, 16, v222
	v_and_b32_e32 v149, 0xffff0000, v222
	v_lshlrev_b32_e32 v150, 16, v230
	v_and_b32_e32 v151, 0xffff0000, v230
	v_lshlrev_b32_e32 v152, 16, v223
	v_and_b32_e32 v153, 0xffff0000, v223
	v_lshlrev_b32_e32 v168, 16, v231
	v_and_b32_e32 v169, 0xffff0000, v231
	v_pk_mul_f32 v[148:149], v[148:149], s[100:101] op_sel_hi:[1,0]
	v_pk_mul_f32 v[150:151], v[150:151], s[100:101] op_sel_hi:[1,0]
	v_pk_mul_f32 v[152:153], v[152:153], s[100:101] op_sel_hi:[1,0]
	v_pk_mul_f32 v[168:169], v[168:169], s[100:101] op_sel_hi:[1,0]
	v_min_f32_e32 v148, 0x42b80000, v148
	v_min_f32_e32 v149, 0x42b80000, v149
	v_min_f32_e32 v150, 0x42b80000, v150
	v_min_f32_e32 v151, 0x42b80000, v151
	v_min_f32_e32 v152, 0x42b80000, v152
	v_min_f32_e32 v153, 0x42b80000, v153
	v_min_f32_e32 v168, 0x42b80000, v168
	v_min_f32_e32 v169, 0x42b80000, v169
	v_exp_f32_e32 v148, v148
	v_exp_f32_e32 v149, v149
	v_exp_f32_e32 v150, v150
	v_exp_f32_e32 v151, v151
	v_exp_f32_e32 v152, v152
	v_exp_f32_e32 v153, v153
	v_exp_f32_e32 v168, v168
	v_exp_f32_e32 v169, v169
	s_nop 0
	v_add_f32_e32 v148, 1.0, v148
	v_add_f32_e32 v149, 1.0, v149
	v_add_f32_e32 v150, 1.0, v150
	v_add_f32_e32 v151, 1.0, v151
	v_add_f32_e32 v152, 1.0, v152
	v_add_f32_e32 v153, 1.0, v153
	v_add_f32_e32 v168, 1.0, v168
	v_add_f32_e32 v169, 1.0, v169
	v_rcp_f32_e32 v148, v148
	v_rcp_f32_e32 v149, v149
	v_rcp_f32_e32 v152, v152
	v_rcp_f32_e32 v153, v153
	s_nop 0
	v_pk_mul_f32 v[148:149], v[148:149], v[150:151]
	v_pk_mul_f32 v[152:153], v[152:153], v[168:169]
	v_pk_mul_f32 v[74:75], v[74:75], v[148:149]
	v_pk_mul_f32 v[76:77], v[76:77], v[152:153]
	global_load_dwordx4 v[216:219], v[140:141], off
	global_load_dwordx4 v[220:223], v[140:141], off offset:256
	global_load_dwordx4 v[224:227], v[140:141], off offset:2048
	global_load_dwordx4 v[228:231], v[140:141], off offset:2304
	s_waitcnt vmcnt(8)
; DI float bflo(unsigned w) { return __uint_as_float(w << 16); }
; DI float bfhi(unsigned w) { return __uint_as_float(w & 0xffff0000u); }
; DI float fexp2(float x) { return __builtin_amdgcn_exp2f(x); }
; DI float fexp(float x) { return __builtin_amdgcn_exp2f(x * LOG2E); }
; DI float frcp(float x) { return __builtin_amdgcn_rcpf(x); }
; DI float fsigmoid(float x) { return frcp(1.0f + fexp(-x)); }
;     DI void operator()(Acc& acc, const Unit& u, int wr, int wc, int fr, int fq) const {
;     ...
;                     for (int bj = 0; bj < 2; ++bj) g[ai][m][bj] = *(const u32x4*)(base + (size_t)(ai * 128 + m * 16) * NPJ + u.k * 1024 + bj * 128);
; #pragma unroll
;             for (int ai = 0; ai < 2; ++ai)
; #pragma unroll
;                 for (int m = 0; m < 4; ++m)
; #pragma unroll
;                     for (int bj = 0; bj < 2; ++bj) { const u32x4 q = g[ai][m][bj]; f32x4& v0 = acc[ai][bj][m][0]; f32x4& v1 = acc[ai][bj][m][1];
;                         v0[0] *= bflo(q.x); v0[1] *= bfhi(q.x); v0[2] *= bflo(q.y); v0[3] *= bfhi(q.y); v1[0] *= bflo(q.z); v1[1] *= bfhi(q.z); v1[2] *= bflo(q.w); v1[3] *= bfhi(q.w); }
	v_lshlrev_b32_e32 v148, 16, v184
	v_and_b32_e32 v149, 0xffff0000, v184
	v_lshlrev_b32_e32 v150, 16, v192
	v_and_b32_e32 v151, 0xffff0000, v192
	v_lshlrev_b32_e32 v152, 16, v185
	v_and_b32_e32 v153, 0xffff0000, v185
	v_lshlrev_b32_e32 v168, 16, v193
	v_and_b32_e32 v169, 0xffff0000, v193
	v_pk_mul_f32 v[148:149], v[148:149], s[100:101] op_sel_hi:[1,0]
	v_pk_mul_f32 v[150:151], v[150:151], s[100:101] op_sel_hi:[1,0]
	v_pk_mul_f32 v[152:153], v[152:153], s[100:101] op_sel_hi:[1,0]
	v_pk_mul_f32 v[168:169], v[168:169], s[100:101] op_sel_hi:[1,0]
	v_min_f32_e32 v148, 0x42b80000, v148
	v_min_f32_e32 v149, 0x42b80000, v149
	v_min_f32_e32 v150, 0x42b80000, v150
	v_min_f32_e32 v151, 0x42b80000, v151
	v_min_f32_e32 v152, 0x42b80000, v152
	v_min_f32_e32 v153, 0x42b80000, v153
	v_min_f32_e32 v168, 0x42b80000, v168
	v_min_f32_e32 v169, 0x42b80000, v169
	v_exp_f32_e32 v148, v148
	v_exp_f32_e32 v149, v149
	v_exp_f32_e32 v150, v150
	v_exp_f32_e32 v151, v151
	v_exp_f32_e32 v152, v152
	v_exp_f32_e32 v153, v153
	v_exp_f32_e32 v168, v168
	v_exp_f32_e32 v169, v169
	s_nop 0
	v_add_f32_e32 v148, 1.0, v148
	v_add_f32_e32 v149, 1.0, v149
	v_add_f32_e32 v150, 1.0, v150
	v_add_f32_e32 v151, 1.0, v151
	v_add_f32_e32 v152, 1.0, v152
	v_add_f32_e32 v153, 1.0, v153
	v_add_f32_e32 v168, 1.0, v168
	v_add_f32_e32 v169, 1.0, v169
	v_rcp_f32_e32 v148, v148
	v_rcp_f32_e32 v149, v149
	v_rcp_f32_e32 v152, v152
	v_rcp_f32_e32 v153, v153
	s_nop 0
	v_pk_mul_f32 v[148:149], v[148:149], v[150:151]
	v_pk_mul_f32 v[152:153], v[152:153], v[168:169]
	v_pk_mul_f32 v[86:87], v[86:87], v[148:149]
	v_pk_mul_f32 v[88:89], v[88:89], v[152:153]
	v_lshlrev_b32_e32 v176, 16, v186
	v_and_b32_e32 v177, 0xffff0000, v186
	v_lshlrev_b32_e32 v178, 16, v194
	v_and_b32_e32 v179, 0xffff0000, v194
	v_lshlrev_b32_e32 v180, 16, v187
	v_and_b32_e32 v181, 0xffff0000, v187
	v_lshlrev_b32_e32 v244, 16, v195
	v_and_b32_e32 v245, 0xffff0000, v195
	v_pk_mul_f32 v[176:177], v[176:177], s[100:101] op_sel_hi:[1,0]
	v_pk_mul_f32 v[178:179], v[178:179], s[100:101] op_sel_hi:[1,0]
	v_pk_mul_f32 v[180:181], v[180:181], s[100:101] op_sel_hi:[1,0]
	v_pk_mul_f32 v[244:245], v[244:245], s[100:101] op_sel_hi:[1,0]
	v_min_f32_e32 v176, 0x42b80000, v176
	v_min_f32_e32 v177, 0x42b80000, v177
	v_min_f32_e32 v178, 0x42b80000, v178
	v_min_f32_e32 v179, 0x42b80000, v179
	v_min_f32_e32 v180, 0x42b80000, v180
	v_min_f32_e32 v181, 0x42b80000, v181
	v_min_f32_e32 v244, 0x42b80000, v244
	v_min_f32_e32 v245, 0x42b80000, v245
	v_exp_f32_e32 v176, v176
	v_exp_f32_e32 v177, v177
	v_exp_f32_e32 v178, v178
	v_exp_f32_e32 v179, v179
	v_exp_f32_e32 v180, v180
	v_exp_f32_e32 v181, v181
	v_exp_f32_e32 v244, v244
	v_exp_f32_e32 v245, v245
	s_nop 0
	v_add_f32_e32 v176, 1.0, v176
	v_add_f32_e32 v177, 1.0, v177
	v_add_f32_e32 v178, 1.0, v178
	v_add_f32_e32 v179, 1.0, v179
	v_add_f32_e32 v180, 1.0, v180
	v_add_f32_e32 v181, 1.0, v181
	v_add_f32_e32 v244, 1.0, v244
	v_add_f32_e32 v245, 1.0, v245
	v_rcp_f32_e32 v176, v176
	v_rcp_f32_e32 v177, v177
	v_rcp_f32_e32 v180, v180
	v_rcp_f32_e32 v181, v181
	s_nop 0
	v_pk_mul_f32 v[176:177], v[176:177], v[178:179]
	v_pk_mul_f32 v[180:181], v[180:181], v[244:245]
	v_pk_mul_f32 v[78:79], v[78:79], v[176:177]
	v_pk_mul_f32 v[80:81], v[80:81], v[180:181]
	v_lshlrev_b32_e32 v176, 16, v188
	v_and_b32_e32 v177, 0xffff0000, v188
	v_lshlrev_b32_e32 v178, 16, v196
	v_and_b32_e32 v179, 0xffff0000, v196
	v_lshlrev_b32_e32 v180, 16, v189
	v_and_b32_e32 v181, 0xffff0000, v189
	v_lshlrev_b32_e32 v244, 16, v197
	v_and_b32_e32 v245, 0xffff0000, v197
	v_pk_mul_f32 v[176:177], v[176:177], s[100:101] op_sel_hi:[1,0]
	v_pk_mul_f32 v[178:179], v[178:179], s[100:101] op_sel_hi:[1,0]
	v_pk_mul_f32 v[180:181], v[180:181], s[100:101] op_sel_hi:[1,0]
	v_pk_mul_f32 v[244:245], v[244:245], s[100:101] op_sel_hi:[1,0]
	v_min_f32_e32 v176, 0x42b80000, v176
	v_min_f32_e32 v177, 0x42b80000, v177
	v_min_f32_e32 v178, 0x42b80000, v178
	v_min_f32_e32 v179, 0x42b80000, v179
	v_min_f32_e32 v180, 0x42b80000, v180
	v_min_f32_e32 v181, 0x42b80000, v181
	v_min_f32_e32 v244, 0x42b80000, v244
	v_min_f32_e32 v245, 0x42b80000, v245
	v_exp_f32_e32 v176, v176
	v_exp_f32_e32 v177, v177
	v_exp_f32_e32 v178, v178
	v_exp_f32_e32 v179, v179
	v_exp_f32_e32 v180, v180
	v_exp_f32_e32 v181, v181
	v_exp_f32_e32 v244, v244
	v_exp_f32_e32 v245, v245
	s_nop 0
	v_add_f32_e32 v176, 1.0, v176
	v_add_f32_e32 v177, 1.0, v177
	v_add_f32_e32 v178, 1.0, v178
	v_add_f32_e32 v179, 1.0, v179
	v_add_f32_e32 v180, 1.0, v180
	v_add_f32_e32 v181, 1.0, v181
	v_add_f32_e32 v244, 1.0, v244
	v_add_f32_e32 v245, 1.0, v245
	v_rcp_f32_e32 v176, v176
	v_rcp_f32_e32 v177, v177
	v_rcp_f32_e32 v180, v180
	v_rcp_f32_e32 v181, v181
	s_nop 0
	v_pk_mul_f32 v[176:177], v[176:177], v[178:179]
	v_pk_mul_f32 v[180:181], v[180:181], v[244:245]
	v_pk_mul_f32 v[70:71], v[70:71], v[176:177]
	v_pk_mul_f32 v[72:73], v[72:73], v[180:181]
	v_lshlrev_b32_e32 v148, 16, v190
	v_and_b32_e32 v149, 0xffff0000, v190
	v_lshlrev_b32_e32 v150, 16, v198
	v_and_b32_e32 v151, 0xffff0000, v198
	v_lshlrev_b32_e32 v152, 16, v191
	v_and_b32_e32 v153, 0xffff0000, v191
	v_lshlrev_b32_e32 v168, 16, v199
	v_and_b32_e32 v169, 0xffff0000, v199
	v_pk_mul_f32 v[148:149], v[148:149], s[100:101] op_sel_hi:[1,0]
	v_pk_mul_f32 v[150:151], v[150:151], s[100:101] op_sel_hi:[1,0]
	v_pk_mul_f32 v[152:153], v[152:153], s[100:101] op_sel_hi:[1,0]
	v_pk_mul_f32 v[168:169], v[168:169], s[100:101] op_sel_hi:[1,0]
	v_min_f32_e32 v148, 0x42b80000, v148
	v_min_f32_e32 v149, 0x42b80000, v149
	v_min_f32_e32 v150, 0x42b80000, v150
	v_min_f32_e32 v151, 0x42b80000, v151
	v_min_f32_e32 v152, 0x42b80000, v152
	v_min_f32_e32 v153, 0x42b80000, v153
	v_min_f32_e32 v168, 0x42b80000, v168
	v_min_f32_e32 v169, 0x42b80000, v169
	v_exp_f32_e32 v148, v148
	v_exp_f32_e32 v149, v149
	v_exp_f32_e32 v150, v150
	v_exp_f32_e32 v151, v151
	v_exp_f32_e32 v152, v152
	v_exp_f32_e32 v153, v153
	v_exp_f32_e32 v168, v168
	v_exp_f32_e32 v169, v169
	s_nop 0
	v_add_f32_e32 v148, 1.0, v148
	v_add_f32_e32 v149, 1.0, v149
	v_add_f32_e32 v150, 1.0, v150
	v_add_f32_e32 v151, 1.0, v151
	v_add_f32_e32 v152, 1.0, v152
	v_add_f32_e32 v153, 1.0, v153
	v_add_f32_e32 v168, 1.0, v168
	v_add_f32_e32 v169, 1.0, v169
	v_rcp_f32_e32 v148, v148
	v_rcp_f32_e32 v149, v149
	v_rcp_f32_e32 v152, v152
	v_rcp_f32_e32 v153, v153
	s_nop 0
	v_pk_mul_f32 v[148:149], v[148:149], v[150:151]
	v_pk_mul_f32 v[152:153], v[152:153], v[168:169]
	v_pk_mul_f32 v[66:67], v[66:67], v[148:149]
	v_pk_mul_f32 v[68:69], v[68:69], v[152:153]
	global_load_dwordx4 v[184:187], v[142:143], off
	global_load_dwordx4 v[188:191], v[142:143], off offset:256
	global_load_dwordx4 v[192:195], v[142:143], off offset:2048
	global_load_dwordx4 v[196:199], v[142:143], off offset:2304
	s_waitcnt vmcnt(8)
; DI float bflo(unsigned w) { return __uint_as_float(w << 16); }
; DI float bfhi(unsigned w) { return __uint_as_float(w & 0xffff0000u); }
; DI float fexp2(float x) { return __builtin_amdgcn_exp2f(x); }
; DI float fexp(float x) { return __builtin_amdgcn_exp2f(x * LOG2E); }
; DI float frcp(float x) { return __builtin_amdgcn_rcpf(x); }
; DI float fsigmoid(float x) { return frcp(1.0f + fexp(-x)); }
;     DI void operator()(Acc& acc, const Unit& u, int wr, int wc, int fr, int fq) const {
;     ...
;                     for (int bj = 0; bj < 2; ++bj) g[ai][m][bj] = *(const u32x4*)(base + (size_t)(ai * 128 + m * 16) * NPJ + u.k * 1024 + bj * 128);
; #pragma unroll
;             for (int ai = 0; ai < 2; ++ai)
; #pragma unroll
;                 for (int m = 0; m < 4; ++m)
; #pragma unroll
;                     for (int bj = 0; bj < 2; ++bj) { const u32x4 q = g[ai][m][bj]; f32x4& v0 = acc[ai][bj][m][0]; f32x4& v1 = acc[ai][bj][m][1];
;                         v0[0] *= bflo(q.x); v0[1] *= bfhi(q.x); v0[2] *= bflo(q.y); v0[3] *= bfhi(q.y); v1[0] *= bflo(q.z); v1[1] *= bfhi(q.z); v1[2] *= bflo(q.w); v1[3] *= bfhi(q.w); }
	v_lshlrev_b32_e32 v148, 16, v200
	v_and_b32_e32 v149, 0xffff0000, v200
	v_lshlrev_b32_e32 v150, 16, v208
	v_and_b32_e32 v151, 0xffff0000, v208
	v_lshlrev_b32_e32 v152, 16, v201
	v_and_b32_e32 v153, 0xffff0000, v201
	v_lshlrev_b32_e32 v168, 16, v209
	v_and_b32_e32 v169, 0xffff0000, v209
	v_pk_mul_f32 v[148:149], v[148:149], s[100:101] op_sel_hi:[1,0]
	v_pk_mul_f32 v[150:151], v[150:151], s[100:101] op_sel_hi:[1,0]
	v_pk_mul_f32 v[152:153], v[152:153], s[100:101] op_sel_hi:[1,0]
	v_pk_mul_f32 v[168:169], v[168:169], s[100:101] op_sel_hi:[1,0]
	v_min_f32_e32 v148, 0x42b80000, v148
	v_min_f32_e32 v149, 0x42b80000, v149
	v_min_f32_e32 v150, 0x42b80000, v150
	v_min_f32_e32 v151, 0x42b80000, v151
	v_min_f32_e32 v152, 0x42b80000, v152
	v_min_f32_e32 v153, 0x42b80000, v153
	v_min_f32_e32 v168, 0x42b80000, v168
	v_min_f32_e32 v169, 0x42b80000, v169
	v_exp_f32_e32 v148, v148
	v_exp_f32_e32 v149, v149
	v_exp_f32_e32 v150, v150
	v_exp_f32_e32 v151, v151
	v_exp_f32_e32 v152, v152
	v_exp_f32_e32 v153, v153
	v_exp_f32_e32 v168, v168
	v_exp_f32_e32 v169, v169
	s_nop 0
	v_add_f32_e32 v148, 1.0, v148
	v_add_f32_e32 v149, 1.0, v149
	v_add_f32_e32 v150, 1.0, v150
	v_add_f32_e32 v151, 1.0, v151
	v_add_f32_e32 v152, 1.0, v152
	v_add_f32_e32 v153, 1.0, v153
	v_add_f32_e32 v168, 1.0, v168
	v_add_f32_e32 v169, 1.0, v169
	v_rcp_f32_e32 v148, v148
	v_rcp_f32_e32 v149, v149
	v_rcp_f32_e32 v152, v152
	v_rcp_f32_e32 v153, v153
	s_nop 0
	v_pk_mul_f32 v[148:149], v[148:149], v[150:151]
	v_pk_mul_f32 v[152:153], v[152:153], v[168:169]
	v_pk_mul_f32 v[62:63], v[62:63], v[148:149]
	v_pk_mul_f32 v[64:65], v[64:65], v[152:153]
	v_lshlrev_b32_e32 v176, 16, v202
	v_and_b32_e32 v177, 0xffff0000, v202
	v_lshlrev_b32_e32 v178, 16, v210
	v_and_b32_e32 v179, 0xffff0000, v210
	v_lshlrev_b32_e32 v180, 16, v203
	v_and_b32_e32 v181, 0xffff0000, v203
	v_lshlrev_b32_e32 v244, 16, v211
	v_and_b32_e32 v245, 0xffff0000, v211
	v_pk_mul_f32 v[176:177], v[176:177], s[100:101] op_sel_hi:[1,0]
	v_pk_mul_f32 v[178:179], v[178:179], s[100:101] op_sel_hi:[1,0]
	v_pk_mul_f32 v[180:181], v[180:181], s[100:101] op_sel_hi:[1,0]
	v_pk_mul_f32 v[244:245], v[244:245], s[100:101] op_sel_hi:[1,0]
	v_min_f32_e32 v176, 0x42b80000, v176
	v_min_f32_e32 v177, 0x42b80000, v177
	v_min_f32_e32 v178, 0x42b80000, v178
	v_min_f32_e32 v179, 0x42b80000, v179
	v_min_f32_e32 v180, 0x42b80000, v180
	v_min_f32_e32 v181, 0x42b80000, v181
	v_min_f32_e32 v244, 0x42b80000, v244
	v_min_f32_e32 v245, 0x42b80000, v245
	v_exp_f32_e32 v176, v176
	v_exp_f32_e32 v177, v177
	v_exp_f32_e32 v178, v178
	v_exp_f32_e32 v179, v179
	v_exp_f32_e32 v180, v180
	v_exp_f32_e32 v181, v181
	v_exp_f32_e32 v244, v244
	v_exp_f32_e32 v245, v245
	s_nop 0
	v_add_f32_e32 v176, 1.0, v176
	v_add_f32_e32 v177, 1.0, v177
	v_add_f32_e32 v178, 1.0, v178
	v_add_f32_e32 v179, 1.0, v179
	v_add_f32_e32 v180, 1.0, v180
	v_add_f32_e32 v181, 1.0, v181
	v_add_f32_e32 v244, 1.0, v244
	v_add_f32_e32 v245, 1.0, v245
	v_rcp_f32_e32 v176, v176
	v_rcp_f32_e32 v177, v177
	v_rcp_f32_e32 v180, v180
	v_rcp_f32_e32 v181, v181
	s_nop 0
	v_pk_mul_f32 v[176:177], v[176:177], v[178:179]
	v_pk_mul_f32 v[180:181], v[180:181], v[244:245]
	v_pk_mul_f32 v[58:59], v[58:59], v[176:177]
	v_pk_mul_f32 v[60:61], v[60:61], v[180:181]
	v_lshlrev_b32_e32 v176, 16, v204
	v_and_b32_e32 v177, 0xffff0000, v204
	v_lshlrev_b32_e32 v178, 16, v212
	v_and_b32_e32 v179, 0xffff0000, v212
	v_lshlrev_b32_e32 v180, 16, v205
	v_and_b32_e32 v181, 0xffff0000, v205
	v_lshlrev_b32_e32 v244, 16, v213
	v_and_b32_e32 v245, 0xffff0000, v213
	v_pk_mul_f32 v[176:177], v[176:177], s[100:101] op_sel_hi:[1,0]
	v_pk_mul_f32 v[178:179], v[178:179], s[100:101] op_sel_hi:[1,0]
	v_pk_mul_f32 v[180:181], v[180:181], s[100:101] op_sel_hi:[1,0]
	v_pk_mul_f32 v[244:245], v[244:245], s[100:101] op_sel_hi:[1,0]
	v_min_f32_e32 v176, 0x42b80000, v176
	v_min_f32_e32 v177, 0x42b80000, v177
	v_min_f32_e32 v178, 0x42b80000, v178
	v_min_f32_e32 v179, 0x42b80000, v179
	v_min_f32_e32 v180, 0x42b80000, v180
	v_min_f32_e32 v181, 0x42b80000, v181
	v_min_f32_e32 v244, 0x42b80000, v244
	v_min_f32_e32 v245, 0x42b80000, v245
	v_exp_f32_e32 v176, v176
	v_exp_f32_e32 v177, v177
	v_exp_f32_e32 v178, v178
	v_exp_f32_e32 v179, v179
	v_exp_f32_e32 v180, v180
	v_exp_f32_e32 v181, v181
	v_exp_f32_e32 v244, v244
	v_exp_f32_e32 v245, v245
	s_nop 0
	v_add_f32_e32 v176, 1.0, v176
	v_add_f32_e32 v177, 1.0, v177
	v_add_f32_e32 v178, 1.0, v178
	v_add_f32_e32 v179, 1.0, v179
	v_add_f32_e32 v180, 1.0, v180
	v_add_f32_e32 v181, 1.0, v181
	v_add_f32_e32 v244, 1.0, v244
	v_add_f32_e32 v245, 1.0, v245
	v_rcp_f32_e32 v176, v176
	v_rcp_f32_e32 v177, v177
	v_rcp_f32_e32 v180, v180
	v_rcp_f32_e32 v181, v181
	s_nop 0
	v_pk_mul_f32 v[176:177], v[176:177], v[178:179]
	v_pk_mul_f32 v[180:181], v[180:181], v[244:245]
	v_pk_mul_f32 v[50:51], v[50:51], v[176:177]
	v_pk_mul_f32 v[52:53], v[52:53], v[180:181]
	v_lshlrev_b32_e32 v148, 16, v206
	v_and_b32_e32 v149, 0xffff0000, v206
	v_lshlrev_b32_e32 v150, 16, v214
	v_and_b32_e32 v151, 0xffff0000, v214
	v_lshlrev_b32_e32 v152, 16, v207
	v_and_b32_e32 v153, 0xffff0000, v207
	v_lshlrev_b32_e32 v168, 16, v215
	v_and_b32_e32 v169, 0xffff0000, v215
	v_pk_mul_f32 v[148:149], v[148:149], s[100:101] op_sel_hi:[1,0]
	v_pk_mul_f32 v[150:151], v[150:151], s[100:101] op_sel_hi:[1,0]
	v_pk_mul_f32 v[152:153], v[152:153], s[100:101] op_sel_hi:[1,0]
	v_pk_mul_f32 v[168:169], v[168:169], s[100:101] op_sel_hi:[1,0]
	v_min_f32_e32 v148, 0x42b80000, v148
	v_min_f32_e32 v149, 0x42b80000, v149
	v_min_f32_e32 v150, 0x42b80000, v150
	v_min_f32_e32 v151, 0x42b80000, v151
	v_min_f32_e32 v152, 0x42b80000, v152
	v_min_f32_e32 v153, 0x42b80000, v153
	v_min_f32_e32 v168, 0x42b80000, v168
	v_min_f32_e32 v169, 0x42b80000, v169
	v_exp_f32_e32 v148, v148
	v_exp_f32_e32 v149, v149
	v_exp_f32_e32 v150, v150
	v_exp_f32_e32 v151, v151
	v_exp_f32_e32 v152, v152
	v_exp_f32_e32 v153, v153
	v_exp_f32_e32 v168, v168
	v_exp_f32_e32 v169, v169
	s_nop 0
	v_add_f32_e32 v148, 1.0, v148
	v_add_f32_e32 v149, 1.0, v149
	v_add_f32_e32 v150, 1.0, v150
	v_add_f32_e32 v151, 1.0, v151
	v_add_f32_e32 v152, 1.0, v152
	v_add_f32_e32 v153, 1.0, v153
	v_add_f32_e32 v168, 1.0, v168
	v_add_f32_e32 v169, 1.0, v169
	v_rcp_f32_e32 v148, v148
	v_rcp_f32_e32 v149, v149
	v_rcp_f32_e32 v152, v152
	v_rcp_f32_e32 v153, v153
	s_nop 0
	v_pk_mul_f32 v[148:149], v[148:149], v[150:151]
	v_pk_mul_f32 v[152:153], v[152:153], v[168:169]
	v_pk_mul_f32 v[42:43], v[42:43], v[148:149]
	v_pk_mul_f32 v[44:45], v[44:45], v[152:153]
	global_load_dwordx4 v[200:203], v[144:145], off
	global_load_dwordx4 v[204:207], v[144:145], off offset:256
	global_load_dwordx4 v[208:211], v[144:145], off offset:2048
	global_load_dwordx4 v[212:215], v[144:145], off offset:2304
	s_waitcnt vmcnt(8)
; DI float bflo(unsigned w) { return __uint_as_float(w << 16); }
; DI float bfhi(unsigned w) { return __uint_as_float(w & 0xffff0000u); }
; DI float fexp2(float x) { return __builtin_amdgcn_exp2f(x); }
; DI float fexp(float x) { return __builtin_amdgcn_exp2f(x * LOG2E); }
; DI float frcp(float x) { return __builtin_amdgcn_rcpf(x); }
; DI float fsigmoid(float x) { return frcp(1.0f + fexp(-x)); }
;     DI void operator()(Acc& acc, const Unit& u, int wr, int wc, int fr, int fq) const {
;     ...
;                     for (int bj = 0; bj < 2; ++bj) g[ai][m][bj] = *(const u32x4*)(base + (size_t)(ai * 128 + m * 16) * NPJ + u.k * 1024 + bj * 128);
; #pragma unroll
;             for (int ai = 0; ai < 2; ++ai)
; #pragma unroll
;                 for (int m = 0; m < 4; ++m)
; #pragma unroll
;                     for (int bj = 0; bj < 2; ++bj) { const u32x4 q = g[ai][m][bj]; f32x4& v0 = acc[ai][bj][m][0]; f32x4& v1 = acc[ai][bj][m][1];
;                         v0[0] *= bflo(q.x); v0[1] *= bfhi(q.x); v0[2] *= bflo(q.y); v0[3] *= bfhi(q.y); v1[0] *= bflo(q.z); v1[1] *= bfhi(q.z); v1[2] *= bflo(q.w); v1[3] *= bfhi(q.w); }
	v_lshlrev_b32_e32 v148, 16, v216
	v_and_b32_e32 v149, 0xffff0000, v216
	v_lshlrev_b32_e32 v150, 16, v224
	v_and_b32_e32 v151, 0xffff0000, v224
	v_lshlrev_b32_e32 v152, 16, v217
	v_and_b32_e32 v153, 0xffff0000, v217
	v_lshlrev_b32_e32 v168, 16, v225
	v_and_b32_e32 v169, 0xffff0000, v225
	v_pk_mul_f32 v[148:149], v[148:149], s[100:101] op_sel_hi:[1,0]
	v_pk_mul_f32 v[150:151], v[150:151], s[100:101] op_sel_hi:[1,0]
	v_pk_mul_f32 v[152:153], v[152:153], s[100:101] op_sel_hi:[1,0]
	v_pk_mul_f32 v[168:169], v[168:169], s[100:101] op_sel_hi:[1,0]
	v_min_f32_e32 v148, 0x42b80000, v148
	v_min_f32_e32 v149, 0x42b80000, v149
	v_min_f32_e32 v150, 0x42b80000, v150
	v_min_f32_e32 v151, 0x42b80000, v151
	v_min_f32_e32 v152, 0x42b80000, v152
	v_min_f32_e32 v153, 0x42b80000, v153
	v_min_f32_e32 v168, 0x42b80000, v168
	v_min_f32_e32 v169, 0x42b80000, v169
	v_exp_f32_e32 v148, v148
	v_exp_f32_e32 v149, v149
	v_exp_f32_e32 v150, v150
	v_exp_f32_e32 v151, v151
	v_exp_f32_e32 v152, v152
	v_exp_f32_e32 v153, v153
	v_exp_f32_e32 v168, v168
	v_exp_f32_e32 v169, v169
	s_nop 0
	v_add_f32_e32 v148, 1.0, v148
	v_add_f32_e32 v149, 1.0, v149
	v_add_f32_e32 v150, 1.0, v150
	v_add_f32_e32 v151, 1.0, v151
	v_add_f32_e32 v152, 1.0, v152
	v_add_f32_e32 v153, 1.0, v153
	v_add_f32_e32 v168, 1.0, v168
	v_add_f32_e32 v169, 1.0, v169
	v_rcp_f32_e32 v148, v148
	v_rcp_f32_e32 v149, v149
	v_rcp_f32_e32 v152, v152
	v_rcp_f32_e32 v153, v153
	s_nop 0
	v_pk_mul_f32 v[148:149], v[148:149], v[150:151]
	v_pk_mul_f32 v[152:153], v[152:153], v[168:169]
	v_pk_mul_f32 v[54:55], v[54:55], v[148:149]
	v_pk_mul_f32 v[56:57], v[56:57], v[152:153]
	v_lshlrev_b32_e32 v176, 16, v218
	v_and_b32_e32 v177, 0xffff0000, v218
	v_lshlrev_b32_e32 v178, 16, v226
	v_and_b32_e32 v179, 0xffff0000, v226
	v_lshlrev_b32_e32 v180, 16, v219
	v_and_b32_e32 v181, 0xffff0000, v219
	v_lshlrev_b32_e32 v244, 16, v227
	v_and_b32_e32 v245, 0xffff0000, v227
	v_pk_mul_f32 v[176:177], v[176:177], s[100:101] op_sel_hi:[1,0]
	v_pk_mul_f32 v[178:179], v[178:179], s[100:101] op_sel_hi:[1,0]
	v_pk_mul_f32 v[180:181], v[180:181], s[100:101] op_sel_hi:[1,0]
	v_pk_mul_f32 v[244:245], v[244:245], s[100:101] op_sel_hi:[1,0]
	v_min_f32_e32 v176, 0x42b80000, v176
	v_min_f32_e32 v177, 0x42b80000, v177
	v_min_f32_e32 v178, 0x42b80000, v178
	v_min_f32_e32 v179, 0x42b80000, v179
	v_min_f32_e32 v180, 0x42b80000, v180
	v_min_f32_e32 v181, 0x42b80000, v181
	v_min_f32_e32 v244, 0x42b80000, v244
	v_min_f32_e32 v245, 0x42b80000, v245
	v_exp_f32_e32 v176, v176
	v_exp_f32_e32 v177, v177
	v_exp_f32_e32 v178, v178
	v_exp_f32_e32 v179, v179
	v_exp_f32_e32 v180, v180
	v_exp_f32_e32 v181, v181
	v_exp_f32_e32 v244, v244
	v_exp_f32_e32 v245, v245
	s_nop 0
	v_add_f32_e32 v176, 1.0, v176
	v_add_f32_e32 v177, 1.0, v177
	v_add_f32_e32 v178, 1.0, v178
	v_add_f32_e32 v179, 1.0, v179
	v_add_f32_e32 v180, 1.0, v180
	v_add_f32_e32 v181, 1.0, v181
	v_add_f32_e32 v244, 1.0, v244
	v_add_f32_e32 v245, 1.0, v245
	v_rcp_f32_e32 v176, v176
	v_rcp_f32_e32 v177, v177
	v_rcp_f32_e32 v180, v180
	v_rcp_f32_e32 v181, v181
	s_nop 0
	v_pk_mul_f32 v[176:177], v[176:177], v[178:179]
	v_pk_mul_f32 v[180:181], v[180:181], v[244:245]
	v_pk_mul_f32 v[46:47], v[46:47], v[176:177]
	v_pk_mul_f32 v[48:49], v[48:49], v[180:181]
	v_lshlrev_b32_e32 v176, 16, v220
	v_and_b32_e32 v177, 0xffff0000, v220
	v_lshlrev_b32_e32 v178, 16, v228
	v_and_b32_e32 v179, 0xffff0000, v228
	v_lshlrev_b32_e32 v180, 16, v221
	v_and_b32_e32 v181, 0xffff0000, v221
	v_lshlrev_b32_e32 v244, 16, v229
	v_and_b32_e32 v245, 0xffff0000, v229
	v_pk_mul_f32 v[176:177], v[176:177], s[100:101] op_sel_hi:[1,0]
	v_pk_mul_f32 v[178:179], v[178:179], s[100:101] op_sel_hi:[1,0]
	v_pk_mul_f32 v[180:181], v[180:181], s[100:101] op_sel_hi:[1,0]
	v_pk_mul_f32 v[244:245], v[244:245], s[100:101] op_sel_hi:[1,0]
	v_min_f32_e32 v176, 0x42b80000, v176
	v_min_f32_e32 v177, 0x42b80000, v177
	v_min_f32_e32 v178, 0x42b80000, v178
	v_min_f32_e32 v179, 0x42b80000, v179
	v_min_f32_e32 v180, 0x42b80000, v180
	v_min_f32_e32 v181, 0x42b80000, v181
	v_min_f32_e32 v244, 0x42b80000, v244
	v_min_f32_e32 v245, 0x42b80000, v245
	v_exp_f32_e32 v176, v176
	v_exp_f32_e32 v177, v177
	v_exp_f32_e32 v178, v178
	v_exp_f32_e32 v179, v179
	v_exp_f32_e32 v180, v180
	v_exp_f32_e32 v181, v181
	v_exp_f32_e32 v244, v244
	v_exp_f32_e32 v245, v245
	s_nop 0
	v_add_f32_e32 v176, 1.0, v176
	v_add_f32_e32 v177, 1.0, v177
	v_add_f32_e32 v178, 1.0, v178
	v_add_f32_e32 v179, 1.0, v179
	v_add_f32_e32 v180, 1.0, v180
	v_add_f32_e32 v181, 1.0, v181
	v_add_f32_e32 v244, 1.0, v244
	v_add_f32_e32 v245, 1.0, v245
	v_rcp_f32_e32 v176, v176
	v_rcp_f32_e32 v177, v177
	v_rcp_f32_e32 v180, v180
	v_rcp_f32_e32 v181, v181
	s_nop 0
	v_pk_mul_f32 v[176:177], v[176:177], v[178:179]
	v_pk_mul_f32 v[180:181], v[180:181], v[244:245]
	v_pk_mul_f32 v[34:35], v[34:35], v[176:177]
	v_pk_mul_f32 v[36:37], v[36:37], v[180:181]
	v_lshlrev_b32_e32 v148, 16, v222
	v_and_b32_e32 v149, 0xffff0000, v222
	v_lshlrev_b32_e32 v150, 16, v230
	v_and_b32_e32 v151, 0xffff0000, v230
	v_lshlrev_b32_e32 v152, 16, v223
	v_and_b32_e32 v153, 0xffff0000, v223
	v_lshlrev_b32_e32 v168, 16, v231
	v_and_b32_e32 v169, 0xffff0000, v231
	v_pk_mul_f32 v[148:149], v[148:149], s[100:101] op_sel_hi:[1,0]
	v_pk_mul_f32 v[150:151], v[150:151], s[100:101] op_sel_hi:[1,0]
	v_pk_mul_f32 v[152:153], v[152:153], s[100:101] op_sel_hi:[1,0]
	v_pk_mul_f32 v[168:169], v[168:169], s[100:101] op_sel_hi:[1,0]
	v_min_f32_e32 v148, 0x42b80000, v148
	v_min_f32_e32 v149, 0x42b80000, v149
	v_min_f32_e32 v150, 0x42b80000, v150
	v_min_f32_e32 v151, 0x42b80000, v151
	v_min_f32_e32 v152, 0x42b80000, v152
	v_min_f32_e32 v153, 0x42b80000, v153
	v_min_f32_e32 v168, 0x42b80000, v168
	v_min_f32_e32 v169, 0x42b80000, v169
	v_exp_f32_e32 v148, v148
	v_exp_f32_e32 v149, v149
	v_exp_f32_e32 v150, v150
	v_exp_f32_e32 v151, v151
	v_exp_f32_e32 v152, v152
	v_exp_f32_e32 v153, v153
	v_exp_f32_e32 v168, v168
	v_exp_f32_e32 v169, v169
	s_nop 0
	v_add_f32_e32 v148, 1.0, v148
	v_add_f32_e32 v149, 1.0, v149
	v_add_f32_e32 v150, 1.0, v150
	v_add_f32_e32 v151, 1.0, v151
	v_add_f32_e32 v152, 1.0, v152
	v_add_f32_e32 v153, 1.0, v153
	v_add_f32_e32 v168, 1.0, v168
	v_add_f32_e32 v169, 1.0, v169
	v_rcp_f32_e32 v148, v148
	v_rcp_f32_e32 v149, v149
	v_rcp_f32_e32 v152, v152
	v_rcp_f32_e32 v153, v153
	s_nop 0
	v_pk_mul_f32 v[148:149], v[148:149], v[150:151]
	v_pk_mul_f32 v[152:153], v[152:153], v[168:169]
	v_pk_mul_f32 v[26:27], v[26:27], v[148:149]
	v_pk_mul_f32 v[28:29], v[28:29], v[152:153]
	s_waitcnt vmcnt(4)
; DI float bflo(unsigned w) { return __uint_as_float(w << 16); }
; DI float bfhi(unsigned w) { return __uint_as_float(w & 0xffff0000u); }
; DI float fexp2(float x) { return __builtin_amdgcn_exp2f(x); }
; DI float fexp(float x) { return __builtin_amdgcn_exp2f(x * LOG2E); }
; DI float frcp(float x) { return __builtin_amdgcn_rcpf(x); }
; DI float fsigmoid(float x) { return frcp(1.0f + fexp(-x)); }
;     DI void operator()(Acc& acc, const Unit& u, int wr, int wc, int fr, int fq) const {
;     ...
;                     for (int bj = 0; bj < 2; ++bj) g[ai][m][bj] = *(const u32x4*)(base + (size_t)(ai * 128 + m * 16) * NPJ + u.k * 1024 + bj * 128);
; #pragma unroll
;             for (int ai = 0; ai < 2; ++ai)
; #pragma unroll
;                 for (int m = 0; m < 4; ++m)
; #pragma unroll
;                     for (int bj = 0; bj < 2; ++bj) { const u32x4 q = g[ai][m][bj]; f32x4& v0 = acc[ai][bj][m][0]; f32x4& v1 = acc[ai][bj][m][1];
;                         v0[0] *= bflo(q.x); v0[1] *= bfhi(q.x); v0[2] *= bflo(q.y); v0[3] *= bfhi(q.y); v1[0] *= bflo(q.z); v1[1] *= bfhi(q.z); v1[2] *= bflo(q.w); v1[3] *= bfhi(q.w); }
	v_lshlrev_b32_e32 v148, 16, v184
	v_and_b32_e32 v149, 0xffff0000, v184
	v_lshlrev_b32_e32 v150, 16, v192
	v_and_b32_e32 v151, 0xffff0000, v192
	v_lshlrev_b32_e32 v152, 16, v185
	v_and_b32_e32 v153, 0xffff0000, v185
	v_lshlrev_b32_e32 v168, 16, v193
	v_and_b32_e32 v169, 0xffff0000, v193
	v_pk_mul_f32 v[148:149], v[148:149], s[100:101] op_sel_hi:[1,0]
	v_pk_mul_f32 v[150:151], v[150:151], s[100:101] op_sel_hi:[1,0]
	v_pk_mul_f32 v[152:153], v[152:153], s[100:101] op_sel_hi:[1,0]
	v_pk_mul_f32 v[168:169], v[168:169], s[100:101] op_sel_hi:[1,0]
	v_min_f32_e32 v148, 0x42b80000, v148
	v_min_f32_e32 v149, 0x42b80000, v149
	v_min_f32_e32 v150, 0x42b80000, v150
	v_min_f32_e32 v151, 0x42b80000, v151
	v_min_f32_e32 v152, 0x42b80000, v152
	v_min_f32_e32 v153, 0x42b80000, v153
	v_min_f32_e32 v168, 0x42b80000, v168
	v_min_f32_e32 v169, 0x42b80000, v169
	v_exp_f32_e32 v148, v148
	v_exp_f32_e32 v149, v149
	v_exp_f32_e32 v150, v150
	v_exp_f32_e32 v151, v151
	v_exp_f32_e32 v152, v152
	v_exp_f32_e32 v153, v153
	v_exp_f32_e32 v168, v168
	v_exp_f32_e32 v169, v169
	s_nop 0
	v_add_f32_e32 v148, 1.0, v148
	v_add_f32_e32 v149, 1.0, v149
	v_add_f32_e32 v150, 1.0, v150
	v_add_f32_e32 v151, 1.0, v151
	v_add_f32_e32 v152, 1.0, v152
	v_add_f32_e32 v153, 1.0, v153
	v_add_f32_e32 v168, 1.0, v168
	v_add_f32_e32 v169, 1.0, v169
	v_rcp_f32_e32 v148, v148
	v_rcp_f32_e32 v149, v149
	v_rcp_f32_e32 v152, v152
	v_rcp_f32_e32 v153, v153
	s_nop 0
	v_pk_mul_f32 v[148:149], v[148:149], v[150:151]
	v_pk_mul_f32 v[152:153], v[152:153], v[168:169]
	v_pk_mul_f32 v[38:39], v[38:39], v[148:149]
	v_pk_mul_f32 v[40:41], v[40:41], v[152:153]
	v_lshlrev_b32_e32 v176, 16, v186
	v_and_b32_e32 v177, 0xffff0000, v186
	v_lshlrev_b32_e32 v178, 16, v194
	v_and_b32_e32 v179, 0xffff0000, v194
	v_lshlrev_b32_e32 v180, 16, v187
	v_and_b32_e32 v181, 0xffff0000, v187
	v_lshlrev_b32_e32 v244, 16, v195
	v_and_b32_e32 v245, 0xffff0000, v195
	v_pk_mul_f32 v[176:177], v[176:177], s[100:101] op_sel_hi:[1,0]
	v_pk_mul_f32 v[178:179], v[178:179], s[100:101] op_sel_hi:[1,0]
	v_pk_mul_f32 v[180:181], v[180:181], s[100:101] op_sel_hi:[1,0]
	v_pk_mul_f32 v[244:245], v[244:245], s[100:101] op_sel_hi:[1,0]
	v_min_f32_e32 v176, 0x42b80000, v176
	v_min_f32_e32 v177, 0x42b80000, v177
	v_min_f32_e32 v178, 0x42b80000, v178
	v_min_f32_e32 v179, 0x42b80000, v179
	v_min_f32_e32 v180, 0x42b80000, v180
	v_min_f32_e32 v181, 0x42b80000, v181
	v_min_f32_e32 v244, 0x42b80000, v244
	v_min_f32_e32 v245, 0x42b80000, v245
	v_exp_f32_e32 v176, v176
	v_exp_f32_e32 v177, v177
	v_exp_f32_e32 v178, v178
	v_exp_f32_e32 v179, v179
	v_exp_f32_e32 v180, v180
	v_exp_f32_e32 v181, v181
	v_exp_f32_e32 v244, v244
	v_exp_f32_e32 v245, v245
	s_nop 0
	v_add_f32_e32 v176, 1.0, v176
	v_add_f32_e32 v177, 1.0, v177
	v_add_f32_e32 v178, 1.0, v178
	v_add_f32_e32 v179, 1.0, v179
	v_add_f32_e32 v180, 1.0, v180
	v_add_f32_e32 v181, 1.0, v181
	v_add_f32_e32 v244, 1.0, v244
	v_add_f32_e32 v245, 1.0, v245
	v_rcp_f32_e32 v176, v176
	v_rcp_f32_e32 v177, v177
	v_rcp_f32_e32 v180, v180
	v_rcp_f32_e32 v181, v181
	s_nop 0
	v_pk_mul_f32 v[176:177], v[176:177], v[178:179]
	v_pk_mul_f32 v[180:181], v[180:181], v[244:245]
	v_pk_mul_f32 v[30:31], v[30:31], v[176:177]
	v_pk_mul_f32 v[32:33], v[32:33], v[180:181]
	v_lshlrev_b32_e32 v176, 16, v188
	v_and_b32_e32 v177, 0xffff0000, v188
	v_lshlrev_b32_e32 v178, 16, v196
	v_and_b32_e32 v179, 0xffff0000, v196
	v_lshlrev_b32_e32 v180, 16, v189
	v_and_b32_e32 v181, 0xffff0000, v189
	v_lshlrev_b32_e32 v244, 16, v197
	v_and_b32_e32 v245, 0xffff0000, v197
	v_pk_mul_f32 v[176:177], v[176:177], s[100:101] op_sel_hi:[1,0]
	v_pk_mul_f32 v[178:179], v[178:179], s[100:101] op_sel_hi:[1,0]
	v_pk_mul_f32 v[180:181], v[180:181], s[100:101] op_sel_hi:[1,0]
	v_pk_mul_f32 v[244:245], v[244:245], s[100:101] op_sel_hi:[1,0]
	v_min_f32_e32 v176, 0x42b80000, v176
	v_min_f32_e32 v177, 0x42b80000, v177
	v_min_f32_e32 v178, 0x42b80000, v178
	v_min_f32_e32 v179, 0x42b80000, v179
	v_min_f32_e32 v180, 0x42b80000, v180
	v_min_f32_e32 v181, 0x42b80000, v181
	v_min_f32_e32 v244, 0x42b80000, v244
	v_min_f32_e32 v245, 0x42b80000, v245
	v_exp_f32_e32 v176, v176
	v_exp_f32_e32 v177, v177
	v_exp_f32_e32 v178, v178
	v_exp_f32_e32 v179, v179
	v_exp_f32_e32 v180, v180
	v_exp_f32_e32 v181, v181
	v_exp_f32_e32 v244, v244
	v_exp_f32_e32 v245, v245
	s_nop 0
	v_add_f32_e32 v176, 1.0, v176
	v_add_f32_e32 v177, 1.0, v177
	v_add_f32_e32 v178, 1.0, v178
	v_add_f32_e32 v179, 1.0, v179
	v_add_f32_e32 v180, 1.0, v180
	v_add_f32_e32 v181, 1.0, v181
	v_add_f32_e32 v244, 1.0, v244
	v_add_f32_e32 v245, 1.0, v245
	v_rcp_f32_e32 v176, v176
	v_rcp_f32_e32 v177, v177
	v_rcp_f32_e32 v180, v180
	v_rcp_f32_e32 v181, v181
	s_nop 0
	v_pk_mul_f32 v[176:177], v[176:177], v[178:179]
	v_pk_mul_f32 v[180:181], v[180:181], v[244:245]
	v_pk_mul_f32 v[18:19], v[18:19], v[176:177]
	v_pk_mul_f32 v[20:21], v[20:21], v[180:181]
	v_lshlrev_b32_e32 v148, 16, v190
	v_and_b32_e32 v149, 0xffff0000, v190
	v_lshlrev_b32_e32 v150, 16, v198
	v_and_b32_e32 v151, 0xffff0000, v198
	v_lshlrev_b32_e32 v152, 16, v191
	v_and_b32_e32 v153, 0xffff0000, v191
	v_lshlrev_b32_e32 v168, 16, v199
	v_and_b32_e32 v169, 0xffff0000, v199
	v_pk_mul_f32 v[148:149], v[148:149], s[100:101] op_sel_hi:[1,0]
	v_pk_mul_f32 v[150:151], v[150:151], s[100:101] op_sel_hi:[1,0]
	v_pk_mul_f32 v[152:153], v[152:153], s[100:101] op_sel_hi:[1,0]
	v_pk_mul_f32 v[168:169], v[168:169], s[100:101] op_sel_hi:[1,0]
	v_min_f32_e32 v148, 0x42b80000, v148
	v_min_f32_e32 v149, 0x42b80000, v149
	v_min_f32_e32 v150, 0x42b80000, v150
	v_min_f32_e32 v151, 0x42b80000, v151
	v_min_f32_e32 v152, 0x42b80000, v152
	v_min_f32_e32 v153, 0x42b80000, v153
	v_min_f32_e32 v168, 0x42b80000, v168
	v_min_f32_e32 v169, 0x42b80000, v169
	v_exp_f32_e32 v148, v148
	v_exp_f32_e32 v149, v149
	v_exp_f32_e32 v150, v150
	v_exp_f32_e32 v151, v151
	v_exp_f32_e32 v152, v152
	v_exp_f32_e32 v153, v153
	v_exp_f32_e32 v168, v168
	v_exp_f32_e32 v169, v169
	s_nop 0
	v_add_f32_e32 v148, 1.0, v148
	v_add_f32_e32 v149, 1.0, v149
	v_add_f32_e32 v150, 1.0, v150
	v_add_f32_e32 v151, 1.0, v151
	v_add_f32_e32 v152, 1.0, v152
	v_add_f32_e32 v153, 1.0, v153
	v_add_f32_e32 v168, 1.0, v168
	v_add_f32_e32 v169, 1.0, v169
	v_rcp_f32_e32 v148, v148
	v_rcp_f32_e32 v149, v149
	v_rcp_f32_e32 v152, v152
	v_rcp_f32_e32 v153, v153
	s_nop 0
	v_pk_mul_f32 v[148:149], v[148:149], v[150:151]
	v_pk_mul_f32 v[152:153], v[152:153], v[168:169]
	v_pk_mul_f32 v[10:11], v[10:11], v[148:149]
	v_pk_mul_f32 v[12:13], v[12:13], v[152:153]
	s_waitcnt vmcnt(0)
; DI float bflo(unsigned w) { return __uint_as_float(w << 16); }
; DI float bfhi(unsigned w) { return __uint_as_float(w & 0xffff0000u); }
; DI float fexp2(float x) { return __builtin_amdgcn_exp2f(x); }
; DI float fexp(float x) { return __builtin_amdgcn_exp2f(x * LOG2E); }
; DI float frcp(float x) { return __builtin_amdgcn_rcpf(x); }
; DI float fsigmoid(float x) { return frcp(1.0f + fexp(-x)); }
;     DI void operator()(Acc& acc, const Unit& u, int wr, int wc, int fr, int fq) const {
;     ...
;                     for (int bj = 0; bj < 2; ++bj) g[ai][m][bj] = *(const u32x4*)(base + (size_t)(ai * 128 + m * 16) * NPJ + u.k * 1024 + bj * 128);
; #pragma unroll
;             for (int ai = 0; ai < 2; ++ai)
; #pragma unroll
;                 for (int m = 0; m < 4; ++m)
; #pragma unroll
;                     for (int bj = 0; bj < 2; ++bj) { const u32x4 q = g[ai][m][bj]; f32x4& v0 = acc[ai][bj][m][0]; f32x4& v1 = acc[ai][bj][m][1];
;                         v0[0] *= bflo(q.x); v0[1] *= bfhi(q.x); v0[2] *= bflo(q.y); v0[3] *= bfhi(q.y); v1[0] *= bflo(q.z); v1[1] *= bfhi(q.z); v1[2] *= bflo(q.w); v1[3] *= bfhi(q.w); }
	v_lshlrev_b32_e32 v148, 16, v200
	v_and_b32_e32 v149, 0xffff0000, v200
	v_lshlrev_b32_e32 v150, 16, v208
	v_and_b32_e32 v151, 0xffff0000, v208
	v_lshlrev_b32_e32 v152, 16, v201
	v_and_b32_e32 v153, 0xffff0000, v201
	v_lshlrev_b32_e32 v168, 16, v209
	v_and_b32_e32 v169, 0xffff0000, v209
	v_pk_mul_f32 v[148:149], v[148:149], s[100:101] op_sel_hi:[1,0]
	v_pk_mul_f32 v[150:151], v[150:151], s[100:101] op_sel_hi:[1,0]
	v_pk_mul_f32 v[152:153], v[152:153], s[100:101] op_sel_hi:[1,0]
	v_pk_mul_f32 v[168:169], v[168:169], s[100:101] op_sel_hi:[1,0]
	v_min_f32_e32 v148, 0x42b80000, v148
	v_min_f32_e32 v149, 0x42b80000, v149
	v_min_f32_e32 v150, 0x42b80000, v150
	v_min_f32_e32 v151, 0x42b80000, v151
	v_min_f32_e32 v152, 0x42b80000, v152
	v_min_f32_e32 v153, 0x42b80000, v153
	v_min_f32_e32 v168, 0x42b80000, v168
	v_min_f32_e32 v169, 0x42b80000, v169
	v_exp_f32_e32 v148, v148
	v_exp_f32_e32 v149, v149
	v_exp_f32_e32 v150, v150
	v_exp_f32_e32 v151, v151
	v_exp_f32_e32 v152, v152
	v_exp_f32_e32 v153, v153
	v_exp_f32_e32 v168, v168
	v_exp_f32_e32 v169, v169
	s_nop 0
	v_add_f32_e32 v148, 1.0, v148
	v_add_f32_e32 v149, 1.0, v149
	v_add_f32_e32 v150, 1.0, v150
	v_add_f32_e32 v151, 1.0, v151
	v_add_f32_e32 v152, 1.0, v152
	v_add_f32_e32 v153, 1.0, v153
	v_add_f32_e32 v168, 1.0, v168
	v_add_f32_e32 v169, 1.0, v169
	v_rcp_f32_e32 v148, v148
	v_rcp_f32_e32 v149, v149
	v_rcp_f32_e32 v152, v152
	v_rcp_f32_e32 v153, v153
	s_nop 0
	v_pk_mul_f32 v[148:149], v[148:149], v[150:151]
	v_pk_mul_f32 v[152:153], v[152:153], v[168:169]
	v_pk_mul_f32 v[22:23], v[22:23], v[148:149]
	v_pk_mul_f32 v[24:25], v[24:25], v[152:153]
	v_lshlrev_b32_e32 v176, 16, v202
	v_and_b32_e32 v177, 0xffff0000, v202
	v_lshlrev_b32_e32 v178, 16, v210
	v_and_b32_e32 v179, 0xffff0000, v210
	v_lshlrev_b32_e32 v180, 16, v203
	v_and_b32_e32 v181, 0xffff0000, v203
	v_lshlrev_b32_e32 v244, 16, v211
	v_and_b32_e32 v245, 0xffff0000, v211
	v_pk_mul_f32 v[176:177], v[176:177], s[100:101] op_sel_hi:[1,0]
	v_pk_mul_f32 v[178:179], v[178:179], s[100:101] op_sel_hi:[1,0]
	v_pk_mul_f32 v[180:181], v[180:181], s[100:101] op_sel_hi:[1,0]
	v_pk_mul_f32 v[244:245], v[244:245], s[100:101] op_sel_hi:[1,0]
	v_min_f32_e32 v176, 0x42b80000, v176
	v_min_f32_e32 v177, 0x42b80000, v177
	v_min_f32_e32 v178, 0x42b80000, v178
	v_min_f32_e32 v179, 0x42b80000, v179
	v_min_f32_e32 v180, 0x42b80000, v180
	v_min_f32_e32 v181, 0x42b80000, v181
	v_min_f32_e32 v244, 0x42b80000, v244
	v_min_f32_e32 v245, 0x42b80000, v245
	v_exp_f32_e32 v176, v176
	v_exp_f32_e32 v177, v177
	v_exp_f32_e32 v178, v178
	v_exp_f32_e32 v179, v179
	v_exp_f32_e32 v180, v180
	v_exp_f32_e32 v181, v181
	v_exp_f32_e32 v244, v244
	v_exp_f32_e32 v245, v245
	s_nop 0
	v_add_f32_e32 v176, 1.0, v176
	v_add_f32_e32 v177, 1.0, v177
	v_add_f32_e32 v178, 1.0, v178
	v_add_f32_e32 v179, 1.0, v179
	v_add_f32_e32 v180, 1.0, v180
	v_add_f32_e32 v181, 1.0, v181
	v_add_f32_e32 v244, 1.0, v244
	v_add_f32_e32 v245, 1.0, v245
	v_rcp_f32_e32 v176, v176
	v_rcp_f32_e32 v177, v177
	v_rcp_f32_e32 v180, v180
	v_rcp_f32_e32 v181, v181
	s_nop 0
	v_pk_mul_f32 v[176:177], v[176:177], v[178:179]
	v_pk_mul_f32 v[180:181], v[180:181], v[244:245]
	v_pk_mul_f32 v[14:15], v[14:15], v[176:177]
	v_pk_mul_f32 v[16:17], v[16:17], v[180:181]
	v_lshlrev_b32_e32 v176, 16, v204
	v_and_b32_e32 v177, 0xffff0000, v204
	v_lshlrev_b32_e32 v178, 16, v212
	v_and_b32_e32 v179, 0xffff0000, v212
	v_lshlrev_b32_e32 v180, 16, v205
	v_and_b32_e32 v181, 0xffff0000, v205
	v_lshlrev_b32_e32 v244, 16, v213
	v_and_b32_e32 v245, 0xffff0000, v213
	v_pk_mul_f32 v[176:177], v[176:177], s[100:101] op_sel_hi:[1,0]
	v_pk_mul_f32 v[178:179], v[178:179], s[100:101] op_sel_hi:[1,0]
	v_pk_mul_f32 v[180:181], v[180:181], s[100:101] op_sel_hi:[1,0]
	v_pk_mul_f32 v[244:245], v[244:245], s[100:101] op_sel_hi:[1,0]
	v_min_f32_e32 v176, 0x42b80000, v176
	v_min_f32_e32 v177, 0x42b80000, v177
	v_min_f32_e32 v178, 0x42b80000, v178
	v_min_f32_e32 v179, 0x42b80000, v179
	v_min_f32_e32 v180, 0x42b80000, v180
	v_min_f32_e32 v181, 0x42b80000, v181
	v_min_f32_e32 v244, 0x42b80000, v244
	v_min_f32_e32 v245, 0x42b80000, v245
	v_exp_f32_e32 v176, v176
	v_exp_f32_e32 v177, v177
	v_exp_f32_e32 v178, v178
	v_exp_f32_e32 v179, v179
	v_exp_f32_e32 v180, v180
	v_exp_f32_e32 v181, v181
	v_exp_f32_e32 v244, v244
	v_exp_f32_e32 v245, v245
	s_nop 0
	v_add_f32_e32 v176, 1.0, v176
	v_add_f32_e32 v177, 1.0, v177
	v_add_f32_e32 v178, 1.0, v178
	v_add_f32_e32 v179, 1.0, v179
	v_add_f32_e32 v180, 1.0, v180
	v_add_f32_e32 v181, 1.0, v181
	v_add_f32_e32 v244, 1.0, v244
	v_add_f32_e32 v245, 1.0, v245
	v_rcp_f32_e32 v176, v176
	v_rcp_f32_e32 v177, v177
	v_rcp_f32_e32 v180, v180
	v_rcp_f32_e32 v181, v181
	s_nop 0
	v_pk_mul_f32 v[176:177], v[176:177], v[178:179]
	v_pk_mul_f32 v[180:181], v[180:181], v[244:245]
	v_pk_mul_f32 v[6:7], v[6:7], v[176:177]
	v_pk_mul_f32 v[8:9], v[8:9], v[180:181]
	v_lshlrev_b32_e32 v148, 16, v206
	v_and_b32_e32 v149, 0xffff0000, v206
	v_lshlrev_b32_e32 v150, 16, v214
	v_and_b32_e32 v151, 0xffff0000, v214
	v_lshlrev_b32_e32 v152, 16, v207
	v_and_b32_e32 v153, 0xffff0000, v207
	v_lshlrev_b32_e32 v168, 16, v215
	v_and_b32_e32 v169, 0xffff0000, v215
	v_pk_mul_f32 v[148:149], v[148:149], s[100:101] op_sel_hi:[1,0]
	v_pk_mul_f32 v[150:151], v[150:151], s[100:101] op_sel_hi:[1,0]
	v_pk_mul_f32 v[152:153], v[152:153], s[100:101] op_sel_hi:[1,0]
	v_pk_mul_f32 v[168:169], v[168:169], s[100:101] op_sel_hi:[1,0]
	v_min_f32_e32 v148, 0x42b80000, v148
	v_min_f32_e32 v149, 0x42b80000, v149
	v_min_f32_e32 v150, 0x42b80000, v150
	v_min_f32_e32 v151, 0x42b80000, v151
	v_min_f32_e32 v152, 0x42b80000, v152
	v_min_f32_e32 v153, 0x42b80000, v153
	v_min_f32_e32 v168, 0x42b80000, v168
	v_min_f32_e32 v169, 0x42b80000, v169
	v_exp_f32_e32 v148, v148
	v_exp_f32_e32 v149, v149
	v_exp_f32_e32 v150, v150
	v_exp_f32_e32 v151, v151
	v_exp_f32_e32 v152, v152
	v_exp_f32_e32 v153, v153
	v_exp_f32_e32 v168, v168
	v_exp_f32_e32 v169, v169
	s_nop 0
	v_add_f32_e32 v148, 1.0, v148
	v_add_f32_e32 v149, 1.0, v149
	v_add_f32_e32 v150, 1.0, v150
	v_add_f32_e32 v151, 1.0, v151
	v_add_f32_e32 v152, 1.0, v152
	v_add_f32_e32 v153, 1.0, v153
	v_add_f32_e32 v168, 1.0, v168
	v_add_f32_e32 v169, 1.0, v169
	v_rcp_f32_e32 v148, v148
	v_rcp_f32_e32 v149, v149
	v_rcp_f32_e32 v152, v152
	v_rcp_f32_e32 v153, v153
	s_nop 0
	v_pk_mul_f32 v[148:149], v[148:149], v[150:151]
	v_pk_mul_f32 v[152:153], v[152:153], v[168:169]
	v_pk_mul_f32 v[2:3], v[2:3], v[148:149]
	v_pk_mul_f32 v[4:5], v[4:5], v[152:153]
	s_branch .Lup6_tail
; DI float bflo(unsigned w) { return __uint_as_float(w << 16); }
; DI float bfhi(unsigned w) { return __uint_as_float(w & 0xffff0000u); }
; DI u32x4 pack8(f32x4 a, f32x4 b) { u32x4 w; w.x = pk2(a[0], a[1]); w.y = pk2(a[2], a[3]); w.z = pk2(b[0], b[1]); w.w = pk2(b[2], b[3]); return w; }
; DI float fexp2(float x) { return __builtin_amdgcn_exp2f(x); }
; DI float fexp(float x) { return __builtin_amdgcn_exp2f(x * LOG2E); }
; DI float frcp(float x) { return __builtin_amdgcn_rcpf(x); }
; DI float fsigmoid(float x) { return frcp(1.0f + fexp(-x)); }
;     DI void operator()(Acc& acc, const Unit& u, int wr, int wc, int fr, int fq) const {
;     ...
;                     for (int bj = 0; bj < 2; ++bj) g[ai][m][bj] = *(const u32x4*)(base + (size_t)(ai * 128 + m * 16) * NPJ + u.k * 1024 + bj * 128);
; #pragma unroll
;             for (int ai = 0; ai < 2; ++ai)
; #pragma unroll
;                 for (int m = 0; m < 4; ++m)
; #pragma unroll
;                     for (int bj = 0; bj < 2; ++bj) { const u32x4 q = g[ai][m][bj]; f32x4& v0 = acc[ai][bj][m][0]; f32x4& v1 = acc[ai][bj][m][1];
;                         v0[0] *= bflo(q.x); v0[1] *= bfhi(q.x); v0[2] *= bflo(q.y); v0[3] *= bfhi(q.y); v1[0] *= bflo(q.z); v1[1] *= bfhi(q.z); v1[2] *= bflo(q.w); v1[3] *= bfhi(q.w); }
;     ...
;                     for (int bj = 0; bj < 2; ++bj) *(u32x4*)(base + (size_t)(ai * 128 + m * 16) * NPJ + bj * 128) = pack8(acc[ai][bj][m][0], acc[ai][bj][m][1]);
.Lup6_final:
	global_load_dwordx4 v[184:187], v[130:131], off
	global_load_dwordx4 v[188:191], v[130:131], off offset:256
	global_load_dwordx4 v[192:195], v[132:133], off
	global_load_dwordx4 v[196:199], v[132:133], off offset:256
	global_load_dwordx4 v[200:203], v[134:135], off
	global_load_dwordx4 v[204:207], v[134:135], off offset:256
	global_load_dwordx4 v[208:211], v[136:137], off
	global_load_dwordx4 v[212:215], v[136:137], off offset:256
	global_load_dwordx4 v[216:219], v[138:139], off
	global_load_dwordx4 v[220:223], v[138:139], off offset:256
	global_load_dwordx4 v[224:227], v[140:141], off
	global_load_dwordx4 v[228:231], v[140:141], off offset:256
	s_waitcnt vmcnt(10)
	v_lshlrev_b32_e32 v148, 16, v184
	v_and_b32_e32 v149, 0xffff0000, v184
	v_lshlrev_b32_e32 v150, 16, v185
	v_and_b32_e32 v151, 0xffff0000, v185
	v_lshlrev_b32_e32 v152, 16, v186
	v_and_b32_e32 v153, 0xffff0000, v186
	v_lshlrev_b32_e32 v168, 16, v187
	v_and_b32_e32 v169, 0xffff0000, v187
	v_pk_mul_f32 v[148:149], v[148:149], s[100:101] op_sel_hi:[1,0]
	v_pk_mul_f32 v[150:151], v[150:151], s[100:101] op_sel_hi:[1,0]
	v_pk_mul_f32 v[152:153], v[152:153], s[100:101] op_sel_hi:[1,0]
	v_pk_mul_f32 v[168:169], v[168:169], s[100:101] op_sel_hi:[1,0]
	v_min_f32_e32 v148, 0x42b80000, v148
	v_min_f32_e32 v149, 0x42b80000, v149
	v_min_f32_e32 v150, 0x42b80000, v150
	v_min_f32_e32 v151, 0x42b80000, v151
	v_min_f32_e32 v152, 0x42b80000, v152
	v_min_f32_e32 v153, 0x42b80000, v153
	v_min_f32_e32 v168, 0x42b80000, v168
	v_min_f32_e32 v169, 0x42b80000, v169
	v_exp_f32_e32 v148, v148
	v_exp_f32_e32 v149, v149
	v_exp_f32_e32 v150, v150
	v_exp_f32_e32 v151, v151
	v_exp_f32_e32 v152, v152
	v_exp_f32_e32 v153, v153
	v_exp_f32_e32 v168, v168
	v_exp_f32_e32 v169, v169
	s_nop 0
	v_add_f32_e32 v148, 1.0, v148
	v_add_f32_e32 v149, 1.0, v149
	v_add_f32_e32 v150, 1.0, v150
	v_add_f32_e32 v151, 1.0, v151
	v_add_f32_e32 v152, 1.0, v152
	v_add_f32_e32 v153, 1.0, v153
	v_add_f32_e32 v168, 1.0, v168
	v_add_f32_e32 v169, 1.0, v169
	v_rcp_f32_e32 v148, v148
	v_rcp_f32_e32 v149, v149
	v_rcp_f32_e32 v150, v150
	v_rcp_f32_e32 v151, v151
	v_rcp_f32_e32 v152, v152
	v_rcp_f32_e32 v153, v153
	v_rcp_f32_e32 v168, v168
	v_rcp_f32_e32 v169, v169
	s_nop 0
	v_pk_mul_f32 v[126:127], v[126:127], v[148:149]
	v_pk_mul_f32 v[128:129], v[128:129], v[150:151]
	v_pk_mul_f32 v[122:123], v[122:123], v[152:153]
	v_pk_mul_f32 v[124:125], v[124:125], v[168:169]
	v_cvt_pk_bf16_f32 v184, v126, v127
	v_cvt_pk_bf16_f32 v185, v128, v129
	v_cvt_pk_bf16_f32 v186, v122, v123
	v_cvt_pk_bf16_f32 v187, v124, v125
	v_lshlrev_b32_e32 v176, 16, v188
	v_and_b32_e32 v177, 0xffff0000, v188
	v_lshlrev_b32_e32 v178, 16, v189
	v_and_b32_e32 v179, 0xffff0000, v189
	v_lshlrev_b32_e32 v180, 16, v190
	v_and_b32_e32 v181, 0xffff0000, v190
	v_lshlrev_b32_e32 v244, 16, v191
	v_and_b32_e32 v245, 0xffff0000, v191
	v_pk_mul_f32 v[176:177], v[176:177], s[100:101] op_sel_hi:[1,0]
	v_pk_mul_f32 v[178:179], v[178:179], s[100:101] op_sel_hi:[1,0]
	v_pk_mul_f32 v[180:181], v[180:181], s[100:101] op_sel_hi:[1,0]
	v_pk_mul_f32 v[244:245], v[244:245], s[100:101] op_sel_hi:[1,0]
	v_min_f32_e32 v176, 0x42b80000, v176
	v_min_f32_e32 v177, 0x42b80000, v177
	v_min_f32_e32 v178, 0x42b80000, v178
	v_min_f32_e32 v179, 0x42b80000, v179
	v_min_f32_e32 v180, 0x42b80000, v180
	v_min_f32_e32 v181, 0x42b80000, v181
	v_min_f32_e32 v244, 0x42b80000, v244
	v_min_f32_e32 v245, 0x42b80000, v245
	v_exp_f32_e32 v176, v176
	v_exp_f32_e32 v177, v177
	v_exp_f32_e32 v178, v178
	v_exp_f32_e32 v179, v179
	v_exp_f32_e32 v180, v180
	v_exp_f32_e32 v181, v181
	v_exp_f32_e32 v244, v244
	v_exp_f32_e32 v245, v245
	s_nop 0
	v_add_f32_e32 v176, 1.0, v176
	v_add_f32_e32 v177, 1.0, v177
	v_add_f32_e32 v178, 1.0, v178
	v_add_f32_e32 v179, 1.0, v179
	v_add_f32_e32 v180, 1.0, v180
	v_add_f32_e32 v181, 1.0, v181
	v_add_f32_e32 v244, 1.0, v244
	v_add_f32_e32 v245, 1.0, v245
	v_rcp_f32_e32 v176, v176
	v_rcp_f32_e32 v177, v177
	v_rcp_f32_e32 v178, v178
	v_rcp_f32_e32 v179, v179
	v_rcp_f32_e32 v180, v180
	v_rcp_f32_e32 v181, v181
	v_rcp_f32_e32 v244, v244
	v_rcp_f32_e32 v245, v245
	s_nop 0
	v_pk_mul_f32 v[114:115], v[114:115], v[176:177]
	v_pk_mul_f32 v[116:117], v[116:117], v[178:179]
	v_pk_mul_f32 v[110:111], v[110:111], v[180:181]
	v_pk_mul_f32 v[112:113], v[112:113], v[244:245]
	v_cvt_pk_bf16_f32 v188, v114, v115
	v_cvt_pk_bf16_f32 v189, v116, v117
	v_cvt_pk_bf16_f32 v190, v110, v111
	v_cvt_pk_bf16_f32 v191, v112, v113
	global_store_dwordx4 v[130:131], v[184:187], off offset:-4096
	global_store_dwordx4 v[130:131], v[188:191], off offset:-3840
	s_nop 1
	global_load_dwordx4 v[184:187], v[142:143], off
	global_load_dwordx4 v[188:191], v[142:143], off offset:256
	s_waitcnt vmcnt(12)
; DI float bflo(unsigned w) { return __uint_as_float(w << 16); }
; DI float bfhi(unsigned w) { return __uint_as_float(w & 0xffff0000u); }
; DI u32x4 pack8(f32x4 a, f32x4 b) { u32x4 w; w.x = pk2(a[0], a[1]); w.y = pk2(a[2], a[3]); w.z = pk2(b[0], b[1]); w.w = pk2(b[2], b[3]); return w; }
; DI float fexp2(float x) { return __builtin_amdgcn_exp2f(x); }
; DI float fexp(float x) { return __builtin_amdgcn_exp2f(x * LOG2E); }
; DI float frcp(float x) { return __builtin_amdgcn_rcpf(x); }
; DI float fsigmoid(float x) { return frcp(1.0f + fexp(-x)); }
;     DI void operator()(Acc& acc, const Unit& u, int wr, int wc, int fr, int fq) const {
;     ...
;                     for (int bj = 0; bj < 2; ++bj) g[ai][m][bj] = *(const u32x4*)(base + (size_t)(ai * 128 + m * 16) * NPJ + u.k * 1024 + bj * 128);
; #pragma unroll
;             for (int ai = 0; ai < 2; ++ai)
; #pragma unroll
;                 for (int m = 0; m < 4; ++m)
; #pragma unroll
;                     for (int bj = 0; bj < 2; ++bj) { const u32x4 q = g[ai][m][bj]; f32x4& v0 = acc[ai][bj][m][0]; f32x4& v1 = acc[ai][bj][m][1];
;                         v0[0] *= bflo(q.x); v0[1] *= bfhi(q.x); v0[2] *= bflo(q.y); v0[3] *= bfhi(q.y); v1[0] *= bflo(q.z); v1[1] *= bfhi(q.z); v1[2] *= bflo(q.w); v1[3] *= bfhi(q.w); }
;     ...
;                     for (int bj = 0; bj < 2; ++bj) *(u32x4*)(base + (size_t)(ai * 128 + m * 16) * NPJ + bj * 128) = pack8(acc[ai][bj][m][0], acc[ai][bj][m][1]);
	v_lshlrev_b32_e32 v148, 16, v192
	v_and_b32_e32 v149, 0xffff0000, v192
	v_lshlrev_b32_e32 v150, 16, v193
	v_and_b32_e32 v151, 0xffff0000, v193
	v_lshlrev_b32_e32 v152, 16, v194
	v_and_b32_e32 v153, 0xffff0000, v194
	v_lshlrev_b32_e32 v168, 16, v195
	v_and_b32_e32 v169, 0xffff0000, v195
	v_pk_mul_f32 v[148:149], v[148:149], s[100:101] op_sel_hi:[1,0]
	v_pk_mul_f32 v[150:151], v[150:151], s[100:101] op_sel_hi:[1,0]
	v_pk_mul_f32 v[152:153], v[152:153], s[100:101] op_sel_hi:[1,0]
	v_pk_mul_f32 v[168:169], v[168:169], s[100:101] op_sel_hi:[1,0]
	v_min_f32_e32 v148, 0x42b80000, v148
	v_min_f32_e32 v149, 0x42b80000, v149
	v_min_f32_e32 v150, 0x42b80000, v150
	v_min_f32_e32 v151, 0x42b80000, v151
	v_min_f32_e32 v152, 0x42b80000, v152
	v_min_f32_e32 v153, 0x42b80000, v153
	v_min_f32_e32 v168, 0x42b80000, v168
	v_min_f32_e32 v169, 0x42b80000, v169
	v_exp_f32_e32 v148, v148
	v_exp_f32_e32 v149, v149
	v_exp_f32_e32 v150, v150
	v_exp_f32_e32 v151, v151
	v_exp_f32_e32 v152, v152
	v_exp_f32_e32 v153, v153
	v_exp_f32_e32 v168, v168
	v_exp_f32_e32 v169, v169
	s_nop 0
	v_add_f32_e32 v148, 1.0, v148
	v_add_f32_e32 v149, 1.0, v149
	v_add_f32_e32 v150, 1.0, v150
	v_add_f32_e32 v151, 1.0, v151
	v_add_f32_e32 v152, 1.0, v152
	v_add_f32_e32 v153, 1.0, v153
	v_add_f32_e32 v168, 1.0, v168
	v_add_f32_e32 v169, 1.0, v169
	v_rcp_f32_e32 v148, v148
	v_rcp_f32_e32 v149, v149
	v_rcp_f32_e32 v150, v150
	v_rcp_f32_e32 v151, v151
	v_rcp_f32_e32 v152, v152
	v_rcp_f32_e32 v153, v153
	v_rcp_f32_e32 v168, v168
	v_rcp_f32_e32 v169, v169
	s_nop 0
	v_pk_mul_f32 v[118:119], v[118:119], v[148:149]
	v_pk_mul_f32 v[120:121], v[120:121], v[150:151]
	v_pk_mul_f32 v[106:107], v[106:107], v[152:153]
	v_pk_mul_f32 v[108:109], v[108:109], v[168:169]
	v_cvt_pk_bf16_f32 v192, v118, v119
	v_cvt_pk_bf16_f32 v193, v120, v121
	v_cvt_pk_bf16_f32 v194, v106, v107
	v_cvt_pk_bf16_f32 v195, v108, v109
	v_lshlrev_b32_e32 v176, 16, v196
	v_and_b32_e32 v177, 0xffff0000, v196
	v_lshlrev_b32_e32 v178, 16, v197
	v_and_b32_e32 v179, 0xffff0000, v197
	v_lshlrev_b32_e32 v180, 16, v198
	v_and_b32_e32 v181, 0xffff0000, v198
	v_lshlrev_b32_e32 v244, 16, v199
	v_and_b32_e32 v245, 0xffff0000, v199
	v_pk_mul_f32 v[176:177], v[176:177], s[100:101] op_sel_hi:[1,0]
	v_pk_mul_f32 v[178:179], v[178:179], s[100:101] op_sel_hi:[1,0]
	v_pk_mul_f32 v[180:181], v[180:181], s[100:101] op_sel_hi:[1,0]
	v_pk_mul_f32 v[244:245], v[244:245], s[100:101] op_sel_hi:[1,0]
	v_min_f32_e32 v176, 0x42b80000, v176
	v_min_f32_e32 v177, 0x42b80000, v177
	v_min_f32_e32 v178, 0x42b80000, v178
	v_min_f32_e32 v179, 0x42b80000, v179
	v_min_f32_e32 v180, 0x42b80000, v180
	v_min_f32_e32 v181, 0x42b80000, v181
	v_min_f32_e32 v244, 0x42b80000, v244
	v_min_f32_e32 v245, 0x42b80000, v245
	v_exp_f32_e32 v176, v176
	v_exp_f32_e32 v177, v177
	v_exp_f32_e32 v178, v178
	v_exp_f32_e32 v179, v179
	v_exp_f32_e32 v180, v180
	v_exp_f32_e32 v181, v181
	v_exp_f32_e32 v244, v244
	v_exp_f32_e32 v245, v245
	s_nop 0
	v_add_f32_e32 v176, 1.0, v176
	v_add_f32_e32 v177, 1.0, v177
	v_add_f32_e32 v178, 1.0, v178
	v_add_f32_e32 v179, 1.0, v179
	v_add_f32_e32 v180, 1.0, v180
	v_add_f32_e32 v181, 1.0, v181
	v_add_f32_e32 v244, 1.0, v244
	v_add_f32_e32 v245, 1.0, v245
	v_rcp_f32_e32 v176, v176
	v_rcp_f32_e32 v177, v177
	v_rcp_f32_e32 v178, v178
	v_rcp_f32_e32 v179, v179
	v_rcp_f32_e32 v180, v180
	v_rcp_f32_e32 v181, v181
	v_rcp_f32_e32 v244, v244
	v_rcp_f32_e32 v245, v245
	s_nop 0
	v_pk_mul_f32 v[98:99], v[98:99], v[176:177]
	v_pk_mul_f32 v[100:101], v[100:101], v[178:179]
	v_pk_mul_f32 v[90:91], v[90:91], v[180:181]
	v_pk_mul_f32 v[92:93], v[92:93], v[244:245]
	v_cvt_pk_bf16_f32 v196, v98, v99
	v_cvt_pk_bf16_f32 v197, v100, v101
	v_cvt_pk_bf16_f32 v198, v90, v91
	v_cvt_pk_bf16_f32 v199, v92, v93
	global_store_dwordx4 v[132:133], v[192:195], off offset:-4096
	global_store_dwordx4 v[132:133], v[196:199], off offset:-3840
	s_nop 1
	global_load_dwordx4 v[192:195], v[144:145], off
	global_load_dwordx4 v[196:199], v[144:145], off offset:256
	s_waitcnt vmcnt(14)
	v_lshlrev_b32_e32 v148, 16, v200
	v_and_b32_e32 v149, 0xffff0000, v200
	v_lshlrev_b32_e32 v150, 16, v201
	v_and_b32_e32 v151, 0xffff0000, v201
	v_lshlrev_b32_e32 v152, 16, v202
	v_and_b32_e32 v153, 0xffff0000, v202
	v_lshlrev_b32_e32 v168, 16, v203
	v_and_b32_e32 v169, 0xffff0000, v203
	v_pk_mul_f32 v[148:149], v[148:149], s[100:101] op_sel_hi:[1,0]
	v_pk_mul_f32 v[150:151], v[150:151], s[100:101] op_sel_hi:[1,0]
	v_pk_mul_f32 v[152:153], v[152:153], s[100:101] op_sel_hi:[1,0]
	v_pk_mul_f32 v[168:169], v[168:169], s[100:101] op_sel_hi:[1,0]
	v_min_f32_e32 v148, 0x42b80000, v148
	v_min_f32_e32 v149, 0x42b80000, v149
	v_min_f32_e32 v150, 0x42b80000, v150
	v_min_f32_e32 v151, 0x42b80000, v151
	v_min_f32_e32 v152, 0x42b80000, v152
	v_min_f32_e32 v153, 0x42b80000, v153
	v_min_f32_e32 v168, 0x42b80000, v168
	v_min_f32_e32 v169, 0x42b80000, v169
	v_exp_f32_e32 v148, v148
	v_exp_f32_e32 v149, v149
	v_exp_f32_e32 v150, v150
	v_exp_f32_e32 v151, v151
	v_exp_f32_e32 v152, v152
	v_exp_f32_e32 v153, v153
	v_exp_f32_e32 v168, v168
	v_exp_f32_e32 v169, v169
	s_nop 0
	v_add_f32_e32 v148, 1.0, v148
	v_add_f32_e32 v149, 1.0, v149
	v_add_f32_e32 v150, 1.0, v150
	v_add_f32_e32 v151, 1.0, v151
	v_add_f32_e32 v152, 1.0, v152
	v_add_f32_e32 v153, 1.0, v153
	v_add_f32_e32 v168, 1.0, v168
	v_add_f32_e32 v169, 1.0, v169
	v_rcp_f32_e32 v148, v148
	v_rcp_f32_e32 v149, v149
	v_rcp_f32_e32 v150, v150
	v_rcp_f32_e32 v151, v151
	v_rcp_f32_e32 v152, v152
	v_rcp_f32_e32 v153, v153
	v_rcp_f32_e32 v168, v168
	v_rcp_f32_e32 v169, v169
	s_nop 0
	v_pk_mul_f32 v[102:103], v[102:103], v[148:149]
	v_pk_mul_f32 v[104:105], v[104:105], v[150:151]
; DI float bflo(unsigned w) { return __uint_as_float(w << 16); }
; DI float bfhi(unsigned w) { return __uint_as_float(w & 0xffff0000u); }
; DI u32x4 pack8(f32x4 a, f32x4 b) { u32x4 w; w.x = pk2(a[0], a[1]); w.y = pk2(a[2], a[3]); w.z = pk2(b[0], b[1]); w.w = pk2(b[2], b[3]); return w; }
; DI float fexp2(float x) { return __builtin_amdgcn_exp2f(x); }
; DI float fexp(float x) { return __builtin_amdgcn_exp2f(x * LOG2E); }
; DI float frcp(float x) { return __builtin_amdgcn_rcpf(x); }
; DI float fsigmoid(float x) { return frcp(1.0f + fexp(-x)); }
;     DI void operator()(Acc& acc, const Unit& u, int wr, int wc, int fr, int fq) const {
;     ...
;                     for (int bj = 0; bj < 2; ++bj) g[ai][m][bj] = *(const u32x4*)(base + (size_t)(ai * 128 + m * 16) * NPJ + u.k * 1024 + bj * 128);
; #pragma unroll
;             for (int ai = 0; ai < 2; ++ai)
; #pragma unroll
;                 for (int m = 0; m < 4; ++m)
; #pragma unroll
;                     for (int bj = 0; bj < 2; ++bj) { const u32x4 q = g[ai][m][bj]; f32x4& v0 = acc[ai][bj][m][0]; f32x4& v1 = acc[ai][bj][m][1];
;                         v0[0] *= bflo(q.x); v0[1] *= bfhi(q.x); v0[2] *= bflo(q.y); v0[3] *= bfhi(q.y); v1[0] *= bflo(q.z); v1[1] *= bfhi(q.z); v1[2] *= bflo(q.w); v1[3] *= bfhi(q.w); }
;     ...
;                     for (int bj = 0; bj < 2; ++bj) *(u32x4*)(base + (size_t)(ai * 128 + m * 16) * NPJ + bj * 128) = pack8(acc[ai][bj][m][0], acc[ai][bj][m][1]);
	v_pk_mul_f32 v[94:95], v[94:95], v[152:153]
	v_pk_mul_f32 v[96:97], v[96:97], v[168:169]
	v_cvt_pk_bf16_f32 v200, v102, v103
	v_cvt_pk_bf16_f32 v201, v104, v105
	v_cvt_pk_bf16_f32 v202, v94, v95
	v_cvt_pk_bf16_f32 v203, v96, v97
	v_lshlrev_b32_e32 v176, 16, v204
	v_and_b32_e32 v177, 0xffff0000, v204
	v_lshlrev_b32_e32 v178, 16, v205
	v_and_b32_e32 v179, 0xffff0000, v205
	v_lshlrev_b32_e32 v180, 16, v206
	v_and_b32_e32 v181, 0xffff0000, v206
	v_lshlrev_b32_e32 v244, 16, v207
	v_and_b32_e32 v245, 0xffff0000, v207
	v_pk_mul_f32 v[176:177], v[176:177], s[100:101] op_sel_hi:[1,0]
	v_pk_mul_f32 v[178:179], v[178:179], s[100:101] op_sel_hi:[1,0]
	v_pk_mul_f32 v[180:181], v[180:181], s[100:101] op_sel_hi:[1,0]
	v_pk_mul_f32 v[244:245], v[244:245], s[100:101] op_sel_hi:[1,0]
	v_min_f32_e32 v176, 0x42b80000, v176
	v_min_f32_e32 v177, 0x42b80000, v177
	v_min_f32_e32 v178, 0x42b80000, v178
	v_min_f32_e32 v179, 0x42b80000, v179
	v_min_f32_e32 v180, 0x42b80000, v180
	v_min_f32_e32 v181, 0x42b80000, v181
	v_min_f32_e32 v244, 0x42b80000, v244
	v_min_f32_e32 v245, 0x42b80000, v245
	v_exp_f32_e32 v176, v176
	v_exp_f32_e32 v177, v177
	v_exp_f32_e32 v178, v178
	v_exp_f32_e32 v179, v179
	v_exp_f32_e32 v180, v180
	v_exp_f32_e32 v181, v181
	v_exp_f32_e32 v244, v244
	v_exp_f32_e32 v245, v245
	s_nop 0
	v_add_f32_e32 v176, 1.0, v176
	v_add_f32_e32 v177, 1.0, v177
	v_add_f32_e32 v178, 1.0, v178
	v_add_f32_e32 v179, 1.0, v179
	v_add_f32_e32 v180, 1.0, v180
	v_add_f32_e32 v181, 1.0, v181
	v_add_f32_e32 v244, 1.0, v244
	v_add_f32_e32 v245, 1.0, v245
	v_rcp_f32_e32 v176, v176
	v_rcp_f32_e32 v177, v177
	v_rcp_f32_e32 v178, v178
	v_rcp_f32_e32 v179, v179
	v_rcp_f32_e32 v180, v180
	v_rcp_f32_e32 v181, v181
	v_rcp_f32_e32 v244, v244
	v_rcp_f32_e32 v245, v245
	s_nop 0
	v_pk_mul_f32 v[82:83], v[82:83], v[176:177]
	v_pk_mul_f32 v[84:85], v[84:85], v[178:179]
	v_pk_mul_f32 v[74:75], v[74:75], v[180:181]
	v_pk_mul_f32 v[76:77], v[76:77], v[244:245]
	v_cvt_pk_bf16_f32 v204, v82, v83
	v_cvt_pk_bf16_f32 v205, v84, v85
	v_cvt_pk_bf16_f32 v206, v74, v75
	v_cvt_pk_bf16_f32 v207, v76, v77
	global_store_dwordx4 v[134:135], v[200:203], off offset:-4096
	global_store_dwordx4 v[134:135], v[204:207], off offset:-3840
	s_waitcnt vmcnt(14)
	v_lshlrev_b32_e32 v148, 16, v208
	v_and_b32_e32 v149, 0xffff0000, v208
	v_lshlrev_b32_e32 v150, 16, v209
	v_and_b32_e32 v151, 0xffff0000, v209
	v_lshlrev_b32_e32 v152, 16, v210
	v_and_b32_e32 v153, 0xffff0000, v210
	v_lshlrev_b32_e32 v168, 16, v211
	v_and_b32_e32 v169, 0xffff0000, v211
	v_pk_mul_f32 v[148:149], v[148:149], s[100:101] op_sel_hi:[1,0]
	v_pk_mul_f32 v[150:151], v[150:151], s[100:101] op_sel_hi:[1,0]
	v_pk_mul_f32 v[152:153], v[152:153], s[100:101] op_sel_hi:[1,0]
	v_pk_mul_f32 v[168:169], v[168:169], s[100:101] op_sel_hi:[1,0]
	v_min_f32_e32 v148, 0x42b80000, v148
	v_min_f32_e32 v149, 0x42b80000, v149
	v_min_f32_e32 v150, 0x42b80000, v150
	v_min_f32_e32 v151, 0x42b80000, v151
	v_min_f32_e32 v152, 0x42b80000, v152
	v_min_f32_e32 v153, 0x42b80000, v153
	v_min_f32_e32 v168, 0x42b80000, v168
	v_min_f32_e32 v169, 0x42b80000, v169
	v_exp_f32_e32 v148, v148
	v_exp_f32_e32 v149, v149
	v_exp_f32_e32 v150, v150
	v_exp_f32_e32 v151, v151
	v_exp_f32_e32 v152, v152
	v_exp_f32_e32 v153, v153
	v_exp_f32_e32 v168, v168
	v_exp_f32_e32 v169, v169
	s_nop 0
	v_add_f32_e32 v148, 1.0, v148
	v_add_f32_e32 v149, 1.0, v149
	v_add_f32_e32 v150, 1.0, v150
	v_add_f32_e32 v151, 1.0, v151
	v_add_f32_e32 v152, 1.0, v152
	v_add_f32_e32 v153, 1.0, v153
	v_add_f32_e32 v168, 1.0, v168
	v_add_f32_e32 v169, 1.0, v169
	v_rcp_f32_e32 v148, v148
	v_rcp_f32_e32 v149, v149
	v_rcp_f32_e32 v150, v150
	v_rcp_f32_e32 v151, v151
	v_rcp_f32_e32 v152, v152
	v_rcp_f32_e32 v153, v153
	v_rcp_f32_e32 v168, v168
	v_rcp_f32_e32 v169, v169
	s_nop 0
	v_pk_mul_f32 v[86:87], v[86:87], v[148:149]
	v_pk_mul_f32 v[88:89], v[88:89], v[150:151]
	v_pk_mul_f32 v[78:79], v[78:79], v[152:153]
	v_pk_mul_f32 v[80:81], v[80:81], v[168:169]
	v_cvt_pk_bf16_f32 v208, v86, v87
	v_cvt_pk_bf16_f32 v209, v88, v89
	v_cvt_pk_bf16_f32 v210, v78, v79
	v_cvt_pk_bf16_f32 v211, v80, v81
	v_lshlrev_b32_e32 v176, 16, v212
	v_and_b32_e32 v177, 0xffff0000, v212
	v_lshlrev_b32_e32 v178, 16, v213
	v_and_b32_e32 v179, 0xffff0000, v213
	v_lshlrev_b32_e32 v180, 16, v214
	v_and_b32_e32 v181, 0xffff0000, v214
	v_lshlrev_b32_e32 v244, 16, v215
	v_and_b32_e32 v245, 0xffff0000, v215
	v_pk_mul_f32 v[176:177], v[176:177], s[100:101] op_sel_hi:[1,0]
	v_pk_mul_f32 v[178:179], v[178:179], s[100:101] op_sel_hi:[1,0]
	v_pk_mul_f32 v[180:181], v[180:181], s[100:101] op_sel_hi:[1,0]
	v_pk_mul_f32 v[244:245], v[244:245], s[100:101] op_sel_hi:[1,0]
	v_min_f32_e32 v176, 0x42b80000, v176
	v_min_f32_e32 v177, 0x42b80000, v177
	v_min_f32_e32 v178, 0x42b80000, v178
	v_min_f32_e32 v179, 0x42b80000, v179
	v_min_f32_e32 v180, 0x42b80000, v180
	v_min_f32_e32 v181, 0x42b80000, v181
	v_min_f32_e32 v244, 0x42b80000, v244
	v_min_f32_e32 v245, 0x42b80000, v245
	v_exp_f32_e32 v176, v176
	v_exp_f32_e32 v177, v177
	v_exp_f32_e32 v178, v178
	v_exp_f32_e32 v179, v179
	v_exp_f32_e32 v180, v180
	v_exp_f32_e32 v181, v181
	v_exp_f32_e32 v244, v244
	v_exp_f32_e32 v245, v245
	s_nop 0
	v_add_f32_e32 v176, 1.0, v176
	v_add_f32_e32 v177, 1.0, v177
	v_add_f32_e32 v178, 1.0, v178
	v_add_f32_e32 v179, 1.0, v179
	v_add_f32_e32 v180, 1.0, v180
	v_add_f32_e32 v181, 1.0, v181
	v_add_f32_e32 v244, 1.0, v244
	v_add_f32_e32 v245, 1.0, v245
	v_rcp_f32_e32 v176, v176
	v_rcp_f32_e32 v177, v177
	v_rcp_f32_e32 v178, v178
	v_rcp_f32_e32 v179, v179
	v_rcp_f32_e32 v180, v180
	v_rcp_f32_e32 v181, v181
	v_rcp_f32_e32 v244, v244
	v_rcp_f32_e32 v245, v245
	s_nop 0
	v_pk_mul_f32 v[70:71], v[70:71], v[176:177]
	v_pk_mul_f32 v[72:73], v[72:73], v[178:179]
	v_pk_mul_f32 v[66:67], v[66:67], v[180:181]
	v_pk_mul_f32 v[68:69], v[68:69], v[244:245]
	v_cvt_pk_bf16_f32 v212, v70, v71
	v_cvt_pk_bf16_f32 v213, v72, v73
	v_cvt_pk_bf16_f32 v214, v66, v67
	v_cvt_pk_bf16_f32 v215, v68, v69
	global_store_dwordx4 v[136:137], v[208:211], off offset:-4096
	global_store_dwordx4 v[136:137], v[212:215], off offset:-3840
	s_waitcnt vmcnt(14)
; DI float bflo(unsigned w) { return __uint_as_float(w << 16); }
; DI float bfhi(unsigned w) { return __uint_as_float(w & 0xffff0000u); }
; DI u32x4 pack8(f32x4 a, f32x4 b) { u32x4 w; w.x = pk2(a[0], a[1]); w.y = pk2(a[2], a[3]); w.z = pk2(b[0], b[1]); w.w = pk2(b[2], b[3]); return w; }
; DI float fexp2(float x) { return __builtin_amdgcn_exp2f(x); }
; DI float fexp(float x) { return __builtin_amdgcn_exp2f(x * LOG2E); }
; DI float frcp(float x) { return __builtin_amdgcn_rcpf(x); }
; DI float fsigmoid(float x) { return frcp(1.0f + fexp(-x)); }
;     DI void operator()(Acc& acc, const Unit& u, int wr, int wc, int fr, int fq) const {
;     ...
;                     for (int bj = 0; bj < 2; ++bj) g[ai][m][bj] = *(const u32x4*)(base + (size_t)(ai * 128 + m * 16) * NPJ + u.k * 1024 + bj * 128);
; #pragma unroll
;             for (int ai = 0; ai < 2; ++ai)
; #pragma unroll
;                 for (int m = 0; m < 4; ++m)
; #pragma unroll
;                     for (int bj = 0; bj < 2; ++bj) { const u32x4 q = g[ai][m][bj]; f32x4& v0 = acc[ai][bj][m][0]; f32x4& v1 = acc[ai][bj][m][1];
;                         v0[0] *= bflo(q.x); v0[1] *= bfhi(q.x); v0[2] *= bflo(q.y); v0[3] *= bfhi(q.y); v1[0] *= bflo(q.z); v1[1] *= bfhi(q.z); v1[2] *= bflo(q.w); v1[3] *= bfhi(q.w); }
;     ...
;                     for (int bj = 0; bj < 2; ++bj) *(u32x4*)(base + (size_t)(ai * 128 + m * 16) * NPJ + bj * 128) = pack8(acc[ai][bj][m][0], acc[ai][bj][m][1]);
	v_lshlrev_b32_e32 v148, 16, v216
	v_and_b32_e32 v149, 0xffff0000, v216
	v_lshlrev_b32_e32 v150, 16, v217
	v_and_b32_e32 v151, 0xffff0000, v217
	v_lshlrev_b32_e32 v152, 16, v218
	v_and_b32_e32 v153, 0xffff0000, v218
	v_lshlrev_b32_e32 v168, 16, v219
	v_and_b32_e32 v169, 0xffff0000, v219
	v_pk_mul_f32 v[148:149], v[148:149], s[100:101] op_sel_hi:[1,0]
	v_pk_mul_f32 v[150:151], v[150:151], s[100:101] op_sel_hi:[1,0]
	v_pk_mul_f32 v[152:153], v[152:153], s[100:101] op_sel_hi:[1,0]
	v_pk_mul_f32 v[168:169], v[168:169], s[100:101] op_sel_hi:[1,0]
	v_min_f32_e32 v148, 0x42b80000, v148
	v_min_f32_e32 v149, 0x42b80000, v149
	v_min_f32_e32 v150, 0x42b80000, v150
	v_min_f32_e32 v151, 0x42b80000, v151
	v_min_f32_e32 v152, 0x42b80000, v152
	v_min_f32_e32 v153, 0x42b80000, v153
	v_min_f32_e32 v168, 0x42b80000, v168
	v_min_f32_e32 v169, 0x42b80000, v169
	v_exp_f32_e32 v148, v148
	v_exp_f32_e32 v149, v149
	v_exp_f32_e32 v150, v150
	v_exp_f32_e32 v151, v151
	v_exp_f32_e32 v152, v152
	v_exp_f32_e32 v153, v153
	v_exp_f32_e32 v168, v168
	v_exp_f32_e32 v169, v169
	s_nop 0
	v_add_f32_e32 v148, 1.0, v148
	v_add_f32_e32 v149, 1.0, v149
	v_add_f32_e32 v150, 1.0, v150
	v_add_f32_e32 v151, 1.0, v151
	v_add_f32_e32 v152, 1.0, v152
	v_add_f32_e32 v153, 1.0, v153
	v_add_f32_e32 v168, 1.0, v168
	v_add_f32_e32 v169, 1.0, v169
	v_rcp_f32_e32 v148, v148
	v_rcp_f32_e32 v149, v149
	v_rcp_f32_e32 v150, v150
	v_rcp_f32_e32 v151, v151
	v_rcp_f32_e32 v152, v152
	v_rcp_f32_e32 v153, v153
	v_rcp_f32_e32 v168, v168
	v_rcp_f32_e32 v169, v169
	s_nop 0
	v_pk_mul_f32 v[62:63], v[62:63], v[148:149]
	v_pk_mul_f32 v[64:65], v[64:65], v[150:151]
	v_pk_mul_f32 v[58:59], v[58:59], v[152:153]
	v_pk_mul_f32 v[60:61], v[60:61], v[168:169]
	v_cvt_pk_bf16_f32 v216, v62, v63
	v_cvt_pk_bf16_f32 v217, v64, v65
	v_cvt_pk_bf16_f32 v218, v58, v59
	v_cvt_pk_bf16_f32 v219, v60, v61
	v_lshlrev_b32_e32 v176, 16, v220
	v_and_b32_e32 v177, 0xffff0000, v220
	v_lshlrev_b32_e32 v178, 16, v221
	v_and_b32_e32 v179, 0xffff0000, v221
	v_lshlrev_b32_e32 v180, 16, v222
	v_and_b32_e32 v181, 0xffff0000, v222
	v_lshlrev_b32_e32 v244, 16, v223
	v_and_b32_e32 v245, 0xffff0000, v223
	v_pk_mul_f32 v[176:177], v[176:177], s[100:101] op_sel_hi:[1,0]
	v_pk_mul_f32 v[178:179], v[178:179], s[100:101] op_sel_hi:[1,0]
	v_pk_mul_f32 v[180:181], v[180:181], s[100:101] op_sel_hi:[1,0]
	v_pk_mul_f32 v[244:245], v[244:245], s[100:101] op_sel_hi:[1,0]
	v_min_f32_e32 v176, 0x42b80000, v176
	v_min_f32_e32 v177, 0x42b80000, v177
	v_min_f32_e32 v178, 0x42b80000, v178
	v_min_f32_e32 v179, 0x42b80000, v179
	v_min_f32_e32 v180, 0x42b80000, v180
	v_min_f32_e32 v181, 0x42b80000, v181
	v_min_f32_e32 v244, 0x42b80000, v244
	v_min_f32_e32 v245, 0x42b80000, v245
	v_exp_f32_e32 v176, v176
	v_exp_f32_e32 v177, v177
	v_exp_f32_e32 v178, v178
	v_exp_f32_e32 v179, v179
	v_exp_f32_e32 v180, v180
	v_exp_f32_e32 v181, v181
	v_exp_f32_e32 v244, v244
	v_exp_f32_e32 v245, v245
	s_nop 0
	v_add_f32_e32 v176, 1.0, v176
	v_add_f32_e32 v177, 1.0, v177
	v_add_f32_e32 v178, 1.0, v178
	v_add_f32_e32 v179, 1.0, v179
	v_add_f32_e32 v180, 1.0, v180
	v_add_f32_e32 v181, 1.0, v181
	v_add_f32_e32 v244, 1.0, v244
	v_add_f32_e32 v245, 1.0, v245
	v_rcp_f32_e32 v176, v176
	v_rcp_f32_e32 v177, v177
	v_rcp_f32_e32 v178, v178
	v_rcp_f32_e32 v179, v179
	v_rcp_f32_e32 v180, v180
	v_rcp_f32_e32 v181, v181
	v_rcp_f32_e32 v244, v244
	v_rcp_f32_e32 v245, v245
	s_nop 0
	v_pk_mul_f32 v[50:51], v[50:51], v[176:177]
	v_pk_mul_f32 v[52:53], v[52:53], v[178:179]
	v_pk_mul_f32 v[42:43], v[42:43], v[180:181]
	v_pk_mul_f32 v[44:45], v[44:45], v[244:245]
	v_cvt_pk_bf16_f32 v220, v50, v51
	v_cvt_pk_bf16_f32 v221, v52, v53
	v_cvt_pk_bf16_f32 v222, v42, v43
	v_cvt_pk_bf16_f32 v223, v44, v45
	global_store_dwordx4 v[138:139], v[216:219], off offset:-4096
	global_store_dwordx4 v[138:139], v[220:223], off offset:-3840
	s_waitcnt vmcnt(14)
	v_lshlrev_b32_e32 v148, 16, v224
	v_and_b32_e32 v149, 0xffff0000, v224
	v_lshlrev_b32_e32 v150, 16, v225
	v_and_b32_e32 v151, 0xffff0000, v225
	v_lshlrev_b32_e32 v152, 16, v226
	v_and_b32_e32 v153, 0xffff0000, v226
	v_lshlrev_b32_e32 v168, 16, v227
	v_and_b32_e32 v169, 0xffff0000, v227
	v_pk_mul_f32 v[148:149], v[148:149], s[100:101] op_sel_hi:[1,0]
	v_pk_mul_f32 v[150:151], v[150:151], s[100:101] op_sel_hi:[1,0]
	v_pk_mul_f32 v[152:153], v[152:153], s[100:101] op_sel_hi:[1,0]
	v_pk_mul_f32 v[168:169], v[168:169], s[100:101] op_sel_hi:[1,0]
	v_min_f32_e32 v148, 0x42b80000, v148
	v_min_f32_e32 v149, 0x42b80000, v149
	v_min_f32_e32 v150, 0x42b80000, v150
	v_min_f32_e32 v151, 0x42b80000, v151
	v_min_f32_e32 v152, 0x42b80000, v152
	v_min_f32_e32 v153, 0x42b80000, v153
	v_min_f32_e32 v168, 0x42b80000, v168
	v_min_f32_e32 v169, 0x42b80000, v169
	v_exp_f32_e32 v148, v148
	v_exp_f32_e32 v149, v149
	v_exp_f32_e32 v150, v150
	v_exp_f32_e32 v151, v151
	v_exp_f32_e32 v152, v152
	v_exp_f32_e32 v153, v153
	v_exp_f32_e32 v168, v168
	v_exp_f32_e32 v169, v169
	s_nop 0
	v_add_f32_e32 v148, 1.0, v148
	v_add_f32_e32 v149, 1.0, v149
	v_add_f32_e32 v150, 1.0, v150
	v_add_f32_e32 v151, 1.0, v151
	v_add_f32_e32 v152, 1.0, v152
	v_add_f32_e32 v153, 1.0, v153
	v_add_f32_e32 v168, 1.0, v168
	v_add_f32_e32 v169, 1.0, v169
	v_rcp_f32_e32 v148, v148
	v_rcp_f32_e32 v149, v149
	v_rcp_f32_e32 v150, v150
	v_rcp_f32_e32 v151, v151
	v_rcp_f32_e32 v152, v152
	v_rcp_f32_e32 v153, v153
	v_rcp_f32_e32 v168, v168
	v_rcp_f32_e32 v169, v169
	s_nop 0
	v_pk_mul_f32 v[54:55], v[54:55], v[148:149]
	v_pk_mul_f32 v[56:57], v[56:57], v[150:151]
	v_pk_mul_f32 v[46:47], v[46:47], v[152:153]
	v_pk_mul_f32 v[48:49], v[48:49], v[168:169]
	v_cvt_pk_bf16_f32 v224, v54, v55
	v_cvt_pk_bf16_f32 v225, v56, v57
; DI float bflo(unsigned w) { return __uint_as_float(w << 16); }
; DI float bfhi(unsigned w) { return __uint_as_float(w & 0xffff0000u); }
; DI u32x4 pack8(f32x4 a, f32x4 b) { u32x4 w; w.x = pk2(a[0], a[1]); w.y = pk2(a[2], a[3]); w.z = pk2(b[0], b[1]); w.w = pk2(b[2], b[3]); return w; }
; DI float fexp2(float x) { return __builtin_amdgcn_exp2f(x); }
; DI float fexp(float x) { return __builtin_amdgcn_exp2f(x * LOG2E); }
; DI float frcp(float x) { return __builtin_amdgcn_rcpf(x); }
; DI float fsigmoid(float x) { return frcp(1.0f + fexp(-x)); }
;     DI void operator()(Acc& acc, const Unit& u, int wr, int wc, int fr, int fq) const {
;     ...
;                     for (int bj = 0; bj < 2; ++bj) g[ai][m][bj] = *(const u32x4*)(base + (size_t)(ai * 128 + m * 16) * NPJ + u.k * 1024 + bj * 128);
; #pragma unroll
;             for (int ai = 0; ai < 2; ++ai)
; #pragma unroll
;                 for (int m = 0; m < 4; ++m)
; #pragma unroll
;                     for (int bj = 0; bj < 2; ++bj) { const u32x4 q = g[ai][m][bj]; f32x4& v0 = acc[ai][bj][m][0]; f32x4& v1 = acc[ai][bj][m][1];
;                         v0[0] *= bflo(q.x); v0[1] *= bfhi(q.x); v0[2] *= bflo(q.y); v0[3] *= bfhi(q.y); v1[0] *= bflo(q.z); v1[1] *= bfhi(q.z); v1[2] *= bflo(q.w); v1[3] *= bfhi(q.w); }
;     ...
;                     for (int bj = 0; bj < 2; ++bj) *(u32x4*)(base + (size_t)(ai * 128 + m * 16) * NPJ + bj * 128) = pack8(acc[ai][bj][m][0], acc[ai][bj][m][1]);
	v_cvt_pk_bf16_f32 v226, v46, v47
	v_cvt_pk_bf16_f32 v227, v48, v49
	v_lshlrev_b32_e32 v176, 16, v228
	v_and_b32_e32 v177, 0xffff0000, v228
	v_lshlrev_b32_e32 v178, 16, v229
	v_and_b32_e32 v179, 0xffff0000, v229
	v_lshlrev_b32_e32 v180, 16, v230
	v_and_b32_e32 v181, 0xffff0000, v230
	v_lshlrev_b32_e32 v244, 16, v231
	v_and_b32_e32 v245, 0xffff0000, v231
	v_pk_mul_f32 v[176:177], v[176:177], s[100:101] op_sel_hi:[1,0]
	v_pk_mul_f32 v[178:179], v[178:179], s[100:101] op_sel_hi:[1,0]
	v_pk_mul_f32 v[180:181], v[180:181], s[100:101] op_sel_hi:[1,0]
	v_pk_mul_f32 v[244:245], v[244:245], s[100:101] op_sel_hi:[1,0]
	v_min_f32_e32 v176, 0x42b80000, v176
	v_min_f32_e32 v177, 0x42b80000, v177
	v_min_f32_e32 v178, 0x42b80000, v178
	v_min_f32_e32 v179, 0x42b80000, v179
	v_min_f32_e32 v180, 0x42b80000, v180
	v_min_f32_e32 v181, 0x42b80000, v181
	v_min_f32_e32 v244, 0x42b80000, v244
	v_min_f32_e32 v245, 0x42b80000, v245
	v_exp_f32_e32 v176, v176
	v_exp_f32_e32 v177, v177
	v_exp_f32_e32 v178, v178
	v_exp_f32_e32 v179, v179
	v_exp_f32_e32 v180, v180
	v_exp_f32_e32 v181, v181
	v_exp_f32_e32 v244, v244
	v_exp_f32_e32 v245, v245
	s_nop 0
	v_add_f32_e32 v176, 1.0, v176
	v_add_f32_e32 v177, 1.0, v177
	v_add_f32_e32 v178, 1.0, v178
	v_add_f32_e32 v179, 1.0, v179
	v_add_f32_e32 v180, 1.0, v180
	v_add_f32_e32 v181, 1.0, v181
	v_add_f32_e32 v244, 1.0, v244
	v_add_f32_e32 v245, 1.0, v245
	v_rcp_f32_e32 v176, v176
	v_rcp_f32_e32 v177, v177
	v_rcp_f32_e32 v178, v178
	v_rcp_f32_e32 v179, v179
	v_rcp_f32_e32 v180, v180
	v_rcp_f32_e32 v181, v181
	v_rcp_f32_e32 v244, v244
	v_rcp_f32_e32 v245, v245
	s_nop 0
	v_pk_mul_f32 v[34:35], v[34:35], v[176:177]
	v_pk_mul_f32 v[36:37], v[36:37], v[178:179]
	v_pk_mul_f32 v[26:27], v[26:27], v[180:181]
	v_pk_mul_f32 v[28:29], v[28:29], v[244:245]
	v_cvt_pk_bf16_f32 v228, v34, v35
	v_cvt_pk_bf16_f32 v229, v36, v37
	v_cvt_pk_bf16_f32 v230, v26, v27
	v_cvt_pk_bf16_f32 v231, v28, v29
	global_store_dwordx4 v[140:141], v[224:227], off offset:-4096
	global_store_dwordx4 v[140:141], v[228:231], off offset:-3840
	s_waitcnt vmcnt(12)
	v_lshlrev_b32_e32 v148, 16, v184
	v_and_b32_e32 v149, 0xffff0000, v184
	v_lshlrev_b32_e32 v150, 16, v185
	v_and_b32_e32 v151, 0xffff0000, v185
	v_lshlrev_b32_e32 v152, 16, v186
	v_and_b32_e32 v153, 0xffff0000, v186
	v_lshlrev_b32_e32 v168, 16, v187
	v_and_b32_e32 v169, 0xffff0000, v187
	v_pk_mul_f32 v[148:149], v[148:149], s[100:101] op_sel_hi:[1,0]
	v_pk_mul_f32 v[150:151], v[150:151], s[100:101] op_sel_hi:[1,0]
	v_pk_mul_f32 v[152:153], v[152:153], s[100:101] op_sel_hi:[1,0]
	v_pk_mul_f32 v[168:169], v[168:169], s[100:101] op_sel_hi:[1,0]
	v_min_f32_e32 v148, 0x42b80000, v148
	v_min_f32_e32 v149, 0x42b80000, v149
	v_min_f32_e32 v150, 0x42b80000, v150
	v_min_f32_e32 v151, 0x42b80000, v151
	v_min_f32_e32 v152, 0x42b80000, v152
	v_min_f32_e32 v153, 0x42b80000, v153
	v_min_f32_e32 v168, 0x42b80000, v168
	v_min_f32_e32 v169, 0x42b80000, v169
	v_exp_f32_e32 v148, v148
	v_exp_f32_e32 v149, v149
	v_exp_f32_e32 v150, v150
	v_exp_f32_e32 v151, v151
	v_exp_f32_e32 v152, v152
	v_exp_f32_e32 v153, v153
	v_exp_f32_e32 v168, v168
	v_exp_f32_e32 v169, v169
	s_nop 0
	v_add_f32_e32 v148, 1.0, v148
	v_add_f32_e32 v149, 1.0, v149
	v_add_f32_e32 v150, 1.0, v150
	v_add_f32_e32 v151, 1.0, v151
	v_add_f32_e32 v152, 1.0, v152
	v_add_f32_e32 v153, 1.0, v153
	v_add_f32_e32 v168, 1.0, v168
	v_add_f32_e32 v169, 1.0, v169
	v_rcp_f32_e32 v148, v148
	v_rcp_f32_e32 v149, v149
	v_rcp_f32_e32 v150, v150
	v_rcp_f32_e32 v151, v151
	v_rcp_f32_e32 v152, v152
	v_rcp_f32_e32 v153, v153
	v_rcp_f32_e32 v168, v168
	v_rcp_f32_e32 v169, v169
	s_nop 0
	v_pk_mul_f32 v[38:39], v[38:39], v[148:149]
	v_pk_mul_f32 v[40:41], v[40:41], v[150:151]
	v_pk_mul_f32 v[30:31], v[30:31], v[152:153]
	v_pk_mul_f32 v[32:33], v[32:33], v[168:169]
	v_cvt_pk_bf16_f32 v184, v38, v39
	v_cvt_pk_bf16_f32 v185, v40, v41
	v_cvt_pk_bf16_f32 v186, v30, v31
	v_cvt_pk_bf16_f32 v187, v32, v33
	v_lshlrev_b32_e32 v176, 16, v188
	v_and_b32_e32 v177, 0xffff0000, v188
	v_lshlrev_b32_e32 v178, 16, v189
	v_and_b32_e32 v179, 0xffff0000, v189
	v_lshlrev_b32_e32 v180, 16, v190
	v_and_b32_e32 v181, 0xffff0000, v190
	v_lshlrev_b32_e32 v244, 16, v191
	v_and_b32_e32 v245, 0xffff0000, v191
	v_pk_mul_f32 v[176:177], v[176:177], s[100:101] op_sel_hi:[1,0]
	v_pk_mul_f32 v[178:179], v[178:179], s[100:101] op_sel_hi:[1,0]
	v_pk_mul_f32 v[180:181], v[180:181], s[100:101] op_sel_hi:[1,0]
	v_pk_mul_f32 v[244:245], v[244:245], s[100:101] op_sel_hi:[1,0]
	v_min_f32_e32 v176, 0x42b80000, v176
	v_min_f32_e32 v177, 0x42b80000, v177
	v_min_f32_e32 v178, 0x42b80000, v178
	v_min_f32_e32 v179, 0x42b80000, v179
	v_min_f32_e32 v180, 0x42b80000, v180
	v_min_f32_e32 v181, 0x42b80000, v181
	v_min_f32_e32 v244, 0x42b80000, v244
	v_min_f32_e32 v245, 0x42b80000, v245
	v_exp_f32_e32 v176, v176
	v_exp_f32_e32 v177, v177
	v_exp_f32_e32 v178, v178
	v_exp_f32_e32 v179, v179
	v_exp_f32_e32 v180, v180
	v_exp_f32_e32 v181, v181
	v_exp_f32_e32 v244, v244
	v_exp_f32_e32 v245, v245
	s_nop 0
	v_add_f32_e32 v176, 1.0, v176
	v_add_f32_e32 v177, 1.0, v177
	v_add_f32_e32 v178, 1.0, v178
	v_add_f32_e32 v179, 1.0, v179
	v_add_f32_e32 v180, 1.0, v180
	v_add_f32_e32 v181, 1.0, v181
	v_add_f32_e32 v244, 1.0, v244
	v_add_f32_e32 v245, 1.0, v245
	v_rcp_f32_e32 v176, v176
	v_rcp_f32_e32 v177, v177
	v_rcp_f32_e32 v178, v178
	v_rcp_f32_e32 v179, v179
	v_rcp_f32_e32 v180, v180
	v_rcp_f32_e32 v181, v181
	v_rcp_f32_e32 v244, v244
	v_rcp_f32_e32 v245, v245
	s_nop 0
	v_pk_mul_f32 v[18:19], v[18:19], v[176:177]
	v_pk_mul_f32 v[20:21], v[20:21], v[178:179]
	v_pk_mul_f32 v[10:11], v[10:11], v[180:181]
	v_pk_mul_f32 v[12:13], v[12:13], v[244:245]
	v_cvt_pk_bf16_f32 v188, v18, v19
	v_cvt_pk_bf16_f32 v189, v20, v21
	v_cvt_pk_bf16_f32 v190, v10, v11
	v_cvt_pk_bf16_f32 v191, v12, v13
	global_store_dwordx4 v[142:143], v[184:187], off offset:-4096
	global_store_dwordx4 v[142:143], v[188:191], off offset:-3840
	s_waitcnt vmcnt(10)
; DI float bflo(unsigned w) { return __uint_as_float(w << 16); }
; DI float bfhi(unsigned w) { return __uint_as_float(w & 0xffff0000u); }
; DI u32x4 pack8(f32x4 a, f32x4 b) { u32x4 w; w.x = pk2(a[0], a[1]); w.y = pk2(a[2], a[3]); w.z = pk2(b[0], b[1]); w.w = pk2(b[2], b[3]); return w; }
;     DI void operator()(Acc& acc, const Unit& u, int wr, int wc, int fr, int fq) const {
;     ...
;                     for (int bj = 0; bj < 2; ++bj) g[ai][m][bj] = *(const u32x4*)(base + (size_t)(ai * 128 + m * 16) * NPJ + u.k * 1024 + bj * 128);
; #pragma unroll
;             for (int ai = 0; ai < 2; ++ai)
; #pragma unroll
;                 for (int m = 0; m < 4; ++m)
; #pragma unroll
;                     for (int bj = 0; bj < 2; ++bj) { const u32x4 q = g[ai][m][bj]; f32x4& v0 = acc[ai][bj][m][0]; f32x4& v1 = acc[ai][bj][m][1];
;                         v0[0] *= bflo(q.x); v0[1] *= bfhi(q.x); v0[2] *= bflo(q.y); v0[3] *= bfhi(q.y); v1[0] *= bflo(q.z); v1[1] *= bfhi(q.z); v1[2] *= bflo(q.w); v1[3] *= bfhi(q.w); }
;     ...
;                     for (int bj = 0; bj < 2; ++bj) *(u32x4*)(base + (size_t)(ai * 128 + m * 16) * NPJ + bj * 128) = pack8(acc[ai][bj][m][0], acc[ai][bj][m][1]);
	v_lshlrev_b32_e32 v148, 16, v192
	v_and_b32_e32 v149, 0xffff0000, v192
	v_lshlrev_b32_e32 v150, 16, v193
	v_and_b32_e32 v151, 0xffff0000, v193
	v_lshlrev_b32_e32 v152, 16, v194
	v_and_b32_e32 v153, 0xffff0000, v194
	v_lshlrev_b32_e32 v168, 16, v195
	v_and_b32_e32 v169, 0xffff0000, v195
	v_pk_mul_f32 v[148:149], v[148:149], s[100:101] op_sel_hi:[1,0]
	v_pk_mul_f32 v[150:151], v[150:151], s[100:101] op_sel_hi:[1,0]
	v_pk_mul_f32 v[152:153], v[152:153], s[100:101] op_sel_hi:[1,0]
	v_pk_mul_f32 v[168:169], v[168:169], s[100:101] op_sel_hi:[1,0]
	v_min_f32_e32 v148, 0x42b80000, v148
	v_min_f32_e32 v149, 0x42b80000, v149
	v_min_f32_e32 v150, 0x42b80000, v150
	v_min_f32_e32 v151, 0x42b80000, v151
	v_min_f32_e32 v152, 0x42b80000, v152
	v_min_f32_e32 v153, 0x42b80000, v153
	v_min_f32_e32 v168, 0x42b80000, v168
	v_min_f32_e32 v169, 0x42b80000, v169
	v_exp_f32_e32 v148, v148
	v_exp_f32_e32 v149, v149
	v_exp_f32_e32 v150, v150
	v_exp_f32_e32 v151, v151
	v_exp_f32_e32 v152, v152
	v_exp_f32_e32 v153, v153
	v_exp_f32_e32 v168, v168
	v_exp_f32_e32 v169, v169
	s_nop 0
	v_add_f32_e32 v148, 1.0, v148
	v_add_f32_e32 v149, 1.0, v149
	v_add_f32_e32 v150, 1.0, v150
	v_add_f32_e32 v151, 1.0, v151
	v_add_f32_e32 v152, 1.0, v152
	v_add_f32_e32 v153, 1.0, v153
	v_add_f32_e32 v168, 1.0, v168
	v_add_f32_e32 v169, 1.0, v169
	v_rcp_f32_e32 v148, v148
	v_rcp_f32_e32 v149, v149
	v_rcp_f32_e32 v150, v150
	v_rcp_f32_e32 v151, v151
	v_rcp_f32_e32 v152, v152
	v_rcp_f32_e32 v153, v153
	v_rcp_f32_e32 v168, v168
	v_rcp_f32_e32 v169, v169
	s_nop 0
	v_pk_mul_f32 v[22:23], v[22:23], v[148:149]
	v_pk_mul_f32 v[24:25], v[24:25], v[150:151]
	v_pk_mul_f32 v[14:15], v[14:15], v[152:153]
	v_pk_mul_f32 v[16:17], v[16:17], v[168:169]
	v_cvt_pk_bf16_f32 v192, v22, v23
	v_cvt_pk_bf16_f32 v193, v24, v25
	v_cvt_pk_bf16_f32 v194, v14, v15
	v_cvt_pk_bf16_f32 v195, v16, v17
	v_lshlrev_b32_e32 v176, 16, v196
	v_and_b32_e32 v177, 0xffff0000, v196
	v_lshlrev_b32_e32 v178, 16, v197
	v_and_b32_e32 v179, 0xffff0000, v197
	v_lshlrev_b32_e32 v180, 16, v198
	v_and_b32_e32 v181, 0xffff0000, v198
	v_lshlrev_b32_e32 v244, 16, v199
	v_and_b32_e32 v245, 0xffff0000, v199
	v_pk_mul_f32 v[176:177], v[176:177], s[100:101] op_sel_hi:[1,0]
	v_pk_mul_f32 v[178:179], v[178:179], s[100:101] op_sel_hi:[1,0]
	v_pk_mul_f32 v[180:181], v[180:181], s[100:101] op_sel_hi:[1,0]
	v_pk_mul_f32 v[244:245], v[244:245], s[100:101] op_sel_hi:[1,0]
	v_min_f32_e32 v176, 0x42b80000, v176
	v_min_f32_e32 v177, 0x42b80000, v177
	v_min_f32_e32 v178, 0x42b80000, v178
	v_min_f32_e32 v179, 0x42b80000, v179
	v_min_f32_e32 v180, 0x42b80000, v180
	v_min_f32_e32 v181, 0x42b80000, v181
	v_min_f32_e32 v244, 0x42b80000, v244
	v_min_f32_e32 v245, 0x42b80000, v245
	v_exp_f32_e32 v176, v176
	v_exp_f32_e32 v177, v177
	v_exp_f32_e32 v178, v178
	v_exp_f32_e32 v179, v179
	v_exp_f32_e32 v180, v180
	v_exp_f32_e32 v181, v181
	v_exp_f32_e32 v244, v244
	v_exp_f32_e32 v245, v245
	s_nop 0
	v_add_f32_e32 v176, 1.0, v176
	v_add_f32_e32 v177, 1.0, v177
	v_add_f32_e32 v178, 1.0, v178
	v_add_f32_e32 v179, 1.0, v179
	v_add_f32_e32 v180, 1.0, v180
	v_add_f32_e32 v181, 1.0, v181
	v_add_f32_e32 v244, 1.0, v244
	v_add_f32_e32 v245, 1.0, v245
	v_rcp_f32_e32 v176, v176
	v_rcp_f32_e32 v177, v177
	v_rcp_f32_e32 v178, v178
	v_rcp_f32_e32 v179, v179
	v_rcp_f32_e32 v180, v180
	v_rcp_f32_e32 v181, v181
	v_rcp_f32_e32 v244, v244
	v_rcp_f32_e32 v245, v245
	s_nop 0
	v_pk_mul_f32 v[6:7], v[6:7], v[176:177]
	v_pk_mul_f32 v[8:9], v[8:9], v[178:179]
	v_pk_mul_f32 v[2:3], v[2:3], v[180:181]
	v_pk_mul_f32 v[4:5], v[4:5], v[244:245]
	v_cvt_pk_bf16_f32 v196, v6, v7
	v_cvt_pk_bf16_f32 v197, v8, v9
	v_cvt_pk_bf16_f32 v198, v2, v3
	v_cvt_pk_bf16_f32 v199, v4, v5
	global_store_dwordx4 v[144:145], v[192:195], off offset:-4096
	global_store_dwordx4 v[144:145], v[196:199], off offset:-3840
